# removed the 36 mid-block s_setprio 0/s_setprio 1 pairs between the two 16-MFMA halves of each GEMM super-phase (priority stays 1 across the 32 MFMAs)
# speedup vs baseline: 1.0103x; 1.0103x over previous
; #define PG8_STAGE(bufoff, gbase, voff) do { _Pragma("unroll") for (int _i = 0; _i < 2; ++_i) \
;         __builtin_amdgcn_global_load_lds((const unsigned*)((const char*)(gbase) + (voff)[_i]), (PG8_LAS unsigned*)(lds + (bufoff) + ldsw + _i * 8192), 16, 0, 0); } while (0)
; #define PG8_LDA(dst, b, h) do { _Pragma("unroll") for (int m = 0; m < 4; ++m) _Pragma("unroll") for (int k = 0; k < 2; ++k) dst[m][k] = *(const PG8_LAS bf16x8*)(lds + PG8_SA(b, h) + aoff + m * 2048 + k * 1024); } while (0)
; #define PG8_LDB(dst, b, h) do { _Pragma("unroll") for (int n = 0; n < 2; ++n) _Pragma("unroll") for (int k = 0; k < 2; ++k) dst[n][k] = *(const PG8_LAS bf16x8*)(lds + PG8_SB(b, h) + boff + n * 2048 + k * 1024); } while (0)
; #define PG8_MMA(ai, bj, At, Bt) do { __builtin_amdgcn_s_setprio(1); _Pragma("unroll") for (int m = 0; m < 4; ++m) _Pragma("unroll") for (int n = 0; n < 2; ++n) _Pragma("unroll") for (int k = 0; k < 2; ++k) \
;         acc[ai][bj][m][n] = __builtin_amdgcn_mfma_f32_16x16x32_bf16(Bt[n][k], At[m][k], acc[ai][bj][m][n], 0, 0, 0); __builtin_amdgcn_s_setprio(0); } while (0)
; #define PG8_WAIT_V(n) asm volatile("s_waitcnt vmcnt(" #n ")" ::: "memory")
; #define PG8_WAIT_L(n) asm volatile("s_waitcnt lgkmcnt(" #n ")" ::: "memory")
; #define PG8_BAR __builtin_amdgcn_s_barrier()
; #define PG8_SCHED __builtin_amdgcn_sched_barrier(0)
; template <class Epi, class Sched, bool ALIGN_EPI = false, bool SP2 = false>
; __device__ __forceinline__ void gemm_phase(PG8_LAS unsigned char* lds, const Gemm g, const Sched& S, const Epi& E) {
;     ...
;             PG8_LDB(B0, 0, 0); PG8_LDB(B1, 0, 1); PG8_SCHED; PG8_LDA(At, 0, 0); PG8_STAGE(PG8_SA(1, 1), a1 + hstep, voffA);
;             PG8_WAIT_V(8); PG8_WAIT_L(0); PG8_BAR; PG8_MMA(0, 0, At, B0); PG8_MMA(0, 1, At, B1); PG8_BAR; PG8_SCHED;
;             PG8_LDA(At, 0, 1); PG8_STAGE(PG8_SB(0, 0), b2, voffB); PG8_STAGE(PG8_SB(0, 1), b2 + hstep, voffB); PG8_STAGE(PG8_SA(0, 0), a2, voffA);
;             PG8_WAIT_V(8); PG8_WAIT_L(0); PG8_BAR; PG8_MMA(1, 0, At, B0); PG8_MMA(1, 1, At, B1); PG8_BAR; PG8_SCHED;
.LBB0_116:
	ds_read_b128 v[150:153], v147
	ds_read_b128 v[154:157], v147 offset:1024
	ds_read_b128 v[158:161], v147 offset:2048
	ds_read_b128 v[174:177], v147 offset:3072
	ds_read_b128 v[178:181], v148
	ds_read_b128 v[182:185], v148 offset:1024
	ds_read_b128 v[186:189], v148 offset:2048
	ds_read_b128 v[190:193], v148 offset:3072
	s_add_i32 s55, s54, 2
	s_add_u32 s28, s0, 0xfff80080
	s_addc_u32 s29, s1, -1
	s_cmp_eq_u32 s50, s54
	s_cselect_b32 s31, s21, s29
	s_cselect_b32 s30, s48, s28
	s_cselect_b32 s29, s19, s53
	s_cselect_b32 s28, s49, s51
	v_lshl_add_u64 v[138:139], s[0:1], 0, v[130:131]
	s_add_i32 m0, s27, 0xc000
	ds_read_b128 v[194:197], v149
	ds_read_b128 v[198:201], v149 offset:1024
	ds_read_b128 v[202:205], v149 offset:2048
	ds_read_b128 v[206:209], v149 offset:3072
	ds_read_b128 v[210:213], v149 offset:4096
	ds_read_b128 v[224:227], v149 offset:5120
	ds_read_b128 v[232:235], v149 offset:6144
	ds_read_b128 v[236:239], v149 offset:7168
	global_load_lds_dwordx4 v[138:139], off
	v_lshl_add_u64 v[138:139], s[0:1], 0, v[132:133]
	s_add_i32 m0, s27, 0xe000
	s_nop 0
	global_load_lds_dwordx4 v[138:139], off
	s_waitcnt vmcnt(8)
	s_waitcnt lgkmcnt(0)
	s_barrier
	s_setprio 1
	s_waitcnt lgkmcnt(0)
	v_mfma_f32_16x16x32_bf16 v[126:129], v[150:153], v[194:197], v[126:129]
	v_mfma_f32_16x16x32_bf16 v[122:125], v[158:161], v[194:197], v[122:125]
	v_mfma_f32_16x16x32_bf16 v[110:113], v[150:153], v[202:205], v[110:113]
	v_mfma_f32_16x16x32_bf16 v[106:109], v[158:161], v[202:205], v[106:109]
	v_mfma_f32_16x16x32_bf16 v[94:97], v[150:153], v[210:213], v[94:97]
	v_mfma_f32_16x16x32_bf16 v[90:93], v[158:161], v[210:213], v[90:93]
	v_mfma_f32_16x16x32_bf16 v[78:81], v[150:153], v[232:235], v[78:81]
	v_mfma_f32_16x16x32_bf16 v[74:77], v[158:161], v[232:235], v[74:77]
	v_mfma_f32_16x16x32_bf16 v[126:129], v[154:157], v[198:201], v[126:129]
	v_mfma_f32_16x16x32_bf16 v[122:125], v[174:177], v[198:201], v[122:125]
	v_mfma_f32_16x16x32_bf16 v[110:113], v[154:157], v[206:209], v[110:113]
	v_mfma_f32_16x16x32_bf16 v[106:109], v[174:177], v[206:209], v[106:109]
	v_mfma_f32_16x16x32_bf16 v[94:97], v[154:157], v[224:227], v[94:97]
	v_mfma_f32_16x16x32_bf16 v[90:93], v[174:177], v[224:227], v[90:93]
	v_mfma_f32_16x16x32_bf16 v[78:81], v[154:157], v[236:239], v[78:81]
	v_mfma_f32_16x16x32_bf16 v[74:77], v[174:177], v[236:239], v[74:77]
	v_mfma_f32_16x16x32_bf16 v[118:121], v[178:181], v[194:197], v[118:121]
	v_mfma_f32_16x16x32_bf16 v[114:117], v[186:189], v[194:197], v[114:117]
	v_mfma_f32_16x16x32_bf16 v[102:105], v[178:181], v[202:205], v[102:105]
	v_mfma_f32_16x16x32_bf16 v[98:101], v[186:189], v[202:205], v[98:101]
	v_mfma_f32_16x16x32_bf16 v[86:89], v[178:181], v[210:213], v[86:89]
	v_mfma_f32_16x16x32_bf16 v[82:85], v[186:189], v[210:213], v[82:85]
	v_mfma_f32_16x16x32_bf16 v[70:73], v[178:181], v[232:235], v[70:73]
	v_mfma_f32_16x16x32_bf16 v[66:69], v[186:189], v[232:235], v[66:69]
	v_mfma_f32_16x16x32_bf16 v[118:121], v[182:185], v[198:201], v[118:121]
	v_mfma_f32_16x16x32_bf16 v[114:117], v[190:193], v[198:201], v[114:117]
	v_mfma_f32_16x16x32_bf16 v[102:105], v[182:185], v[206:209], v[102:105]
	v_mfma_f32_16x16x32_bf16 v[98:101], v[190:193], v[206:209], v[98:101]
	v_mfma_f32_16x16x32_bf16 v[86:89], v[182:185], v[224:227], v[86:89]
	v_mfma_f32_16x16x32_bf16 v[82:85], v[190:193], v[224:227], v[82:85]
	v_mfma_f32_16x16x32_bf16 v[70:73], v[182:185], v[236:239], v[70:73]
	v_mfma_f32_16x16x32_bf16 v[66:69], v[190:193], v[236:239], v[66:69]
	s_setprio 0
	s_barrier
	s_add_i32 s54, s42, s2
	v_lshl_add_u64 v[138:139], s[28:29], 0, v[168:169]
	s_mov_b32 m0, s54
	ds_read_b128 v[194:197], v149 offset:16384
	ds_read_b128 v[198:201], v149 offset:17408
	ds_read_b128 v[202:205], v149 offset:18432
	ds_read_b128 v[206:209], v149 offset:19456
	ds_read_b128 v[210:213], v149 offset:20480
	ds_read_b128 v[224:227], v149 offset:21504
	ds_read_b128 v[232:235], v149 offset:22528
	ds_read_b128 v[236:239], v149 offset:23552
	global_load_lds_dwordx4 v[138:139], off
	s_add_i32 m0, s54, 0x2000
	s_add_u32 s56, s28, 0x80000
	v_lshl_add_u64 v[240:241], s[28:29], 0, v[172:173]
	s_addc_u32 s57, s29, 0
	s_add_i32 s54, s43, s2
	global_load_lds_dwordx4 v[240:241], off
	v_lshl_add_u64 v[242:243], s[56:57], 0, v[168:169]
	s_mov_b32 m0, s54
	v_lshl_add_u64 v[244:245], s[30:31], 0, v[170:171]
	global_load_lds_dwordx4 v[242:243], off
	v_lshl_add_u64 v[242:243], s[56:57], 0, v[172:173]
	s_add_i32 m0, s54, 0x2000
	s_nop 0
	global_load_lds_dwordx4 v[242:243], off
	v_lshl_add_u64 v[242:243], s[30:31], 0, v[166:167]
	s_mov_b32 m0, s27
	s_nop 0
	global_load_lds_dwordx4 v[242:243], off
	s_mov_b32 m0, s34
	s_nop 0
	global_load_lds_dwordx4 v[244:245], off
	s_waitcnt vmcnt(8)
	s_waitcnt lgkmcnt(0)
	s_barrier
; #define PG8_STAGE(bufoff, gbase, voff) do { _Pragma("unroll") for (int _i = 0; _i < 2; ++_i) \
;         __builtin_amdgcn_global_load_lds((const unsigned*)((const char*)(gbase) + (voff)[_i]), (PG8_LAS unsigned*)(lds + (bufoff) + ldsw + _i * 8192), 16, 0, 0); } while (0)
; #define PG8_LDA(dst, b, h) do { _Pragma("unroll") for (int m = 0; m < 4; ++m) _Pragma("unroll") for (int k = 0; k < 2; ++k) dst[m][k] = *(const PG8_LAS bf16x8*)(lds + PG8_SA(b, h) + aoff + m * 2048 + k * 1024); } while (0)
; #define PG8_LDB(dst, b, h) do { _Pragma("unroll") for (int n = 0; n < 2; ++n) _Pragma("unroll") for (int k = 0; k < 2; ++k) dst[n][k] = *(const PG8_LAS bf16x8*)(lds + PG8_SB(b, h) + boff + n * 2048 + k * 1024); } while (0)
; #define PG8_MMA(ai, bj, At, Bt) do { __builtin_amdgcn_s_setprio(1); _Pragma("unroll") for (int m = 0; m < 4; ++m) _Pragma("unroll") for (int n = 0; n < 2; ++n) _Pragma("unroll") for (int k = 0; k < 2; ++k) \
;         acc[ai][bj][m][n] = __builtin_amdgcn_mfma_f32_16x16x32_bf16(Bt[n][k], At[m][k], acc[ai][bj][m][n], 0, 0, 0); __builtin_amdgcn_s_setprio(0); } while (0)
; #define PG8_WAIT_V(n) asm volatile("s_waitcnt vmcnt(" #n ")" ::: "memory")
; #define PG8_WAIT_L(n) asm volatile("s_waitcnt lgkmcnt(" #n ")" ::: "memory")
; #define PG8_BAR __builtin_amdgcn_s_barrier()
; #define PG8_SCHED __builtin_amdgcn_sched_barrier(0)
; template <class Epi, class Sched, bool ALIGN_EPI = false, bool SP2 = false>
; __device__ __forceinline__ void gemm_phase(PG8_LAS unsigned char* lds, const Gemm g, const Sched& S, const Epi& E) {
;     ...
;             PG8_WAIT_V(8); PG8_WAIT_L(0); PG8_BAR; PG8_MMA(1, 0, At, B0); PG8_MMA(1, 1, At, B1); PG8_BAR; PG8_SCHED;
;             PG8_LDB(B0, 1, 0); PG8_LDB(B1, 1, 1); PG8_SCHED; PG8_LDA(At, 1, 0); PG8_STAGE(PG8_SA(0, 1), a2 + hstep, voffA);
;             PG8_WAIT_V(8); PG8_WAIT_L(0); PG8_BAR; PG8_MMA(0, 0, At, B0); PG8_MMA(0, 1, At, B1); PG8_BAR; PG8_SCHED;
;             PG8_LDA(At, 1, 1); PG8_STAGE(PG8_SB(1, 0), b3, voffB); PG8_STAGE(PG8_SB(1, 1), b3 + hstep, voffB); PG8_STAGE(PG8_SA(1, 0), a3, voffA);
	s_setprio 1
	s_waitcnt lgkmcnt(0)
	v_mfma_f32_16x16x32_bf16 v[62:65], v[150:153], v[194:197], v[62:65]
	v_mfma_f32_16x16x32_bf16 v[58:61], v[158:161], v[194:197], v[58:61]
	v_mfma_f32_16x16x32_bf16 v[46:49], v[150:153], v[202:205], v[46:49]
	v_mfma_f32_16x16x32_bf16 v[42:45], v[158:161], v[202:205], v[42:45]
	v_mfma_f32_16x16x32_bf16 v[30:33], v[150:153], v[210:213], v[30:33]
	v_mfma_f32_16x16x32_bf16 v[26:29], v[158:161], v[210:213], v[26:29]
	v_mfma_f32_16x16x32_bf16 v[14:17], v[150:153], v[232:235], v[14:17]
	v_mfma_f32_16x16x32_bf16 v[10:13], v[158:161], v[232:235], v[10:13]
	v_mfma_f32_16x16x32_bf16 v[62:65], v[154:157], v[198:201], v[62:65]
	v_mfma_f32_16x16x32_bf16 v[58:61], v[174:177], v[198:201], v[58:61]
	v_mfma_f32_16x16x32_bf16 v[46:49], v[154:157], v[206:209], v[46:49]
	v_mfma_f32_16x16x32_bf16 v[42:45], v[174:177], v[206:209], v[42:45]
	v_mfma_f32_16x16x32_bf16 v[30:33], v[154:157], v[224:227], v[30:33]
	v_mfma_f32_16x16x32_bf16 v[26:29], v[174:177], v[224:227], v[26:29]
	v_mfma_f32_16x16x32_bf16 v[14:17], v[154:157], v[236:239], v[14:17]
	v_mfma_f32_16x16x32_bf16 v[10:13], v[174:177], v[236:239], v[10:13]
	v_mfma_f32_16x16x32_bf16 v[54:57], v[178:181], v[194:197], v[54:57]
	v_mfma_f32_16x16x32_bf16 v[50:53], v[186:189], v[194:197], v[50:53]
	v_mfma_f32_16x16x32_bf16 v[38:41], v[178:181], v[202:205], v[38:41]
	v_mfma_f32_16x16x32_bf16 v[34:37], v[186:189], v[202:205], v[34:37]
	v_mfma_f32_16x16x32_bf16 v[22:25], v[178:181], v[210:213], v[22:25]
	v_mfma_f32_16x16x32_bf16 v[18:21], v[186:189], v[210:213], v[18:21]
	v_mfma_f32_16x16x32_bf16 v[6:9], v[178:181], v[232:235], v[6:9]
	v_mfma_f32_16x16x32_bf16 v[2:5], v[186:189], v[232:235], v[2:5]
	v_mfma_f32_16x16x32_bf16 v[54:57], v[182:185], v[198:201], v[54:57]
	v_mfma_f32_16x16x32_bf16 v[50:53], v[190:193], v[198:201], v[50:53]
	v_mfma_f32_16x16x32_bf16 v[38:41], v[182:185], v[206:209], v[38:41]
	v_mfma_f32_16x16x32_bf16 v[34:37], v[190:193], v[206:209], v[34:37]
	v_mfma_f32_16x16x32_bf16 v[22:25], v[182:185], v[224:227], v[22:25]
	v_mfma_f32_16x16x32_bf16 v[18:21], v[190:193], v[224:227], v[18:21]
	v_mfma_f32_16x16x32_bf16 v[6:9], v[182:185], v[236:239], v[6:9]
	v_mfma_f32_16x16x32_bf16 v[2:5], v[190:193], v[236:239], v[2:5]
	s_setprio 0
	s_barrier
	s_add_i32 s54, 0, 0x18000
	s_add_i32 s56, 0, 0x1c000
	v_add_u32_e32 v174, s54, v145
	v_add_u32_e32 v190, s56, v145
	ds_read_b128 v[150:153], v174
	ds_read_b128 v[154:157], v174 offset:1024
	ds_read_b128 v[158:161], v174 offset:2048
	ds_read_b128 v[174:177], v174 offset:3072
	ds_read_b128 v[178:181], v190
	ds_read_b128 v[182:185], v190 offset:1024
	ds_read_b128 v[186:189], v190 offset:2048
	ds_read_b128 v[190:193], v190 offset:3072
	s_add_u32 s30, s30, 0x80000
	s_addc_u32 s31, s31, 0
	s_mov_b32 m0, s35
	v_lshl_add_u64 v[246:247], s[30:31], 0, v[166:167]
	ds_read_b128 v[194:197], v149 offset:32768
	ds_read_b128 v[198:201], v149 offset:33792
	ds_read_b128 v[202:205], v149 offset:34816
	ds_read_b128 v[206:209], v149 offset:35840
	ds_read_b128 v[210:213], v149 offset:36864
	ds_read_b128 v[224:227], v149 offset:37888
	ds_read_b128 v[232:235], v149 offset:38912
	ds_read_b128 v[236:239], v149 offset:39936
	global_load_lds_dwordx4 v[246:247], off
	v_lshl_add_u64 v[246:247], s[30:31], 0, v[170:171]
	s_mov_b32 m0, s36
	s_nop 0
	global_load_lds_dwordx4 v[246:247], off
	s_waitcnt vmcnt(8)
	s_waitcnt lgkmcnt(0)
	s_barrier
	s_setprio 1
	s_waitcnt lgkmcnt(0)
	v_mfma_f32_16x16x32_bf16 v[126:129], v[150:153], v[194:197], v[126:129]
	v_mfma_f32_16x16x32_bf16 v[122:125], v[158:161], v[194:197], v[122:125]
	v_mfma_f32_16x16x32_bf16 v[110:113], v[150:153], v[202:205], v[110:113]
	v_mfma_f32_16x16x32_bf16 v[106:109], v[158:161], v[202:205], v[106:109]
	v_mfma_f32_16x16x32_bf16 v[94:97], v[150:153], v[210:213], v[94:97]
	v_mfma_f32_16x16x32_bf16 v[90:93], v[158:161], v[210:213], v[90:93]
	v_mfma_f32_16x16x32_bf16 v[78:81], v[150:153], v[232:235], v[78:81]
	v_mfma_f32_16x16x32_bf16 v[74:77], v[158:161], v[232:235], v[74:77]
	v_mfma_f32_16x16x32_bf16 v[126:129], v[154:157], v[198:201], v[126:129]
	v_mfma_f32_16x16x32_bf16 v[122:125], v[174:177], v[198:201], v[122:125]
	v_mfma_f32_16x16x32_bf16 v[110:113], v[154:157], v[206:209], v[110:113]
	v_mfma_f32_16x16x32_bf16 v[106:109], v[174:177], v[206:209], v[106:109]
	v_mfma_f32_16x16x32_bf16 v[94:97], v[154:157], v[224:227], v[94:97]
	v_mfma_f32_16x16x32_bf16 v[90:93], v[174:177], v[224:227], v[90:93]
	v_mfma_f32_16x16x32_bf16 v[78:81], v[154:157], v[236:239], v[78:81]
	v_mfma_f32_16x16x32_bf16 v[74:77], v[174:177], v[236:239], v[74:77]
	v_mfma_f32_16x16x32_bf16 v[118:121], v[178:181], v[194:197], v[118:121]
	v_mfma_f32_16x16x32_bf16 v[114:117], v[186:189], v[194:197], v[114:117]
	v_mfma_f32_16x16x32_bf16 v[102:105], v[178:181], v[202:205], v[102:105]
	v_mfma_f32_16x16x32_bf16 v[98:101], v[186:189], v[202:205], v[98:101]
	v_mfma_f32_16x16x32_bf16 v[86:89], v[178:181], v[210:213], v[86:89]
	v_mfma_f32_16x16x32_bf16 v[82:85], v[186:189], v[210:213], v[82:85]
	v_mfma_f32_16x16x32_bf16 v[70:73], v[178:181], v[232:235], v[70:73]
	v_mfma_f32_16x16x32_bf16 v[66:69], v[186:189], v[232:235], v[66:69]
	v_mfma_f32_16x16x32_bf16 v[118:121], v[182:185], v[198:201], v[118:121]
	v_mfma_f32_16x16x32_bf16 v[114:117], v[190:193], v[198:201], v[114:117]
	v_mfma_f32_16x16x32_bf16 v[102:105], v[182:185], v[206:209], v[102:105]
	v_mfma_f32_16x16x32_bf16 v[98:101], v[190:193], v[206:209], v[98:101]
	v_mfma_f32_16x16x32_bf16 v[86:89], v[182:185], v[224:227], v[86:89]
	v_mfma_f32_16x16x32_bf16 v[82:85], v[190:193], v[224:227], v[82:85]
	v_mfma_f32_16x16x32_bf16 v[70:73], v[182:185], v[236:239], v[70:73]
	v_mfma_f32_16x16x32_bf16 v[66:69], v[190:193], v[236:239], v[66:69]
	s_setprio 0
	s_barrier
; #define PG8_STAGE(bufoff, gbase, voff) do { _Pragma("unroll") for (int _i = 0; _i < 2; ++_i) \
;         __builtin_amdgcn_global_load_lds((const unsigned*)((const char*)(gbase) + (voff)[_i]), (PG8_LAS unsigned*)(lds + (bufoff) + ldsw + _i * 8192), 16, 0, 0); } while (0)
; #define PG8_LDA(dst, b, h) do { _Pragma("unroll") for (int m = 0; m < 4; ++m) _Pragma("unroll") for (int k = 0; k < 2; ++k) dst[m][k] = *(const PG8_LAS bf16x8*)(lds + PG8_SA(b, h) + aoff + m * 2048 + k * 1024); } while (0)
; #define PG8_MMA(ai, bj, At, Bt) do { __builtin_amdgcn_s_setprio(1); _Pragma("unroll") for (int m = 0; m < 4; ++m) _Pragma("unroll") for (int n = 0; n < 2; ++n) _Pragma("unroll") for (int k = 0; k < 2; ++k) \
;         acc[ai][bj][m][n] = __builtin_amdgcn_mfma_f32_16x16x32_bf16(Bt[n][k], At[m][k], acc[ai][bj][m][n], 0, 0, 0); __builtin_amdgcn_s_setprio(0); } while (0)
; #define PG8_WAIT_V(n) asm volatile("s_waitcnt vmcnt(" #n ")" ::: "memory")
; #define PG8_WAIT_L(n) asm volatile("s_waitcnt lgkmcnt(" #n ")" ::: "memory")
; #define PG8_BAR __builtin_amdgcn_s_barrier()
; #define PG8_SCHED __builtin_amdgcn_sched_barrier(0)
; template <class Epi, class Sched, bool ALIGN_EPI = false, bool SP2 = false>
; __device__ __forceinline__ void gemm_phase(PG8_LAS unsigned char* lds, const Gemm g, const Sched& S, const Epi& E) {
;     ...
;             PG8_LDA(At, 1, 1); PG8_STAGE(PG8_SB(1, 0), b3, voffB); PG8_STAGE(PG8_SB(1, 1), b3 + hstep, voffB); PG8_STAGE(PG8_SA(1, 0), a3, voffA);
;             PG8_WAIT_V(8); PG8_WAIT_L(0); PG8_BAR; PG8_MMA(1, 0, At, B0); PG8_MMA(1, 1, At, B1); PG8_BAR; PG8_SCHED;
	s_add_i32 s30, s54, s2
	v_lshl_add_u64 v[138:139], v[138:139], 0, s[14:15]
	s_mov_b32 m0, s30
	ds_read_b128 v[194:197], v149 offset:49152
	ds_read_b128 v[198:201], v149 offset:50176
	ds_read_b128 v[202:205], v149 offset:51200
	ds_read_b128 v[206:209], v149 offset:52224
	ds_read_b128 v[210:213], v149 offset:53248
	ds_read_b128 v[224:227], v149 offset:54272
	ds_read_b128 v[232:235], v149 offset:55296
	ds_read_b128 v[236:239], v149 offset:56320
	global_load_lds_dwordx4 v[138:139], off
	s_add_i32 m0, s30, 0x2000
	s_add_u32 s28, s28, 0x80080
	v_lshl_add_u64 v[138:139], v[240:241], 0, s[14:15]
	s_addc_u32 s29, s29, 0
	s_add_i32 s30, s56, s2
	global_load_lds_dwordx4 v[138:139], off
	v_lshl_add_u64 v[138:139], s[28:29], 0, v[168:169]
	s_mov_b32 m0, s30
	s_nop 0
	global_load_lds_dwordx4 v[138:139], off
	v_lshl_add_u64 v[138:139], s[28:29], 0, v[172:173]
	s_add_i32 m0, s30, 0x2000
	s_nop 0
	global_load_lds_dwordx4 v[138:139], off
	v_lshl_add_u64 v[138:139], v[242:243], 0, s[14:15]
	s_mov_b32 m0, s38
	s_nop 0
	global_load_lds_dwordx4 v[138:139], off
	v_lshl_add_u64 v[138:139], v[244:245], 0, s[14:15]
	s_mov_b32 m0, s39
	s_nop 0
	global_load_lds_dwordx4 v[138:139], off
	s_waitcnt vmcnt(8)
	s_waitcnt lgkmcnt(0)
	s_barrier
	s_setprio 1
	s_waitcnt lgkmcnt(0)
	v_mfma_f32_16x16x32_bf16 v[62:65], v[150:153], v[194:197], v[62:65]
	v_mfma_f32_16x16x32_bf16 v[58:61], v[158:161], v[194:197], v[58:61]
	v_mfma_f32_16x16x32_bf16 v[46:49], v[150:153], v[202:205], v[46:49]
	v_mfma_f32_16x16x32_bf16 v[42:45], v[158:161], v[202:205], v[42:45]
	v_mfma_f32_16x16x32_bf16 v[30:33], v[150:153], v[210:213], v[30:33]
	v_mfma_f32_16x16x32_bf16 v[26:29], v[158:161], v[210:213], v[26:29]
	v_mfma_f32_16x16x32_bf16 v[14:17], v[150:153], v[232:235], v[14:17]
	v_mfma_f32_16x16x32_bf16 v[10:13], v[158:161], v[232:235], v[10:13]
	v_mfma_f32_16x16x32_bf16 v[62:65], v[154:157], v[198:201], v[62:65]
	v_mfma_f32_16x16x32_bf16 v[58:61], v[174:177], v[198:201], v[58:61]
	v_mfma_f32_16x16x32_bf16 v[46:49], v[154:157], v[206:209], v[46:49]
	v_mfma_f32_16x16x32_bf16 v[42:45], v[174:177], v[206:209], v[42:45]
	v_mfma_f32_16x16x32_bf16 v[30:33], v[154:157], v[224:227], v[30:33]
	v_mfma_f32_16x16x32_bf16 v[26:29], v[174:177], v[224:227], v[26:29]
	v_mfma_f32_16x16x32_bf16 v[14:17], v[154:157], v[236:239], v[14:17]
	v_mfma_f32_16x16x32_bf16 v[10:13], v[174:177], v[236:239], v[10:13]
	v_mfma_f32_16x16x32_bf16 v[54:57], v[178:181], v[194:197], v[54:57]
	v_mfma_f32_16x16x32_bf16 v[50:53], v[186:189], v[194:197], v[50:53]
	v_mfma_f32_16x16x32_bf16 v[38:41], v[178:181], v[202:205], v[38:41]
	v_mfma_f32_16x16x32_bf16 v[34:37], v[186:189], v[202:205], v[34:37]
	v_mfma_f32_16x16x32_bf16 v[22:25], v[178:181], v[210:213], v[22:25]
	v_mfma_f32_16x16x32_bf16 v[18:21], v[186:189], v[210:213], v[18:21]
	v_mfma_f32_16x16x32_bf16 v[6:9], v[178:181], v[232:235], v[6:9]
	v_mfma_f32_16x16x32_bf16 v[2:5], v[186:189], v[232:235], v[2:5]
	v_mfma_f32_16x16x32_bf16 v[54:57], v[182:185], v[198:201], v[54:57]
	v_mfma_f32_16x16x32_bf16 v[50:53], v[190:193], v[198:201], v[50:53]
	v_mfma_f32_16x16x32_bf16 v[38:41], v[182:185], v[206:209], v[38:41]
	v_mfma_f32_16x16x32_bf16 v[34:37], v[190:193], v[206:209], v[34:37]
	v_mfma_f32_16x16x32_bf16 v[22:25], v[182:185], v[224:227], v[22:25]
	v_mfma_f32_16x16x32_bf16 v[18:21], v[190:193], v[224:227], v[18:21]
	v_mfma_f32_16x16x32_bf16 v[6:9], v[182:185], v[236:239], v[6:9]
	v_mfma_f32_16x16x32_bf16 v[2:5], v[190:193], v[236:239], v[2:5]
	s_setprio 0
	s_barrier
	s_add_u32 s0, s0, 0x100
	s_addc_u32 s1, s1, 0
	s_add_u32 s51, s51, 0x100
	s_addc_u32 s53, s53, 0
	s_cmp_ge_u32 s55, s47
	s_mov_b32 s54, s55
	s_cbranch_scc0 .LBB0_116
	s_and_b64 vcc, exec, s[16:17]
	s_cbranch_vccz .LBB0_119
	s_barrier

; #define PG8_STAGE(bufoff, gbase, voff) do { _Pragma("unroll") for (int _i = 0; _i < 2; ++_i) \
;         __builtin_amdgcn_global_load_lds((const unsigned*)((const char*)(gbase) + (voff)[_i]), (PG8_LAS unsigned*)(lds + (bufoff) + ldsw + _i * 8192), 16, 0, 0); } while (0)
; #define PG8_LDA(dst, b, h) do { _Pragma("unroll") for (int m = 0; m < 4; ++m) _Pragma("unroll") for (int k = 0; k < 2; ++k) dst[m][k] = *(const PG8_LAS bf16x8*)(lds + PG8_SA(b, h) + aoff + m * 2048 + k * 1024); } while (0)
; #define PG8_LDB(dst, b, h) do { _Pragma("unroll") for (int n = 0; n < 2; ++n) _Pragma("unroll") for (int k = 0; k < 2; ++k) dst[n][k] = *(const PG8_LAS bf16x8*)(lds + PG8_SB(b, h) + boff + n * 2048 + k * 1024); } while (0)
; #define PG8_MMA(ai, bj, At, Bt) do { __builtin_amdgcn_s_setprio(1); _Pragma("unroll") for (int m = 0; m < 4; ++m) _Pragma("unroll") for (int n = 0; n < 2; ++n) _Pragma("unroll") for (int k = 0; k < 2; ++k) \
;         acc[ai][bj][m][n] = __builtin_amdgcn_mfma_f32_16x16x32_bf16(Bt[n][k], At[m][k], acc[ai][bj][m][n], 0, 0, 0); __builtin_amdgcn_s_setprio(0); } while (0)
; #define PG8_WAIT_V(n) asm volatile("s_waitcnt vmcnt(" #n ")" ::: "memory")
; #define PG8_WAIT_L(n) asm volatile("s_waitcnt lgkmcnt(" #n ")" ::: "memory")
; #define PG8_BAR __builtin_amdgcn_s_barrier()
; #define PG8_SCHED __builtin_amdgcn_sched_barrier(0)
; template <class Epi, class Sched, bool ALIGN_EPI = false, bool SP2 = false>
; __device__ __forceinline__ void gemm_phase(PG8_LAS unsigned char* lds, const Gemm g, const Sched& S, const Epi& E) {
;     ...
;             PG8_LDB(B0, 0, 0); PG8_LDB(B1, 0, 1); PG8_SCHED; PG8_LDA(At, 0, 0); PG8_STAGE(PG8_SA(1, 1), a1 + hstep, voffA);
;             PG8_WAIT_V(8); PG8_WAIT_L(0); PG8_BAR; PG8_MMA(0, 0, At, B0); PG8_MMA(0, 1, At, B1); PG8_BAR; PG8_SCHED;
;             PG8_LDA(At, 0, 1); PG8_STAGE(PG8_SB(0, 0), b2, voffB); PG8_STAGE(PG8_SB(0, 1), b2 + hstep, voffB); PG8_STAGE(PG8_SA(0, 0), a2, voffA);
;             PG8_WAIT_V(8); PG8_WAIT_L(0); PG8_BAR; PG8_MMA(1, 0, At, B0); PG8_MMA(1, 1, At, B1); PG8_BAR; PG8_SCHED;
.LBB0_281:
	ds_read_b128 v[136:139], v146
	ds_read_b128 v[150:153], v146 offset:1024
	ds_read_b128 v[154:157], v146 offset:2048
	ds_read_b128 v[158:161], v146 offset:3072
	ds_read_b128 v[178:181], v147
	ds_read_b128 v[182:185], v147 offset:1024
	ds_read_b128 v[186:189], v147 offset:2048
	ds_read_b128 v[190:193], v147 offset:3072
	s_add_i32 s54, s24, 2
	s_add_u32 s25, s22, 0xffea0080
	s_addc_u32 s26, s23, -1
	s_cmp_eq_u32 s50, s24
	s_cselect_b32 s24, s20, s51
	s_cselect_b32 s27, s19, s26
	s_cselect_b32 s26, s18, s25
	s_cselect_b32 s25, s21, s53
	v_lshl_add_u64 v[244:245], s[22:23], 0, v[130:131]
	s_add_i32 m0, s3, 0xc000
	ds_read_b128 v[194:197], v148
	ds_read_b128 v[198:201], v148 offset:1024
	ds_read_b128 v[202:205], v148 offset:2048
	ds_read_b128 v[206:209], v148 offset:3072
	ds_read_b128 v[210:213], v148 offset:4096
	ds_read_b128 v[232:235], v148 offset:5120
	ds_read_b128 v[236:239], v148 offset:6144
	ds_read_b128 v[240:243], v148 offset:7168
	global_load_lds_dwordx4 v[244:245], off
	v_lshl_add_u64 v[244:245], s[22:23], 0, v[132:133]
	s_add_i32 m0, s3, 0xe000
	s_nop 0
	global_load_lds_dwordx4 v[244:245], off
	s_waitcnt vmcnt(8)
	s_waitcnt lgkmcnt(0)
	s_barrier
	s_setprio 1
	s_waitcnt lgkmcnt(0)
	v_mfma_f32_16x16x32_bf16 v[126:129], v[136:139], v[194:197], v[126:129]
	v_mfma_f32_16x16x32_bf16 v[122:125], v[154:157], v[194:197], v[122:125]
	v_mfma_f32_16x16x32_bf16 v[118:121], v[136:139], v[202:205], v[118:121]
	v_mfma_f32_16x16x32_bf16 v[114:117], v[154:157], v[202:205], v[114:117]
	v_mfma_f32_16x16x32_bf16 v[102:105], v[136:139], v[210:213], v[102:105]
	v_mfma_f32_16x16x32_bf16 v[98:101], v[154:157], v[210:213], v[98:101]
	v_mfma_f32_16x16x32_bf16 v[86:89], v[136:139], v[236:239], v[86:89]
	v_mfma_f32_16x16x32_bf16 v[82:85], v[154:157], v[236:239], v[82:85]
	v_mfma_f32_16x16x32_bf16 v[126:129], v[150:153], v[198:201], v[126:129]
	v_mfma_f32_16x16x32_bf16 v[122:125], v[158:161], v[198:201], v[122:125]
	v_mfma_f32_16x16x32_bf16 v[118:121], v[150:153], v[206:209], v[118:121]
	v_mfma_f32_16x16x32_bf16 v[114:117], v[158:161], v[206:209], v[114:117]
	v_mfma_f32_16x16x32_bf16 v[102:105], v[150:153], v[232:235], v[102:105]
	v_mfma_f32_16x16x32_bf16 v[98:101], v[158:161], v[232:235], v[98:101]
	v_mfma_f32_16x16x32_bf16 v[86:89], v[150:153], v[240:243], v[86:89]
	v_mfma_f32_16x16x32_bf16 v[82:85], v[158:161], v[240:243], v[82:85]
	v_mfma_f32_16x16x32_bf16 v[110:113], v[178:181], v[194:197], v[110:113]
	v_mfma_f32_16x16x32_bf16 v[106:109], v[186:189], v[194:197], v[106:109]
	v_mfma_f32_16x16x32_bf16 v[94:97], v[178:181], v[202:205], v[94:97]
	v_mfma_f32_16x16x32_bf16 v[90:93], v[186:189], v[202:205], v[90:93]
	v_mfma_f32_16x16x32_bf16 v[78:81], v[178:181], v[210:213], v[78:81]
	v_mfma_f32_16x16x32_bf16 v[74:77], v[186:189], v[210:213], v[74:77]
	v_mfma_f32_16x16x32_bf16 v[70:73], v[178:181], v[236:239], v[70:73]
	v_mfma_f32_16x16x32_bf16 v[66:69], v[186:189], v[236:239], v[66:69]
	v_mfma_f32_16x16x32_bf16 v[110:113], v[182:185], v[198:201], v[110:113]
	v_mfma_f32_16x16x32_bf16 v[106:109], v[190:193], v[198:201], v[106:109]
	v_mfma_f32_16x16x32_bf16 v[94:97], v[182:185], v[206:209], v[94:97]
	v_mfma_f32_16x16x32_bf16 v[90:93], v[190:193], v[206:209], v[90:93]
	v_mfma_f32_16x16x32_bf16 v[78:81], v[182:185], v[232:235], v[78:81]
	v_mfma_f32_16x16x32_bf16 v[74:77], v[190:193], v[232:235], v[74:77]
	v_mfma_f32_16x16x32_bf16 v[70:73], v[182:185], v[240:243], v[70:73]
	v_mfma_f32_16x16x32_bf16 v[66:69], v[190:193], v[240:243], v[66:69]
	s_setprio 0
	s_barrier
	s_add_i32 s55, s40, s2
	v_lshl_add_u64 v[244:245], s[24:25], 0, v[174:175]
	s_mov_b32 m0, s55
	ds_read_b128 v[194:197], v148 offset:16384
	ds_read_b128 v[198:201], v148 offset:17408
	ds_read_b128 v[202:205], v148 offset:18432
	ds_read_b128 v[206:209], v148 offset:19456
	ds_read_b128 v[210:213], v148 offset:20480
	ds_read_b128 v[232:235], v148 offset:21504
	ds_read_b128 v[236:239], v148 offset:22528
	ds_read_b128 v[240:243], v148 offset:23552
	global_load_lds_dwordx4 v[244:245], off
	s_add_i32 m0, s55, 0x2000
	s_add_u32 s56, s24, 0x160000
	v_lshl_add_u64 v[246:247], s[24:25], 0, v[176:177]
	s_addc_u32 s57, s25, 0
	s_add_i32 s55, s41, s2
	global_load_lds_dwordx4 v[246:247], off
	v_lshl_add_u64 v[248:249], s[56:57], 0, v[174:175]
	s_mov_b32 m0, s55
	v_lshl_add_u64 v[250:251], s[26:27], 0, v[176:177]
	global_load_lds_dwordx4 v[248:249], off
	v_lshl_add_u64 v[248:249], s[56:57], 0, v[176:177]
	s_add_i32 m0, s55, 0x2000
	s_nop 0
	global_load_lds_dwordx4 v[248:249], off
	v_lshl_add_u64 v[248:249], s[26:27], 0, v[174:175]
	s_mov_b32 m0, s3
	s_nop 0
	global_load_lds_dwordx4 v[248:249], off
	s_mov_b32 m0, s28
	s_nop 0
	global_load_lds_dwordx4 v[250:251], off
	s_waitcnt vmcnt(8)
	s_waitcnt lgkmcnt(0)
	s_barrier
; #define PG8_STAGE(bufoff, gbase, voff) do { _Pragma("unroll") for (int _i = 0; _i < 2; ++_i) \
;         __builtin_amdgcn_global_load_lds((const unsigned*)((const char*)(gbase) + (voff)[_i]), (PG8_LAS unsigned*)(lds + (bufoff) + ldsw + _i * 8192), 16, 0, 0); } while (0)
; #define PG8_LDA(dst, b, h) do { _Pragma("unroll") for (int m = 0; m < 4; ++m) _Pragma("unroll") for (int k = 0; k < 2; ++k) dst[m][k] = *(const PG8_LAS bf16x8*)(lds + PG8_SA(b, h) + aoff + m * 2048 + k * 1024); } while (0)
; #define PG8_LDB(dst, b, h) do { _Pragma("unroll") for (int n = 0; n < 2; ++n) _Pragma("unroll") for (int k = 0; k < 2; ++k) dst[n][k] = *(const PG8_LAS bf16x8*)(lds + PG8_SB(b, h) + boff + n * 2048 + k * 1024); } while (0)
; #define PG8_MMA(ai, bj, At, Bt) do { __builtin_amdgcn_s_setprio(1); _Pragma("unroll") for (int m = 0; m < 4; ++m) _Pragma("unroll") for (int n = 0; n < 2; ++n) _Pragma("unroll") for (int k = 0; k < 2; ++k) \
;         acc[ai][bj][m][n] = __builtin_amdgcn_mfma_f32_16x16x32_bf16(Bt[n][k], At[m][k], acc[ai][bj][m][n], 0, 0, 0); __builtin_amdgcn_s_setprio(0); } while (0)
; #define PG8_WAIT_V(n) asm volatile("s_waitcnt vmcnt(" #n ")" ::: "memory")
; #define PG8_WAIT_L(n) asm volatile("s_waitcnt lgkmcnt(" #n ")" ::: "memory")
; #define PG8_BAR __builtin_amdgcn_s_barrier()
; #define PG8_SCHED __builtin_amdgcn_sched_barrier(0)
; template <class Epi, class Sched, bool ALIGN_EPI = false, bool SP2 = false>
; __device__ __forceinline__ void gemm_phase(PG8_LAS unsigned char* lds, const Gemm g, const Sched& S, const Epi& E) {
;     ...
;             PG8_WAIT_V(8); PG8_WAIT_L(0); PG8_BAR; PG8_MMA(1, 0, At, B0); PG8_MMA(1, 1, At, B1); PG8_BAR; PG8_SCHED;
;             PG8_LDB(B0, 1, 0); PG8_LDB(B1, 1, 1); PG8_SCHED; PG8_LDA(At, 1, 0); PG8_STAGE(PG8_SA(0, 1), a2 + hstep, voffA);
;             PG8_WAIT_V(8); PG8_WAIT_L(0); PG8_BAR; PG8_MMA(0, 0, At, B0); PG8_MMA(0, 1, At, B1); PG8_BAR; PG8_SCHED;
	s_setprio 1
	s_waitcnt lgkmcnt(0)
	v_mfma_f32_16x16x32_bf16 v[62:65], v[136:139], v[194:197], v[62:65]
	v_mfma_f32_16x16x32_bf16 v[58:61], v[154:157], v[194:197], v[58:61]
	v_mfma_f32_16x16x32_bf16 v[54:57], v[136:139], v[202:205], v[54:57]
	v_mfma_f32_16x16x32_bf16 v[50:53], v[154:157], v[202:205], v[50:53]
	v_mfma_f32_16x16x32_bf16 v[38:41], v[136:139], v[210:213], v[38:41]
	v_mfma_f32_16x16x32_bf16 v[34:37], v[154:157], v[210:213], v[34:37]
	v_mfma_f32_16x16x32_bf16 v[22:25], v[136:139], v[236:239], v[22:25]
	v_mfma_f32_16x16x32_bf16 v[18:21], v[154:157], v[236:239], v[18:21]
	v_mfma_f32_16x16x32_bf16 v[62:65], v[150:153], v[198:201], v[62:65]
	v_mfma_f32_16x16x32_bf16 v[58:61], v[158:161], v[198:201], v[58:61]
	v_mfma_f32_16x16x32_bf16 v[54:57], v[150:153], v[206:209], v[54:57]
	v_mfma_f32_16x16x32_bf16 v[50:53], v[158:161], v[206:209], v[50:53]
	v_mfma_f32_16x16x32_bf16 v[38:41], v[150:153], v[232:235], v[38:41]
	v_mfma_f32_16x16x32_bf16 v[34:37], v[158:161], v[232:235], v[34:37]
	v_mfma_f32_16x16x32_bf16 v[22:25], v[150:153], v[240:243], v[22:25]
	v_mfma_f32_16x16x32_bf16 v[18:21], v[158:161], v[240:243], v[18:21]
	v_mfma_f32_16x16x32_bf16 v[46:49], v[178:181], v[194:197], v[46:49]
	v_mfma_f32_16x16x32_bf16 v[42:45], v[186:189], v[194:197], v[42:45]
	v_mfma_f32_16x16x32_bf16 v[30:33], v[178:181], v[202:205], v[30:33]
	v_mfma_f32_16x16x32_bf16 v[26:29], v[186:189], v[202:205], v[26:29]
	v_mfma_f32_16x16x32_bf16 v[14:17], v[178:181], v[210:213], v[14:17]
	v_mfma_f32_16x16x32_bf16 v[10:13], v[186:189], v[210:213], v[10:13]
	v_mfma_f32_16x16x32_bf16 v[6:9], v[178:181], v[236:239], v[6:9]
	v_mfma_f32_16x16x32_bf16 v[2:5], v[186:189], v[236:239], v[2:5]
	v_mfma_f32_16x16x32_bf16 v[46:49], v[182:185], v[198:201], v[46:49]
	v_mfma_f32_16x16x32_bf16 v[42:45], v[190:193], v[198:201], v[42:45]
	v_mfma_f32_16x16x32_bf16 v[30:33], v[182:185], v[206:209], v[30:33]
	v_mfma_f32_16x16x32_bf16 v[26:29], v[190:193], v[206:209], v[26:29]
	v_mfma_f32_16x16x32_bf16 v[14:17], v[182:185], v[232:235], v[14:17]
	v_mfma_f32_16x16x32_bf16 v[10:13], v[190:193], v[232:235], v[10:13]
	v_mfma_f32_16x16x32_bf16 v[6:9], v[182:185], v[240:243], v[6:9]
	v_mfma_f32_16x16x32_bf16 v[2:5], v[190:193], v[240:243], v[2:5]
	s_setprio 0
	s_barrier
	s_add_i32 s55, 0, 0x18000
	v_add_u32_e32 v149, s55, v144
	s_add_i32 s56, 0, 0x1c000
	ds_read_b128 v[136:139], v149
	ds_read_b128 v[150:153], v149 offset:1024
	ds_read_b128 v[154:157], v149 offset:2048
	ds_read_b128 v[158:161], v149 offset:3072
	v_add_u32_e32 v149, s56, v144
	ds_read_b128 v[178:181], v149
	ds_read_b128 v[182:185], v149 offset:1024
	ds_read_b128 v[186:189], v149 offset:2048
	ds_read_b128 v[190:193], v149 offset:3072
	s_add_u32 s26, s26, 0x160000
	s_addc_u32 s27, s27, 0
	s_mov_b32 m0, s29
	v_lshl_add_u64 v[252:253], s[26:27], 0, v[174:175]
	ds_read_b128 v[194:197], v148 offset:32768
	ds_read_b128 v[198:201], v148 offset:33792
	ds_read_b128 v[202:205], v148 offset:34816
	ds_read_b128 v[206:209], v148 offset:35840
	ds_read_b128 v[210:213], v148 offset:36864
	ds_read_b128 v[232:235], v148 offset:37888
	ds_read_b128 v[236:239], v148 offset:38912
	ds_read_b128 v[240:243], v148 offset:39936
	global_load_lds_dwordx4 v[252:253], off
	v_lshl_add_u64 v[252:253], s[26:27], 0, v[176:177]
	s_mov_b32 m0, s30
	s_nop 0
	global_load_lds_dwordx4 v[252:253], off
	s_waitcnt vmcnt(8)
	s_waitcnt lgkmcnt(0)
	s_barrier
	s_setprio 1
	s_waitcnt lgkmcnt(0)
	v_mfma_f32_16x16x32_bf16 v[126:129], v[136:139], v[194:197], v[126:129]
	v_mfma_f32_16x16x32_bf16 v[122:125], v[154:157], v[194:197], v[122:125]
	v_mfma_f32_16x16x32_bf16 v[118:121], v[136:139], v[202:205], v[118:121]
	v_mfma_f32_16x16x32_bf16 v[114:117], v[154:157], v[202:205], v[114:117]
	v_mfma_f32_16x16x32_bf16 v[102:105], v[136:139], v[210:213], v[102:105]
	v_mfma_f32_16x16x32_bf16 v[98:101], v[154:157], v[210:213], v[98:101]
	v_mfma_f32_16x16x32_bf16 v[86:89], v[136:139], v[236:239], v[86:89]
	v_mfma_f32_16x16x32_bf16 v[82:85], v[154:157], v[236:239], v[82:85]
	v_mfma_f32_16x16x32_bf16 v[126:129], v[150:153], v[198:201], v[126:129]
	v_mfma_f32_16x16x32_bf16 v[122:125], v[158:161], v[198:201], v[122:125]
	v_mfma_f32_16x16x32_bf16 v[118:121], v[150:153], v[206:209], v[118:121]
	v_mfma_f32_16x16x32_bf16 v[114:117], v[158:161], v[206:209], v[114:117]
	v_mfma_f32_16x16x32_bf16 v[102:105], v[150:153], v[232:235], v[102:105]
	v_mfma_f32_16x16x32_bf16 v[98:101], v[158:161], v[232:235], v[98:101]
	v_mfma_f32_16x16x32_bf16 v[86:89], v[150:153], v[240:243], v[86:89]
	v_mfma_f32_16x16x32_bf16 v[82:85], v[158:161], v[240:243], v[82:85]
	v_mfma_f32_16x16x32_bf16 v[110:113], v[178:181], v[194:197], v[110:113]
	v_mfma_f32_16x16x32_bf16 v[106:109], v[186:189], v[194:197], v[106:109]
	v_mfma_f32_16x16x32_bf16 v[94:97], v[178:181], v[202:205], v[94:97]
	v_mfma_f32_16x16x32_bf16 v[90:93], v[186:189], v[202:205], v[90:93]
	v_mfma_f32_16x16x32_bf16 v[78:81], v[178:181], v[210:213], v[78:81]
	v_mfma_f32_16x16x32_bf16 v[74:77], v[186:189], v[210:213], v[74:77]
	v_mfma_f32_16x16x32_bf16 v[70:73], v[178:181], v[236:239], v[70:73]
	v_mfma_f32_16x16x32_bf16 v[66:69], v[186:189], v[236:239], v[66:69]
	v_mfma_f32_16x16x32_bf16 v[110:113], v[182:185], v[198:201], v[110:113]
	v_mfma_f32_16x16x32_bf16 v[106:109], v[190:193], v[198:201], v[106:109]
	v_mfma_f32_16x16x32_bf16 v[94:97], v[182:185], v[206:209], v[94:97]
	v_mfma_f32_16x16x32_bf16 v[90:93], v[190:193], v[206:209], v[90:93]
	v_mfma_f32_16x16x32_bf16 v[78:81], v[182:185], v[232:235], v[78:81]
	v_mfma_f32_16x16x32_bf16 v[74:77], v[190:193], v[232:235], v[74:77]
	v_mfma_f32_16x16x32_bf16 v[70:73], v[182:185], v[240:243], v[70:73]
	v_mfma_f32_16x16x32_bf16 v[66:69], v[190:193], v[240:243], v[66:69]
	s_setprio 0
	s_barrier
; #define PG8_STAGE(bufoff, gbase, voff) do { _Pragma("unroll") for (int _i = 0; _i < 2; ++_i) \
;         __builtin_amdgcn_global_load_lds((const unsigned*)((const char*)(gbase) + (voff)[_i]), (PG8_LAS unsigned*)(lds + (bufoff) + ldsw + _i * 8192), 16, 0, 0); } while (0)
; #define PG8_LDA(dst, b, h) do { _Pragma("unroll") for (int m = 0; m < 4; ++m) _Pragma("unroll") for (int k = 0; k < 2; ++k) dst[m][k] = *(const PG8_LAS bf16x8*)(lds + PG8_SA(b, h) + aoff + m * 2048 + k * 1024); } while (0)
; #define PG8_MMA(ai, bj, At, Bt) do { __builtin_amdgcn_s_setprio(1); _Pragma("unroll") for (int m = 0; m < 4; ++m) _Pragma("unroll") for (int n = 0; n < 2; ++n) _Pragma("unroll") for (int k = 0; k < 2; ++k) \
;         acc[ai][bj][m][n] = __builtin_amdgcn_mfma_f32_16x16x32_bf16(Bt[n][k], At[m][k], acc[ai][bj][m][n], 0, 0, 0); __builtin_amdgcn_s_setprio(0); } while (0)
; #define PG8_WAIT_V(n) asm volatile("s_waitcnt vmcnt(" #n ")" ::: "memory")
; #define PG8_WAIT_L(n) asm volatile("s_waitcnt lgkmcnt(" #n ")" ::: "memory")
; #define PG8_BAR __builtin_amdgcn_s_barrier()
; #define PG8_SCHED __builtin_amdgcn_sched_barrier(0)
; template <class Epi, class Sched, bool ALIGN_EPI = false, bool SP2 = false>
; __device__ __forceinline__ void gemm_phase(PG8_LAS unsigned char* lds, const Gemm g, const Sched& S, const Epi& E) {
;     ...
;             PG8_LDA(At, 1, 1); PG8_STAGE(PG8_SB(1, 0), b3, voffB); PG8_STAGE(PG8_SB(1, 1), b3 + hstep, voffB); PG8_STAGE(PG8_SA(1, 0), a3, voffA);
;             PG8_WAIT_V(8); PG8_WAIT_L(0); PG8_BAR; PG8_MMA(1, 0, At, B0); PG8_MMA(1, 1, At, B1); PG8_BAR; PG8_SCHED;
;     ...
;         }
;         if constexpr (ALIGN_EPI) { if (wr == 0) PG8_BAR; }
	s_add_i32 s26, s55, s2
	v_lshl_add_u64 v[244:245], v[244:245], 0, s[12:13]
	s_mov_b32 m0, s26
	ds_read_b128 v[194:197], v148 offset:49152
	ds_read_b128 v[198:201], v148 offset:50176
	ds_read_b128 v[202:205], v148 offset:51200
	ds_read_b128 v[206:209], v148 offset:52224
	ds_read_b128 v[210:213], v148 offset:53248
	ds_read_b128 v[232:235], v148 offset:54272
	ds_read_b128 v[236:239], v148 offset:55296
	ds_read_b128 v[240:243], v148 offset:56320
	global_load_lds_dwordx4 v[244:245], off
	s_add_i32 m0, s26, 0x2000
	s_add_u32 s24, s24, 0x160080
	v_lshl_add_u64 v[244:245], v[246:247], 0, s[12:13]
	s_addc_u32 s25, s25, 0
	s_add_i32 s26, s56, s2
	global_load_lds_dwordx4 v[244:245], off
	v_lshl_add_u64 v[244:245], s[24:25], 0, v[174:175]
	s_mov_b32 m0, s26
	s_nop 0
	global_load_lds_dwordx4 v[244:245], off
	v_lshl_add_u64 v[244:245], s[24:25], 0, v[176:177]
	s_add_i32 m0, s26, 0x2000
	s_nop 0
	global_load_lds_dwordx4 v[244:245], off
	v_lshl_add_u64 v[244:245], v[248:249], 0, s[12:13]
	s_mov_b32 m0, s31
	s_nop 0
	global_load_lds_dwordx4 v[244:245], off
	v_lshl_add_u64 v[244:245], v[250:251], 0, s[12:13]
	s_mov_b32 m0, s33
	s_nop 0
	global_load_lds_dwordx4 v[244:245], off
	s_waitcnt vmcnt(8)
	s_waitcnt lgkmcnt(0)
	s_barrier
	s_setprio 1
	s_waitcnt lgkmcnt(0)
	v_mfma_f32_16x16x32_bf16 v[62:65], v[136:139], v[194:197], v[62:65]
	v_mfma_f32_16x16x32_bf16 v[58:61], v[154:157], v[194:197], v[58:61]
	v_mfma_f32_16x16x32_bf16 v[54:57], v[136:139], v[202:205], v[54:57]
	v_mfma_f32_16x16x32_bf16 v[50:53], v[154:157], v[202:205], v[50:53]
	v_mfma_f32_16x16x32_bf16 v[38:41], v[136:139], v[210:213], v[38:41]
	v_mfma_f32_16x16x32_bf16 v[34:37], v[154:157], v[210:213], v[34:37]
	v_mfma_f32_16x16x32_bf16 v[22:25], v[136:139], v[236:239], v[22:25]
	v_mfma_f32_16x16x32_bf16 v[18:21], v[154:157], v[236:239], v[18:21]
	v_mfma_f32_16x16x32_bf16 v[62:65], v[150:153], v[198:201], v[62:65]
	v_mfma_f32_16x16x32_bf16 v[58:61], v[158:161], v[198:201], v[58:61]
	v_mfma_f32_16x16x32_bf16 v[54:57], v[150:153], v[206:209], v[54:57]
	v_mfma_f32_16x16x32_bf16 v[50:53], v[158:161], v[206:209], v[50:53]
	v_mfma_f32_16x16x32_bf16 v[38:41], v[150:153], v[232:235], v[38:41]
	v_mfma_f32_16x16x32_bf16 v[34:37], v[158:161], v[232:235], v[34:37]
	v_mfma_f32_16x16x32_bf16 v[22:25], v[150:153], v[240:243], v[22:25]
	v_mfma_f32_16x16x32_bf16 v[18:21], v[158:161], v[240:243], v[18:21]
	v_mfma_f32_16x16x32_bf16 v[46:49], v[178:181], v[194:197], v[46:49]
	v_mfma_f32_16x16x32_bf16 v[42:45], v[186:189], v[194:197], v[42:45]
	v_mfma_f32_16x16x32_bf16 v[30:33], v[178:181], v[202:205], v[30:33]
	v_mfma_f32_16x16x32_bf16 v[26:29], v[186:189], v[202:205], v[26:29]
	v_mfma_f32_16x16x32_bf16 v[14:17], v[178:181], v[210:213], v[14:17]
	v_mfma_f32_16x16x32_bf16 v[10:13], v[186:189], v[210:213], v[10:13]
	v_mfma_f32_16x16x32_bf16 v[6:9], v[178:181], v[236:239], v[6:9]
	v_mfma_f32_16x16x32_bf16 v[2:5], v[186:189], v[236:239], v[2:5]
	v_mfma_f32_16x16x32_bf16 v[46:49], v[182:185], v[198:201], v[46:49]
	v_mfma_f32_16x16x32_bf16 v[42:45], v[190:193], v[198:201], v[42:45]
	v_mfma_f32_16x16x32_bf16 v[30:33], v[182:185], v[206:209], v[30:33]
	v_mfma_f32_16x16x32_bf16 v[26:29], v[190:193], v[206:209], v[26:29]
	v_mfma_f32_16x16x32_bf16 v[14:17], v[182:185], v[232:235], v[14:17]
	v_mfma_f32_16x16x32_bf16 v[10:13], v[190:193], v[232:235], v[10:13]
	v_mfma_f32_16x16x32_bf16 v[6:9], v[182:185], v[240:243], v[6:9]
	v_mfma_f32_16x16x32_bf16 v[2:5], v[190:193], v[240:243], v[2:5]
	s_setprio 0
	s_barrier
	s_add_u32 s22, s22, 0x100
	s_addc_u32 s23, s23, 0
	s_add_u32 s51, s51, 0x100
	s_addc_u32 s53, s53, 0
	s_cmp_ge_u32 s54, s43
	s_mov_b32 s24, s54
	s_cbranch_scc0 .LBB0_281
	s_and_b64 vcc, exec, s[14:15]
	s_cbranch_vccz .LBB0_284
	s_barrier

; #define PG8_STAGE(bufoff, gbase, voff) do { _Pragma("unroll") for (int _i = 0; _i < 2; ++_i) \
;         __builtin_amdgcn_global_load_lds((const unsigned*)((const char*)(gbase) + (voff)[_i]), (PG8_LAS unsigned*)(lds + (bufoff) + ldsw + _i * 8192), 16, 0, 0); } while (0)
; #define PG8_LDA(dst, b, h) do { _Pragma("unroll") for (int m = 0; m < 4; ++m) _Pragma("unroll") for (int k = 0; k < 2; ++k) dst[m][k] = *(const PG8_LAS bf16x8*)(lds + PG8_SA(b, h) + aoff + m * 2048 + k * 1024); } while (0)
; #define PG8_LDB(dst, b, h) do { _Pragma("unroll") for (int n = 0; n < 2; ++n) _Pragma("unroll") for (int k = 0; k < 2; ++k) dst[n][k] = *(const PG8_LAS bf16x8*)(lds + PG8_SB(b, h) + boff + n * 2048 + k * 1024); } while (0)
; #define PG8_MMA(ai, bj, At, Bt) do { __builtin_amdgcn_s_setprio(1); _Pragma("unroll") for (int m = 0; m < 4; ++m) _Pragma("unroll") for (int n = 0; n < 2; ++n) _Pragma("unroll") for (int k = 0; k < 2; ++k) \
;         acc[ai][bj][m][n] = __builtin_amdgcn_mfma_f32_16x16x32_bf16(Bt[n][k], At[m][k], acc[ai][bj][m][n], 0, 0, 0); __builtin_amdgcn_s_setprio(0); } while (0)
; #define PG8_WAIT_V(n) asm volatile("s_waitcnt vmcnt(" #n ")" ::: "memory")
; #define PG8_WAIT_L(n) asm volatile("s_waitcnt lgkmcnt(" #n ")" ::: "memory")
; #define PG8_BAR __builtin_amdgcn_s_barrier()
; #define PG8_SCHED __builtin_amdgcn_sched_barrier(0)
; template <class Epi, class Sched, bool ALIGN_EPI = false, bool SP2 = false>
; __device__ __forceinline__ void gemm_phase(PG8_LAS unsigned char* lds, const Gemm g, const Sched& S, const Epi& E) {
;     ...
;         for (int t = 0; t < nt; t += 2) {
;             const bool last = (t == nt - 2);
;             const char* a1 = cA + (size_t)(t + 1) * kstep;
;             const char* a2 = last ? nA : cA + (size_t)(t + 2) * kstep; const char* b2 = last ? nB : cB + (size_t)(t + 2) * kstep;
;             const char* a3 = a2 + kstep; const char* b3 = b2 + kstep;
;             if (last && has_next) S.a_ready(nxt);
;             if constexpr (SP2) {
;             PG8_LDB(B0, 0, 0); PG8_LDB(B1, 0, 1); PG8_SCHED; PG8_LDA(At, 0, 0); PG8_STAGE(PG8_SA(1, 1), a1 + hstep, voffA);
;             PG8_WAIT_V(8); PG8_WAIT_L(0); PG8_BAR; PG8_MMA(0, 0, At, B0); PG8_MMA(0, 1, At, B1); PG8_BAR; PG8_SCHED;
;             PG8_LDA(At, 0, 1); PG8_STAGE(PG8_SB(0, 0), b2, voffB); PG8_STAGE(PG8_SB(0, 1), b2 + hstep, voffB); PG8_STAGE(PG8_SA(0, 0), a2, voffA);
.LBB0_423:
	ds_read_b128 v[146:149], v139
	ds_read_b128 v[150:153], v139 offset:1024
	ds_read_b128 v[154:157], v139 offset:2048
	ds_read_b128 v[158:161], v139 offset:3072
	ds_read_b128 v[180:183], v143
	ds_read_b128 v[184:187], v143 offset:1024
	ds_read_b128 v[188:191], v143 offset:2048
	ds_read_b128 v[192:195], v143 offset:3072
	s_add_i32 s49, s48, 2
	s_add_u32 s24, s4, 0xfff80080
	s_addc_u32 s25, s5, -1
	s_cmp_eq_u32 s45, s48
	s_cselect_b32 s27, s19, s25
	s_cselect_b32 s26, s43, s24
	s_cselect_b32 s25, s17, s47
	s_cselect_b32 s24, s44, s46
	v_lshl_add_u64 v[212:213], s[4:5], 0, v[130:131]
	s_add_i32 m0, s15, 0xc000
	ds_read_b128 v[196:199], v144
	ds_read_b128 v[200:203], v144 offset:1024
	ds_read_b128 v[204:207], v144 offset:2048
	ds_read_b128 v[208:211], v144 offset:3072
	ds_read_b128 v[232:235], v144 offset:4096
	ds_read_b128 v[236:239], v144 offset:5120
	ds_read_b128 v[240:243], v144 offset:6144
	ds_read_b128 v[244:247], v144 offset:7168
	global_load_lds_dwordx4 v[212:213], off
	v_lshl_add_u64 v[212:213], s[4:5], 0, v[132:133]
	s_add_i32 m0, s15, 0xe000
	s_nop 0
	global_load_lds_dwordx4 v[212:213], off
	s_waitcnt vmcnt(8)
	s_waitcnt lgkmcnt(0)
	s_barrier
	s_setprio 1
	s_waitcnt lgkmcnt(0)
	v_mfma_f32_16x16x32_bf16 v[126:129], v[146:149], v[196:199], v[126:129]
	v_mfma_f32_16x16x32_bf16 v[122:125], v[154:157], v[196:199], v[122:125]
	v_mfma_f32_16x16x32_bf16 v[118:121], v[146:149], v[204:207], v[118:121]
	v_mfma_f32_16x16x32_bf16 v[114:117], v[154:157], v[204:207], v[114:117]
	v_mfma_f32_16x16x32_bf16 v[102:105], v[146:149], v[232:235], v[102:105]
	v_mfma_f32_16x16x32_bf16 v[98:101], v[154:157], v[232:235], v[98:101]
	v_mfma_f32_16x16x32_bf16 v[86:89], v[146:149], v[240:243], v[86:89]
	v_mfma_f32_16x16x32_bf16 v[82:85], v[154:157], v[240:243], v[82:85]
	v_mfma_f32_16x16x32_bf16 v[126:129], v[150:153], v[200:203], v[126:129]
	v_mfma_f32_16x16x32_bf16 v[122:125], v[158:161], v[200:203], v[122:125]
	v_mfma_f32_16x16x32_bf16 v[118:121], v[150:153], v[208:211], v[118:121]
	v_mfma_f32_16x16x32_bf16 v[114:117], v[158:161], v[208:211], v[114:117]
	v_mfma_f32_16x16x32_bf16 v[102:105], v[150:153], v[236:239], v[102:105]
	v_mfma_f32_16x16x32_bf16 v[98:101], v[158:161], v[236:239], v[98:101]
	v_mfma_f32_16x16x32_bf16 v[86:89], v[150:153], v[244:247], v[86:89]
	v_mfma_f32_16x16x32_bf16 v[82:85], v[158:161], v[244:247], v[82:85]
	v_mfma_f32_16x16x32_bf16 v[110:113], v[180:183], v[196:199], v[110:113]
	v_mfma_f32_16x16x32_bf16 v[106:109], v[188:191], v[196:199], v[106:109]
	v_mfma_f32_16x16x32_bf16 v[94:97], v[180:183], v[204:207], v[94:97]
	v_mfma_f32_16x16x32_bf16 v[90:93], v[188:191], v[204:207], v[90:93]
	v_mfma_f32_16x16x32_bf16 v[78:81], v[180:183], v[232:235], v[78:81]
	v_mfma_f32_16x16x32_bf16 v[74:77], v[188:191], v[232:235], v[74:77]
	v_mfma_f32_16x16x32_bf16 v[70:73], v[180:183], v[240:243], v[70:73]
	v_mfma_f32_16x16x32_bf16 v[66:69], v[188:191], v[240:243], v[66:69]
	v_mfma_f32_16x16x32_bf16 v[110:113], v[184:187], v[200:203], v[110:113]
	v_mfma_f32_16x16x32_bf16 v[106:109], v[192:195], v[200:203], v[106:109]
	v_mfma_f32_16x16x32_bf16 v[94:97], v[184:187], v[208:211], v[94:97]
	v_mfma_f32_16x16x32_bf16 v[90:93], v[192:195], v[208:211], v[90:93]
	v_mfma_f32_16x16x32_bf16 v[78:81], v[184:187], v[236:239], v[78:81]
	v_mfma_f32_16x16x32_bf16 v[74:77], v[192:195], v[236:239], v[74:77]
	v_mfma_f32_16x16x32_bf16 v[70:73], v[184:187], v[244:247], v[70:73]
	v_mfma_f32_16x16x32_bf16 v[66:69], v[192:195], v[244:247], v[66:69]
	s_setprio 0
	s_barrier
	s_add_i32 s48, s37, s2
	v_lshl_add_u64 v[212:213], s[24:25], 0, v[168:169]
	s_mov_b32 m0, s48
	ds_read_b128 v[196:199], v144 offset:16384
	ds_read_b128 v[200:203], v144 offset:17408
	ds_read_b128 v[204:207], v144 offset:18432
	ds_read_b128 v[208:211], v144 offset:19456
	ds_read_b128 v[232:235], v144 offset:20480
	ds_read_b128 v[236:239], v144 offset:21504
	ds_read_b128 v[240:243], v144 offset:22528
	ds_read_b128 v[244:247], v144 offset:23552
	global_load_lds_dwordx4 v[212:213], off
	s_add_i32 m0, s48, 0x2000
	s_add_u32 s50, s24, 0x80000
	v_lshl_add_u64 v[248:249], s[24:25], 0, v[172:173]
	s_addc_u32 s51, s25, 0
	s_add_i32 s48, s38, s2
	global_load_lds_dwordx4 v[248:249], off
	v_lshl_add_u64 v[250:251], s[50:51], 0, v[168:169]
	s_mov_b32 m0, s48
	v_lshl_add_u64 v[252:253], s[26:27], 0, v[170:171]
	global_load_lds_dwordx4 v[250:251], off
	v_lshl_add_u64 v[250:251], s[50:51], 0, v[172:173]
	s_add_i32 m0, s48, 0x2000
	s_nop 0
	global_load_lds_dwordx4 v[250:251], off
	v_lshl_add_u64 v[250:251], s[26:27], 0, v[166:167]
	s_mov_b32 m0, s15
	s_nop 0
	global_load_lds_dwordx4 v[250:251], off
	s_mov_b32 m0, s29
	s_nop 0
	global_load_lds_dwordx4 v[252:253], off
	s_waitcnt vmcnt(8)
	s_waitcnt lgkmcnt(0)
	s_barrier
; #define PG8_STAGE(bufoff, gbase, voff) do { _Pragma("unroll") for (int _i = 0; _i < 2; ++_i) \
;         __builtin_amdgcn_global_load_lds((const unsigned*)((const char*)(gbase) + (voff)[_i]), (PG8_LAS unsigned*)(lds + (bufoff) + ldsw + _i * 8192), 16, 0, 0); } while (0)
; #define PG8_LDA(dst, b, h) do { _Pragma("unroll") for (int m = 0; m < 4; ++m) _Pragma("unroll") for (int k = 0; k < 2; ++k) dst[m][k] = *(const PG8_LAS bf16x8*)(lds + PG8_SA(b, h) + aoff + m * 2048 + k * 1024); } while (0)
; #define PG8_LDB(dst, b, h) do { _Pragma("unroll") for (int n = 0; n < 2; ++n) _Pragma("unroll") for (int k = 0; k < 2; ++k) dst[n][k] = *(const PG8_LAS bf16x8*)(lds + PG8_SB(b, h) + boff + n * 2048 + k * 1024); } while (0)
; #define PG8_MMA(ai, bj, At, Bt) do { __builtin_amdgcn_s_setprio(1); _Pragma("unroll") for (int m = 0; m < 4; ++m) _Pragma("unroll") for (int n = 0; n < 2; ++n) _Pragma("unroll") for (int k = 0; k < 2; ++k) \
;         acc[ai][bj][m][n] = __builtin_amdgcn_mfma_f32_16x16x32_bf16(Bt[n][k], At[m][k], acc[ai][bj][m][n], 0, 0, 0); __builtin_amdgcn_s_setprio(0); } while (0)
; #define PG8_WAIT_V(n) asm volatile("s_waitcnt vmcnt(" #n ")" ::: "memory")
; #define PG8_WAIT_L(n) asm volatile("s_waitcnt lgkmcnt(" #n ")" ::: "memory")
; #define PG8_BAR __builtin_amdgcn_s_barrier()
; #define PG8_SCHED __builtin_amdgcn_sched_barrier(0)
; template <class Epi, class Sched, bool ALIGN_EPI = false, bool SP2 = false>
; __device__ __forceinline__ void gemm_phase(PG8_LAS unsigned char* lds, const Gemm g, const Sched& S, const Epi& E) {
;     ...
;             PG8_WAIT_V(8); PG8_WAIT_L(0); PG8_BAR; PG8_MMA(1, 0, At, B0); PG8_MMA(1, 1, At, B1); PG8_BAR; PG8_SCHED;
;             PG8_LDB(B0, 1, 0); PG8_LDB(B1, 1, 1); PG8_SCHED; PG8_LDA(At, 1, 0); PG8_STAGE(PG8_SA(0, 1), a2 + hstep, voffA);
;             PG8_WAIT_V(8); PG8_WAIT_L(0); PG8_BAR; PG8_MMA(0, 0, At, B0); PG8_MMA(0, 1, At, B1); PG8_BAR; PG8_SCHED;
	s_setprio 1
	s_waitcnt lgkmcnt(0)
	v_mfma_f32_16x16x32_bf16 v[62:65], v[146:149], v[196:199], v[62:65]
	v_mfma_f32_16x16x32_bf16 v[58:61], v[154:157], v[196:199], v[58:61]
	v_mfma_f32_16x16x32_bf16 v[54:57], v[146:149], v[204:207], v[54:57]
	v_mfma_f32_16x16x32_bf16 v[50:53], v[154:157], v[204:207], v[50:53]
	v_mfma_f32_16x16x32_bf16 v[38:41], v[146:149], v[232:235], v[38:41]
	v_mfma_f32_16x16x32_bf16 v[34:37], v[154:157], v[232:235], v[34:37]
	v_mfma_f32_16x16x32_bf16 v[22:25], v[146:149], v[240:243], v[22:25]
	v_mfma_f32_16x16x32_bf16 v[18:21], v[154:157], v[240:243], v[18:21]
	v_mfma_f32_16x16x32_bf16 v[62:65], v[150:153], v[200:203], v[62:65]
	v_mfma_f32_16x16x32_bf16 v[58:61], v[158:161], v[200:203], v[58:61]
	v_mfma_f32_16x16x32_bf16 v[54:57], v[150:153], v[208:211], v[54:57]
	v_mfma_f32_16x16x32_bf16 v[50:53], v[158:161], v[208:211], v[50:53]
	v_mfma_f32_16x16x32_bf16 v[38:41], v[150:153], v[236:239], v[38:41]
	v_mfma_f32_16x16x32_bf16 v[34:37], v[158:161], v[236:239], v[34:37]
	v_mfma_f32_16x16x32_bf16 v[22:25], v[150:153], v[244:247], v[22:25]
	v_mfma_f32_16x16x32_bf16 v[18:21], v[158:161], v[244:247], v[18:21]
	v_mfma_f32_16x16x32_bf16 v[46:49], v[180:183], v[196:199], v[46:49]
	v_mfma_f32_16x16x32_bf16 v[42:45], v[188:191], v[196:199], v[42:45]
	v_mfma_f32_16x16x32_bf16 v[30:33], v[180:183], v[204:207], v[30:33]
	v_mfma_f32_16x16x32_bf16 v[26:29], v[188:191], v[204:207], v[26:29]
	v_mfma_f32_16x16x32_bf16 v[14:17], v[180:183], v[232:235], v[14:17]
	v_mfma_f32_16x16x32_bf16 v[10:13], v[188:191], v[232:235], v[10:13]
	v_mfma_f32_16x16x32_bf16 v[6:9], v[180:183], v[240:243], v[6:9]
	v_mfma_f32_16x16x32_bf16 v[2:5], v[188:191], v[240:243], v[2:5]
	v_mfma_f32_16x16x32_bf16 v[46:49], v[184:187], v[200:203], v[46:49]
	v_mfma_f32_16x16x32_bf16 v[42:45], v[192:195], v[200:203], v[42:45]
	v_mfma_f32_16x16x32_bf16 v[30:33], v[184:187], v[208:211], v[30:33]
	v_mfma_f32_16x16x32_bf16 v[26:29], v[192:195], v[208:211], v[26:29]
	v_mfma_f32_16x16x32_bf16 v[14:17], v[184:187], v[236:239], v[14:17]
	v_mfma_f32_16x16x32_bf16 v[10:13], v[192:195], v[236:239], v[10:13]
	v_mfma_f32_16x16x32_bf16 v[6:9], v[184:187], v[244:247], v[6:9]
	v_mfma_f32_16x16x32_bf16 v[2:5], v[192:195], v[244:247], v[2:5]
	s_setprio 0
	s_barrier
	s_add_i32 s48, 0, 0x18000
	v_add_u32_e32 v145, s48, v137
	s_add_i32 s50, 0, 0x1c000
	ds_read_b128 v[146:149], v145
	ds_read_b128 v[150:153], v145 offset:1024
	ds_read_b128 v[154:157], v145 offset:2048
	ds_read_b128 v[158:161], v145 offset:3072
	v_add_u32_e32 v145, s50, v137
	ds_read_b128 v[180:183], v145
	ds_read_b128 v[184:187], v145 offset:1024
	ds_read_b128 v[188:191], v145 offset:2048
	ds_read_b128 v[192:195], v145 offset:3072
	s_add_u32 s26, s26, 0x80000
	s_addc_u32 s27, s27, 0
	s_mov_b32 m0, s30
	v_lshl_add_u64 v[222:223], s[26:27], 0, v[166:167]
	ds_read_b128 v[196:199], v144 offset:32768
	ds_read_b128 v[200:203], v144 offset:33792
	ds_read_b128 v[204:207], v144 offset:34816
	ds_read_b128 v[208:211], v144 offset:35840
	ds_read_b128 v[232:235], v144 offset:36864
	ds_read_b128 v[236:239], v144 offset:37888
	ds_read_b128 v[240:243], v144 offset:38912
	ds_read_b128 v[244:247], v144 offset:39936
	global_load_lds_dwordx4 v[222:223], off
	v_lshl_add_u64 v[222:223], s[26:27], 0, v[170:171]
	s_mov_b32 m0, s31
	s_nop 0
	global_load_lds_dwordx4 v[222:223], off
	s_waitcnt vmcnt(8)
	s_waitcnt lgkmcnt(0)
	s_barrier
	s_setprio 1
	s_waitcnt lgkmcnt(0)
	v_mfma_f32_16x16x32_bf16 v[126:129], v[146:149], v[196:199], v[126:129]
	v_mfma_f32_16x16x32_bf16 v[122:125], v[154:157], v[196:199], v[122:125]
	v_mfma_f32_16x16x32_bf16 v[118:121], v[146:149], v[204:207], v[118:121]
	v_mfma_f32_16x16x32_bf16 v[114:117], v[154:157], v[204:207], v[114:117]
	v_mfma_f32_16x16x32_bf16 v[102:105], v[146:149], v[232:235], v[102:105]
	v_mfma_f32_16x16x32_bf16 v[98:101], v[154:157], v[232:235], v[98:101]
	v_mfma_f32_16x16x32_bf16 v[86:89], v[146:149], v[240:243], v[86:89]
	v_mfma_f32_16x16x32_bf16 v[82:85], v[154:157], v[240:243], v[82:85]
	v_mfma_f32_16x16x32_bf16 v[126:129], v[150:153], v[200:203], v[126:129]
	v_mfma_f32_16x16x32_bf16 v[122:125], v[158:161], v[200:203], v[122:125]
	v_mfma_f32_16x16x32_bf16 v[118:121], v[150:153], v[208:211], v[118:121]
	v_mfma_f32_16x16x32_bf16 v[114:117], v[158:161], v[208:211], v[114:117]
	v_mfma_f32_16x16x32_bf16 v[102:105], v[150:153], v[236:239], v[102:105]
	v_mfma_f32_16x16x32_bf16 v[98:101], v[158:161], v[236:239], v[98:101]
	v_mfma_f32_16x16x32_bf16 v[86:89], v[150:153], v[244:247], v[86:89]
	v_mfma_f32_16x16x32_bf16 v[82:85], v[158:161], v[244:247], v[82:85]
	v_mfma_f32_16x16x32_bf16 v[110:113], v[180:183], v[196:199], v[110:113]
	v_mfma_f32_16x16x32_bf16 v[106:109], v[188:191], v[196:199], v[106:109]
	v_mfma_f32_16x16x32_bf16 v[94:97], v[180:183], v[204:207], v[94:97]
	v_mfma_f32_16x16x32_bf16 v[90:93], v[188:191], v[204:207], v[90:93]
	v_mfma_f32_16x16x32_bf16 v[78:81], v[180:183], v[232:235], v[78:81]
	v_mfma_f32_16x16x32_bf16 v[74:77], v[188:191], v[232:235], v[74:77]
	v_mfma_f32_16x16x32_bf16 v[70:73], v[180:183], v[240:243], v[70:73]
	v_mfma_f32_16x16x32_bf16 v[66:69], v[188:191], v[240:243], v[66:69]
	v_mfma_f32_16x16x32_bf16 v[110:113], v[184:187], v[200:203], v[110:113]
	v_mfma_f32_16x16x32_bf16 v[106:109], v[192:195], v[200:203], v[106:109]
	v_mfma_f32_16x16x32_bf16 v[94:97], v[184:187], v[208:211], v[94:97]
	v_mfma_f32_16x16x32_bf16 v[90:93], v[192:195], v[208:211], v[90:93]
	v_mfma_f32_16x16x32_bf16 v[78:81], v[184:187], v[236:239], v[78:81]
	v_mfma_f32_16x16x32_bf16 v[74:77], v[192:195], v[236:239], v[74:77]
	v_mfma_f32_16x16x32_bf16 v[70:73], v[184:187], v[244:247], v[70:73]
	v_mfma_f32_16x16x32_bf16 v[66:69], v[192:195], v[244:247], v[66:69]
	s_setprio 0
	s_barrier
; #define PG8_STAGE(bufoff, gbase, voff) do { _Pragma("unroll") for (int _i = 0; _i < 2; ++_i) \
;         __builtin_amdgcn_global_load_lds((const unsigned*)((const char*)(gbase) + (voff)[_i]), (PG8_LAS unsigned*)(lds + (bufoff) + ldsw + _i * 8192), 16, 0, 0); } while (0)
; #define PG8_LDA(dst, b, h) do { _Pragma("unroll") for (int m = 0; m < 4; ++m) _Pragma("unroll") for (int k = 0; k < 2; ++k) dst[m][k] = *(const PG8_LAS bf16x8*)(lds + PG8_SA(b, h) + aoff + m * 2048 + k * 1024); } while (0)
; #define PG8_MMA(ai, bj, At, Bt) do { __builtin_amdgcn_s_setprio(1); _Pragma("unroll") for (int m = 0; m < 4; ++m) _Pragma("unroll") for (int n = 0; n < 2; ++n) _Pragma("unroll") for (int k = 0; k < 2; ++k) \
;         acc[ai][bj][m][n] = __builtin_amdgcn_mfma_f32_16x16x32_bf16(Bt[n][k], At[m][k], acc[ai][bj][m][n], 0, 0, 0); __builtin_amdgcn_s_setprio(0); } while (0)
; #define PG8_WAIT_V(n) asm volatile("s_waitcnt vmcnt(" #n ")" ::: "memory")
; #define PG8_WAIT_L(n) asm volatile("s_waitcnt lgkmcnt(" #n ")" ::: "memory")
; #define PG8_BAR __builtin_amdgcn_s_barrier()
; #define PG8_SCHED __builtin_amdgcn_sched_barrier(0)
; template <class Epi, class Sched, bool ALIGN_EPI = false, bool SP2 = false>
; __device__ __forceinline__ void gemm_phase(PG8_LAS unsigned char* lds, const Gemm g, const Sched& S, const Epi& E) {
;     ...
;             PG8_LDA(At, 1, 1); PG8_STAGE(PG8_SB(1, 0), b3, voffB); PG8_STAGE(PG8_SB(1, 1), b3 + hstep, voffB); PG8_STAGE(PG8_SA(1, 0), a3, voffA);
;             PG8_WAIT_V(8); PG8_WAIT_L(0); PG8_BAR; PG8_MMA(1, 0, At, B0); PG8_MMA(1, 1, At, B1); PG8_BAR; PG8_SCHED;
;     ...
;         }
;         if constexpr (ALIGN_EPI) { if (wr == 0) PG8_BAR; }
	s_add_i32 s26, s48, s2
	v_lshl_add_u64 v[212:213], v[212:213], 0, s[10:11]
	s_mov_b32 m0, s26
	ds_read_b128 v[196:199], v144 offset:49152
	ds_read_b128 v[200:203], v144 offset:50176
	ds_read_b128 v[204:207], v144 offset:51200
	ds_read_b128 v[208:211], v144 offset:52224
	ds_read_b128 v[232:235], v144 offset:53248
	ds_read_b128 v[236:239], v144 offset:54272
	ds_read_b128 v[240:243], v144 offset:55296
	ds_read_b128 v[244:247], v144 offset:56320
	global_load_lds_dwordx4 v[212:213], off
	s_add_i32 m0, s26, 0x2000
	s_add_u32 s24, s24, 0x80080
	v_lshl_add_u64 v[212:213], v[248:249], 0, s[10:11]
	s_addc_u32 s25, s25, 0
	s_add_i32 s26, s50, s2
	global_load_lds_dwordx4 v[212:213], off
	v_lshl_add_u64 v[212:213], s[24:25], 0, v[168:169]
	s_mov_b32 m0, s26
	s_nop 0
	global_load_lds_dwordx4 v[212:213], off
	v_lshl_add_u64 v[212:213], s[24:25], 0, v[172:173]
	s_add_i32 m0, s26, 0x2000
	s_nop 0
	global_load_lds_dwordx4 v[212:213], off
	v_lshl_add_u64 v[212:213], v[250:251], 0, s[10:11]
	s_mov_b32 m0, s34
	s_nop 0
	global_load_lds_dwordx4 v[212:213], off
	v_lshl_add_u64 v[212:213], v[252:253], 0, s[10:11]
	s_mov_b32 m0, s35
	s_nop 0
	global_load_lds_dwordx4 v[212:213], off
	s_waitcnt vmcnt(8)
	s_waitcnt lgkmcnt(0)
	s_barrier
	s_setprio 1
	s_waitcnt lgkmcnt(0)
	v_mfma_f32_16x16x32_bf16 v[62:65], v[146:149], v[196:199], v[62:65]
	v_mfma_f32_16x16x32_bf16 v[58:61], v[154:157], v[196:199], v[58:61]
	v_mfma_f32_16x16x32_bf16 v[54:57], v[146:149], v[204:207], v[54:57]
	v_mfma_f32_16x16x32_bf16 v[50:53], v[154:157], v[204:207], v[50:53]
	v_mfma_f32_16x16x32_bf16 v[38:41], v[146:149], v[232:235], v[38:41]
	v_mfma_f32_16x16x32_bf16 v[34:37], v[154:157], v[232:235], v[34:37]
	v_mfma_f32_16x16x32_bf16 v[22:25], v[146:149], v[240:243], v[22:25]
	v_mfma_f32_16x16x32_bf16 v[18:21], v[154:157], v[240:243], v[18:21]
	v_mfma_f32_16x16x32_bf16 v[62:65], v[150:153], v[200:203], v[62:65]
	v_mfma_f32_16x16x32_bf16 v[58:61], v[158:161], v[200:203], v[58:61]
	v_mfma_f32_16x16x32_bf16 v[54:57], v[150:153], v[208:211], v[54:57]
	v_mfma_f32_16x16x32_bf16 v[50:53], v[158:161], v[208:211], v[50:53]
	v_mfma_f32_16x16x32_bf16 v[38:41], v[150:153], v[236:239], v[38:41]
	v_mfma_f32_16x16x32_bf16 v[34:37], v[158:161], v[236:239], v[34:37]
	v_mfma_f32_16x16x32_bf16 v[22:25], v[150:153], v[244:247], v[22:25]
	v_mfma_f32_16x16x32_bf16 v[18:21], v[158:161], v[244:247], v[18:21]
	v_mfma_f32_16x16x32_bf16 v[46:49], v[180:183], v[196:199], v[46:49]
	v_mfma_f32_16x16x32_bf16 v[42:45], v[188:191], v[196:199], v[42:45]
	v_mfma_f32_16x16x32_bf16 v[30:33], v[180:183], v[204:207], v[30:33]
	v_mfma_f32_16x16x32_bf16 v[26:29], v[188:191], v[204:207], v[26:29]
	v_mfma_f32_16x16x32_bf16 v[14:17], v[180:183], v[232:235], v[14:17]
	v_mfma_f32_16x16x32_bf16 v[10:13], v[188:191], v[232:235], v[10:13]
	v_mfma_f32_16x16x32_bf16 v[6:9], v[180:183], v[240:243], v[6:9]
	v_mfma_f32_16x16x32_bf16 v[2:5], v[188:191], v[240:243], v[2:5]
	v_mfma_f32_16x16x32_bf16 v[46:49], v[184:187], v[200:203], v[46:49]
	v_mfma_f32_16x16x32_bf16 v[42:45], v[192:195], v[200:203], v[42:45]
	v_mfma_f32_16x16x32_bf16 v[30:33], v[184:187], v[208:211], v[30:33]
	v_mfma_f32_16x16x32_bf16 v[26:29], v[192:195], v[208:211], v[26:29]
	v_mfma_f32_16x16x32_bf16 v[14:17], v[184:187], v[236:239], v[14:17]
	v_mfma_f32_16x16x32_bf16 v[10:13], v[192:195], v[236:239], v[10:13]
	v_mfma_f32_16x16x32_bf16 v[6:9], v[184:187], v[244:247], v[6:9]
	v_mfma_f32_16x16x32_bf16 v[2:5], v[192:195], v[244:247], v[2:5]
	s_setprio 0
	s_barrier
	s_add_u32 s4, s4, 0x100
	s_addc_u32 s5, s5, 0
	s_add_u32 s46, s46, 0x100
	s_addc_u32 s47, s47, 0
	s_cmp_ge_u32 s49, s41
	s_mov_b32 s48, s49
	s_cbranch_scc0 .LBB0_423
	s_and_b64 vcc, exec, s[12:13]
	s_cbranch_vccz .LBB0_426
	s_barrier

; #define PG8_STAGE(bufoff, gbase, voff) do { _Pragma("unroll") for (int _i = 0; _i < 2; ++_i) \
;         __builtin_amdgcn_global_load_lds((const unsigned*)((const char*)(gbase) + (voff)[_i]), (PG8_LAS unsigned*)(lds + (bufoff) + ldsw + _i * 8192), 16, 0, 0); } while (0)
; #define PG8_LDA(dst, b, h) do { _Pragma("unroll") for (int m = 0; m < 4; ++m) _Pragma("unroll") for (int k = 0; k < 2; ++k) dst[m][k] = *(const PG8_LAS bf16x8*)(lds + PG8_SA(b, h) + aoff + m * 2048 + k * 1024); } while (0)
; #define PG8_LDB(dst, b, h) do { _Pragma("unroll") for (int n = 0; n < 2; ++n) _Pragma("unroll") for (int k = 0; k < 2; ++k) dst[n][k] = *(const PG8_LAS bf16x8*)(lds + PG8_SB(b, h) + boff + n * 2048 + k * 1024); } while (0)
; #define PG8_MMA(ai, bj, At, Bt) do { __builtin_amdgcn_s_setprio(1); _Pragma("unroll") for (int m = 0; m < 4; ++m) _Pragma("unroll") for (int n = 0; n < 2; ++n) _Pragma("unroll") for (int k = 0; k < 2; ++k) \
;         acc[ai][bj][m][n] = __builtin_amdgcn_mfma_f32_16x16x32_bf16(Bt[n][k], At[m][k], acc[ai][bj][m][n], 0, 0, 0); __builtin_amdgcn_s_setprio(0); } while (0)
; #define PG8_WAIT_V(n) asm volatile("s_waitcnt vmcnt(" #n ")" ::: "memory")
; #define PG8_WAIT_L(n) asm volatile("s_waitcnt lgkmcnt(" #n ")" ::: "memory")
; #define PG8_BAR __builtin_amdgcn_s_barrier()
; #define PG8_SCHED __builtin_amdgcn_sched_barrier(0)
; template <class Epi, class Sched, bool ALIGN_EPI = false, bool SP2 = false>
; __device__ __forceinline__ void gemm_phase(PG8_LAS unsigned char* lds, const Gemm g, const Sched& S, const Epi& E) {
;     ...
;         for (int t = 0; t < nt; t += 2) {
;             const bool last = (t == nt - 2);
;             const char* a1 = cA + (size_t)(t + 1) * kstep;
;             const char* a2 = last ? nA : cA + (size_t)(t + 2) * kstep; const char* b2 = last ? nB : cB + (size_t)(t + 2) * kstep;
;             const char* a3 = a2 + kstep; const char* b3 = b2 + kstep;
;             if (last && has_next) S.a_ready(nxt);
;             if constexpr (SP2) {
;             PG8_LDB(B0, 0, 0); PG8_LDB(B1, 0, 1); PG8_SCHED; PG8_LDA(At, 0, 0); PG8_STAGE(PG8_SA(1, 1), a1 + hstep, voffA);
;             PG8_WAIT_V(8); PG8_WAIT_L(0); PG8_BAR; PG8_MMA(0, 0, At, B0); PG8_MMA(0, 1, At, B1); PG8_BAR; PG8_SCHED;
;             PG8_LDA(At, 0, 1); PG8_STAGE(PG8_SB(0, 0), b2, voffB); PG8_STAGE(PG8_SB(0, 1), b2 + hstep, voffB); PG8_STAGE(PG8_SA(0, 0), a2, voffA);
.LBB0_892:
	ds_read_b128 v[136:139], v143
	ds_read_b128 v[146:149], v143 offset:1024
	ds_read_b128 v[150:153], v143 offset:2048
	ds_read_b128 v[154:157], v143 offset:3072
	ds_read_b128 v[158:161], v144
	ds_read_b128 v[180:183], v144 offset:1024
	ds_read_b128 v[184:187], v144 offset:2048
	ds_read_b128 v[188:191], v144 offset:3072
	s_add_i32 s53, s28, 2
	s_add_u32 s29, s26, 0xfff80080
	s_addc_u32 s30, s27, -1
	s_cmp_eq_u32 s49, s28
	s_cselect_b32 s28, s48, s51
	s_cselect_b32 s31, s13, s30
	s_cselect_b32 s30, s19, s29
	s_cselect_b32 s29, s17, s52
	v_lshl_add_u64 v[212:213], s[26:27], 0, v[130:131]
	s_add_i32 m0, s3, 0xc000
	ds_read_b128 v[192:195], v145
	ds_read_b128 v[196:199], v145 offset:1024
	ds_read_b128 v[200:203], v145 offset:2048
	ds_read_b128 v[204:207], v145 offset:3072
	ds_read_b128 v[208:211], v145 offset:4096
	ds_read_b128 v[232:235], v145 offset:5120
	ds_read_b128 v[236:239], v145 offset:6144
	ds_read_b128 v[240:243], v145 offset:7168
	global_load_lds_dwordx4 v[212:213], off
	v_lshl_add_u64 v[212:213], s[26:27], 0, v[132:133]
	s_add_i32 m0, s3, 0xe000
	s_nop 0
	global_load_lds_dwordx4 v[212:213], off
	s_waitcnt vmcnt(8)
	s_waitcnt lgkmcnt(0)
	s_barrier
	s_setprio 1
	s_waitcnt lgkmcnt(0)
	v_mfma_f32_16x16x32_bf16 v[126:129], v[136:139], v[192:195], v[126:129]
	v_mfma_f32_16x16x32_bf16 v[122:125], v[150:153], v[192:195], v[122:125]
	v_mfma_f32_16x16x32_bf16 v[118:121], v[136:139], v[200:203], v[118:121]
	v_mfma_f32_16x16x32_bf16 v[114:117], v[150:153], v[200:203], v[114:117]
	v_mfma_f32_16x16x32_bf16 v[102:105], v[136:139], v[208:211], v[102:105]
	v_mfma_f32_16x16x32_bf16 v[98:101], v[150:153], v[208:211], v[98:101]
	v_mfma_f32_16x16x32_bf16 v[86:89], v[136:139], v[236:239], v[86:89]
	v_mfma_f32_16x16x32_bf16 v[82:85], v[150:153], v[236:239], v[82:85]
	v_mfma_f32_16x16x32_bf16 v[126:129], v[146:149], v[196:199], v[126:129]
	v_mfma_f32_16x16x32_bf16 v[122:125], v[154:157], v[196:199], v[122:125]
	v_mfma_f32_16x16x32_bf16 v[118:121], v[146:149], v[204:207], v[118:121]
	v_mfma_f32_16x16x32_bf16 v[114:117], v[154:157], v[204:207], v[114:117]
	v_mfma_f32_16x16x32_bf16 v[102:105], v[146:149], v[232:235], v[102:105]
	v_mfma_f32_16x16x32_bf16 v[98:101], v[154:157], v[232:235], v[98:101]
	v_mfma_f32_16x16x32_bf16 v[86:89], v[146:149], v[240:243], v[86:89]
	v_mfma_f32_16x16x32_bf16 v[82:85], v[154:157], v[240:243], v[82:85]
	v_mfma_f32_16x16x32_bf16 v[110:113], v[158:161], v[192:195], v[110:113]
	v_mfma_f32_16x16x32_bf16 v[106:109], v[184:187], v[192:195], v[106:109]
	v_mfma_f32_16x16x32_bf16 v[94:97], v[158:161], v[200:203], v[94:97]
	v_mfma_f32_16x16x32_bf16 v[90:93], v[184:187], v[200:203], v[90:93]
	v_mfma_f32_16x16x32_bf16 v[78:81], v[158:161], v[208:211], v[78:81]
	v_mfma_f32_16x16x32_bf16 v[74:77], v[184:187], v[208:211], v[74:77]
	v_mfma_f32_16x16x32_bf16 v[70:73], v[158:161], v[236:239], v[70:73]
	v_mfma_f32_16x16x32_bf16 v[66:69], v[184:187], v[236:239], v[66:69]
	v_mfma_f32_16x16x32_bf16 v[110:113], v[180:183], v[196:199], v[110:113]
	v_mfma_f32_16x16x32_bf16 v[106:109], v[188:191], v[196:199], v[106:109]
	v_mfma_f32_16x16x32_bf16 v[94:97], v[180:183], v[204:207], v[94:97]
	v_mfma_f32_16x16x32_bf16 v[90:93], v[188:191], v[204:207], v[90:93]
	v_mfma_f32_16x16x32_bf16 v[78:81], v[180:183], v[232:235], v[78:81]
	v_mfma_f32_16x16x32_bf16 v[74:77], v[188:191], v[232:235], v[74:77]
	v_mfma_f32_16x16x32_bf16 v[70:73], v[180:183], v[240:243], v[70:73]
	v_mfma_f32_16x16x32_bf16 v[66:69], v[188:191], v[240:243], v[66:69]
	s_setprio 0
	s_barrier
	s_add_i32 s54, s42, s2
	v_lshl_add_u64 v[212:213], s[28:29], 0, v[166:167]
	s_mov_b32 m0, s54
	ds_read_b128 v[192:195], v145 offset:16384
	ds_read_b128 v[196:199], v145 offset:17408
	ds_read_b128 v[200:203], v145 offset:18432
	ds_read_b128 v[204:207], v145 offset:19456
	ds_read_b128 v[208:211], v145 offset:20480
	ds_read_b128 v[232:235], v145 offset:21504
	ds_read_b128 v[236:239], v145 offset:22528
	ds_read_b128 v[240:243], v145 offset:23552
	global_load_lds_dwordx4 v[212:213], off
	s_add_i32 m0, s54, 0x2000
	s_add_u32 s54, s28, 0x80000
	v_lshl_add_u64 v[222:223], s[28:29], 0, v[170:171]
	s_addc_u32 s55, s29, 0
	s_add_i32 s56, s43, s2
	global_load_lds_dwordx4 v[222:223], off
	v_lshl_add_u64 v[244:245], s[54:55], 0, v[166:167]
	s_mov_b32 m0, s56
	v_lshl_add_u64 v[246:247], s[30:31], 0, v[170:171]
	global_load_lds_dwordx4 v[244:245], off
	v_lshl_add_u64 v[244:245], s[54:55], 0, v[170:171]
	s_add_i32 m0, s56, 0x2000
	s_nop 0
	global_load_lds_dwordx4 v[244:245], off
	v_lshl_add_u64 v[244:245], s[30:31], 0, v[166:167]
	s_mov_b32 m0, s3
	s_nop 0
	global_load_lds_dwordx4 v[244:245], off
	s_mov_b32 m0, s15
	s_nop 0
	global_load_lds_dwordx4 v[246:247], off
	s_waitcnt vmcnt(8)
	s_waitcnt lgkmcnt(0)
	s_barrier
; #define PG8_STAGE(bufoff, gbase, voff) do { _Pragma("unroll") for (int _i = 0; _i < 2; ++_i) \
;         __builtin_amdgcn_global_load_lds((const unsigned*)((const char*)(gbase) + (voff)[_i]), (PG8_LAS unsigned*)(lds + (bufoff) + ldsw + _i * 8192), 16, 0, 0); } while (0)
; #define PG8_LDA(dst, b, h) do { _Pragma("unroll") for (int m = 0; m < 4; ++m) _Pragma("unroll") for (int k = 0; k < 2; ++k) dst[m][k] = *(const PG8_LAS bf16x8*)(lds + PG8_SA(b, h) + aoff + m * 2048 + k * 1024); } while (0)
; #define PG8_LDB(dst, b, h) do { _Pragma("unroll") for (int n = 0; n < 2; ++n) _Pragma("unroll") for (int k = 0; k < 2; ++k) dst[n][k] = *(const PG8_LAS bf16x8*)(lds + PG8_SB(b, h) + boff + n * 2048 + k * 1024); } while (0)
; #define PG8_MMA(ai, bj, At, Bt) do { __builtin_amdgcn_s_setprio(1); _Pragma("unroll") for (int m = 0; m < 4; ++m) _Pragma("unroll") for (int n = 0; n < 2; ++n) _Pragma("unroll") for (int k = 0; k < 2; ++k) \
;         acc[ai][bj][m][n] = __builtin_amdgcn_mfma_f32_16x16x32_bf16(Bt[n][k], At[m][k], acc[ai][bj][m][n], 0, 0, 0); __builtin_amdgcn_s_setprio(0); } while (0)
; #define PG8_WAIT_V(n) asm volatile("s_waitcnt vmcnt(" #n ")" ::: "memory")
; #define PG8_WAIT_L(n) asm volatile("s_waitcnt lgkmcnt(" #n ")" ::: "memory")
; #define PG8_BAR __builtin_amdgcn_s_barrier()
; #define PG8_SCHED __builtin_amdgcn_sched_barrier(0)
; template <class Epi, class Sched, bool ALIGN_EPI = false, bool SP2 = false>
; __device__ __forceinline__ void gemm_phase(PG8_LAS unsigned char* lds, const Gemm g, const Sched& S, const Epi& E) {
;     ...
;             PG8_WAIT_V(8); PG8_WAIT_L(0); PG8_BAR; PG8_MMA(1, 0, At, B0); PG8_MMA(1, 1, At, B1); PG8_BAR; PG8_SCHED;
;             PG8_LDB(B0, 1, 0); PG8_LDB(B1, 1, 1); PG8_SCHED; PG8_LDA(At, 1, 0); PG8_STAGE(PG8_SA(0, 1), a2 + hstep, voffA);
;             PG8_WAIT_V(8); PG8_WAIT_L(0); PG8_BAR; PG8_MMA(0, 0, At, B0); PG8_MMA(0, 1, At, B1); PG8_BAR; PG8_SCHED;
	s_setprio 1
	s_waitcnt lgkmcnt(0)
	v_mfma_f32_16x16x32_bf16 v[62:65], v[136:139], v[192:195], v[62:65]
	v_mfma_f32_16x16x32_bf16 v[58:61], v[150:153], v[192:195], v[58:61]
	v_mfma_f32_16x16x32_bf16 v[54:57], v[136:139], v[200:203], v[54:57]
	v_mfma_f32_16x16x32_bf16 v[50:53], v[150:153], v[200:203], v[50:53]
	v_mfma_f32_16x16x32_bf16 v[38:41], v[136:139], v[208:211], v[38:41]
	v_mfma_f32_16x16x32_bf16 v[34:37], v[150:153], v[208:211], v[34:37]
	v_mfma_f32_16x16x32_bf16 v[22:25], v[136:139], v[236:239], v[22:25]
	v_mfma_f32_16x16x32_bf16 v[18:21], v[150:153], v[236:239], v[18:21]
	v_mfma_f32_16x16x32_bf16 v[62:65], v[146:149], v[196:199], v[62:65]
	v_mfma_f32_16x16x32_bf16 v[58:61], v[154:157], v[196:199], v[58:61]
	v_mfma_f32_16x16x32_bf16 v[54:57], v[146:149], v[204:207], v[54:57]
	v_mfma_f32_16x16x32_bf16 v[50:53], v[154:157], v[204:207], v[50:53]
	v_mfma_f32_16x16x32_bf16 v[38:41], v[146:149], v[232:235], v[38:41]
	v_mfma_f32_16x16x32_bf16 v[34:37], v[154:157], v[232:235], v[34:37]
	v_mfma_f32_16x16x32_bf16 v[22:25], v[146:149], v[240:243], v[22:25]
	v_mfma_f32_16x16x32_bf16 v[18:21], v[154:157], v[240:243], v[18:21]
	v_mfma_f32_16x16x32_bf16 v[46:49], v[158:161], v[192:195], v[46:49]
	v_mfma_f32_16x16x32_bf16 v[42:45], v[184:187], v[192:195], v[42:45]
	v_mfma_f32_16x16x32_bf16 v[30:33], v[158:161], v[200:203], v[30:33]
	v_mfma_f32_16x16x32_bf16 v[26:29], v[184:187], v[200:203], v[26:29]
	v_mfma_f32_16x16x32_bf16 v[14:17], v[158:161], v[208:211], v[14:17]
	v_mfma_f32_16x16x32_bf16 v[10:13], v[184:187], v[208:211], v[10:13]
	v_mfma_f32_16x16x32_bf16 v[6:9], v[158:161], v[236:239], v[6:9]
	v_mfma_f32_16x16x32_bf16 v[2:5], v[184:187], v[236:239], v[2:5]
	v_mfma_f32_16x16x32_bf16 v[46:49], v[180:183], v[196:199], v[46:49]
	v_mfma_f32_16x16x32_bf16 v[42:45], v[188:191], v[196:199], v[42:45]
	v_mfma_f32_16x16x32_bf16 v[30:33], v[180:183], v[204:207], v[30:33]
	v_mfma_f32_16x16x32_bf16 v[26:29], v[188:191], v[204:207], v[26:29]
	v_mfma_f32_16x16x32_bf16 v[14:17], v[180:183], v[232:235], v[14:17]
	v_mfma_f32_16x16x32_bf16 v[10:13], v[188:191], v[232:235], v[10:13]
	v_mfma_f32_16x16x32_bf16 v[6:9], v[180:183], v[240:243], v[6:9]
	v_mfma_f32_16x16x32_bf16 v[2:5], v[188:191], v[240:243], v[2:5]
	s_setprio 0
	s_barrier
	s_add_i32 s54, 0, 0x18000
	s_add_i32 s55, 0, 0x1c000
	v_add_u32_e32 v154, s54, v141
	v_add_u32_e32 v169, s55, v141
	ds_read_b128 v[136:139], v154
	ds_read_b128 v[146:149], v154 offset:1024
	ds_read_b128 v[150:153], v154 offset:2048
	ds_read_b128 v[154:157], v154 offset:3072
	ds_read_b128 v[158:161], v169
	ds_read_b128 v[180:183], v169 offset:1024
	ds_read_b128 v[184:187], v169 offset:2048
	ds_read_b128 v[188:191], v169 offset:3072
	s_add_u32 s30, s30, 0x80000
	s_addc_u32 s31, s31, 0
	s_mov_b32 m0, s33
	v_lshl_add_u64 v[248:249], s[30:31], 0, v[166:167]
	ds_read_b128 v[192:195], v145 offset:32768
	ds_read_b128 v[196:199], v145 offset:33792
	ds_read_b128 v[200:203], v145 offset:34816
	ds_read_b128 v[204:207], v145 offset:35840
	ds_read_b128 v[208:211], v145 offset:36864
	ds_read_b128 v[232:235], v145 offset:37888
	ds_read_b128 v[236:239], v145 offset:38912
	ds_read_b128 v[240:243], v145 offset:39936
	global_load_lds_dwordx4 v[248:249], off
	v_lshl_add_u64 v[248:249], s[30:31], 0, v[170:171]
	s_mov_b32 m0, s34
	s_nop 0
	global_load_lds_dwordx4 v[248:249], off
	s_waitcnt vmcnt(8)
	s_waitcnt lgkmcnt(0)
	s_barrier
	s_setprio 1
	s_waitcnt lgkmcnt(0)
	v_mfma_f32_16x16x32_bf16 v[126:129], v[136:139], v[192:195], v[126:129]
	v_mfma_f32_16x16x32_bf16 v[122:125], v[150:153], v[192:195], v[122:125]
	v_mfma_f32_16x16x32_bf16 v[118:121], v[136:139], v[200:203], v[118:121]
	v_mfma_f32_16x16x32_bf16 v[114:117], v[150:153], v[200:203], v[114:117]
	v_mfma_f32_16x16x32_bf16 v[102:105], v[136:139], v[208:211], v[102:105]
	v_mfma_f32_16x16x32_bf16 v[98:101], v[150:153], v[208:211], v[98:101]
	v_mfma_f32_16x16x32_bf16 v[86:89], v[136:139], v[236:239], v[86:89]
	v_mfma_f32_16x16x32_bf16 v[82:85], v[150:153], v[236:239], v[82:85]
	v_mfma_f32_16x16x32_bf16 v[126:129], v[146:149], v[196:199], v[126:129]
	v_mfma_f32_16x16x32_bf16 v[122:125], v[154:157], v[196:199], v[122:125]
	v_mfma_f32_16x16x32_bf16 v[118:121], v[146:149], v[204:207], v[118:121]
	v_mfma_f32_16x16x32_bf16 v[114:117], v[154:157], v[204:207], v[114:117]
	v_mfma_f32_16x16x32_bf16 v[102:105], v[146:149], v[232:235], v[102:105]
	v_mfma_f32_16x16x32_bf16 v[98:101], v[154:157], v[232:235], v[98:101]
	v_mfma_f32_16x16x32_bf16 v[86:89], v[146:149], v[240:243], v[86:89]
	v_mfma_f32_16x16x32_bf16 v[82:85], v[154:157], v[240:243], v[82:85]
	v_mfma_f32_16x16x32_bf16 v[110:113], v[158:161], v[192:195], v[110:113]
	v_mfma_f32_16x16x32_bf16 v[106:109], v[184:187], v[192:195], v[106:109]
	v_mfma_f32_16x16x32_bf16 v[94:97], v[158:161], v[200:203], v[94:97]
	v_mfma_f32_16x16x32_bf16 v[90:93], v[184:187], v[200:203], v[90:93]
	v_mfma_f32_16x16x32_bf16 v[78:81], v[158:161], v[208:211], v[78:81]
	v_mfma_f32_16x16x32_bf16 v[74:77], v[184:187], v[208:211], v[74:77]
	v_mfma_f32_16x16x32_bf16 v[70:73], v[158:161], v[236:239], v[70:73]
	v_mfma_f32_16x16x32_bf16 v[66:69], v[184:187], v[236:239], v[66:69]
	v_mfma_f32_16x16x32_bf16 v[110:113], v[180:183], v[196:199], v[110:113]
	v_mfma_f32_16x16x32_bf16 v[106:109], v[188:191], v[196:199], v[106:109]
	v_mfma_f32_16x16x32_bf16 v[94:97], v[180:183], v[204:207], v[94:97]
	v_mfma_f32_16x16x32_bf16 v[90:93], v[188:191], v[204:207], v[90:93]
	v_mfma_f32_16x16x32_bf16 v[78:81], v[180:183], v[232:235], v[78:81]
	v_mfma_f32_16x16x32_bf16 v[74:77], v[188:191], v[232:235], v[74:77]
	v_mfma_f32_16x16x32_bf16 v[70:73], v[180:183], v[240:243], v[70:73]
	v_mfma_f32_16x16x32_bf16 v[66:69], v[188:191], v[240:243], v[66:69]
	s_setprio 0
	s_barrier
; #define PG8_STAGE(bufoff, gbase, voff) do { _Pragma("unroll") for (int _i = 0; _i < 2; ++_i) \
;         __builtin_amdgcn_global_load_lds((const unsigned*)((const char*)(gbase) + (voff)[_i]), (PG8_LAS unsigned*)(lds + (bufoff) + ldsw + _i * 8192), 16, 0, 0); } while (0)
; #define PG8_LDA(dst, b, h) do { _Pragma("unroll") for (int m = 0; m < 4; ++m) _Pragma("unroll") for (int k = 0; k < 2; ++k) dst[m][k] = *(const PG8_LAS bf16x8*)(lds + PG8_SA(b, h) + aoff + m * 2048 + k * 1024); } while (0)
; #define PG8_MMA(ai, bj, At, Bt) do { __builtin_amdgcn_s_setprio(1); _Pragma("unroll") for (int m = 0; m < 4; ++m) _Pragma("unroll") for (int n = 0; n < 2; ++n) _Pragma("unroll") for (int k = 0; k < 2; ++k) \
;         acc[ai][bj][m][n] = __builtin_amdgcn_mfma_f32_16x16x32_bf16(Bt[n][k], At[m][k], acc[ai][bj][m][n], 0, 0, 0); __builtin_amdgcn_s_setprio(0); } while (0)
; #define PG8_WAIT_V(n) asm volatile("s_waitcnt vmcnt(" #n ")" ::: "memory")
; #define PG8_WAIT_L(n) asm volatile("s_waitcnt lgkmcnt(" #n ")" ::: "memory")
; #define PG8_BAR __builtin_amdgcn_s_barrier()
; #define PG8_SCHED __builtin_amdgcn_sched_barrier(0)
; template <class Epi, class Sched, bool ALIGN_EPI = false, bool SP2 = false>
; __device__ __forceinline__ void gemm_phase(PG8_LAS unsigned char* lds, const Gemm g, const Sched& S, const Epi& E) {
;     ...
;             PG8_LDA(At, 1, 1); PG8_STAGE(PG8_SB(1, 0), b3, voffB); PG8_STAGE(PG8_SB(1, 1), b3 + hstep, voffB); PG8_STAGE(PG8_SA(1, 0), a3, voffA);
;             PG8_WAIT_V(8); PG8_WAIT_L(0); PG8_BAR; PG8_MMA(1, 0, At, B0); PG8_MMA(1, 1, At, B1); PG8_BAR; PG8_SCHED;
;     ...
;         }
;         if constexpr (ALIGN_EPI) { if (wr == 0) PG8_BAR; }
	s_add_i32 s30, s54, s2
	v_lshl_add_u64 v[212:213], v[212:213], 0, s[6:7]
	s_mov_b32 m0, s30
	ds_read_b128 v[192:195], v145 offset:49152
	ds_read_b128 v[196:199], v145 offset:50176
	ds_read_b128 v[200:203], v145 offset:51200
	ds_read_b128 v[204:207], v145 offset:52224
	ds_read_b128 v[208:211], v145 offset:53248
	ds_read_b128 v[232:235], v145 offset:54272
	ds_read_b128 v[236:239], v145 offset:55296
	ds_read_b128 v[240:243], v145 offset:56320
	global_load_lds_dwordx4 v[212:213], off
	s_add_i32 m0, s30, 0x2000
	s_add_u32 s28, s28, 0x80080
	v_lshl_add_u64 v[212:213], v[222:223], 0, s[6:7]
	s_addc_u32 s29, s29, 0
	s_add_i32 s30, s55, s2
	global_load_lds_dwordx4 v[212:213], off
	v_lshl_add_u64 v[212:213], s[28:29], 0, v[166:167]
	s_mov_b32 m0, s30
	s_nop 0
	global_load_lds_dwordx4 v[212:213], off
	v_lshl_add_u64 v[212:213], s[28:29], 0, v[170:171]
	s_add_i32 m0, s30, 0x2000
	s_nop 0
	global_load_lds_dwordx4 v[212:213], off
	v_lshl_add_u64 v[212:213], v[244:245], 0, s[6:7]
	s_mov_b32 m0, s35
	s_nop 0
	global_load_lds_dwordx4 v[212:213], off
	v_lshl_add_u64 v[212:213], v[246:247], 0, s[6:7]
	s_mov_b32 m0, s36
	s_nop 0
	global_load_lds_dwordx4 v[212:213], off
	s_waitcnt vmcnt(8)
	s_waitcnt lgkmcnt(0)
	s_barrier
	s_setprio 1
	s_waitcnt lgkmcnt(0)
	v_mfma_f32_16x16x32_bf16 v[62:65], v[136:139], v[192:195], v[62:65]
	v_mfma_f32_16x16x32_bf16 v[58:61], v[150:153], v[192:195], v[58:61]
	v_mfma_f32_16x16x32_bf16 v[54:57], v[136:139], v[200:203], v[54:57]
	v_mfma_f32_16x16x32_bf16 v[50:53], v[150:153], v[200:203], v[50:53]
	v_mfma_f32_16x16x32_bf16 v[38:41], v[136:139], v[208:211], v[38:41]
	v_mfma_f32_16x16x32_bf16 v[34:37], v[150:153], v[208:211], v[34:37]
	v_mfma_f32_16x16x32_bf16 v[22:25], v[136:139], v[236:239], v[22:25]
	v_mfma_f32_16x16x32_bf16 v[18:21], v[150:153], v[236:239], v[18:21]
	v_mfma_f32_16x16x32_bf16 v[62:65], v[146:149], v[196:199], v[62:65]
	v_mfma_f32_16x16x32_bf16 v[58:61], v[154:157], v[196:199], v[58:61]
	v_mfma_f32_16x16x32_bf16 v[54:57], v[146:149], v[204:207], v[54:57]
	v_mfma_f32_16x16x32_bf16 v[50:53], v[154:157], v[204:207], v[50:53]
	v_mfma_f32_16x16x32_bf16 v[38:41], v[146:149], v[232:235], v[38:41]
	v_mfma_f32_16x16x32_bf16 v[34:37], v[154:157], v[232:235], v[34:37]
	v_mfma_f32_16x16x32_bf16 v[22:25], v[146:149], v[240:243], v[22:25]
	v_mfma_f32_16x16x32_bf16 v[18:21], v[154:157], v[240:243], v[18:21]
	v_mfma_f32_16x16x32_bf16 v[46:49], v[158:161], v[192:195], v[46:49]
	v_mfma_f32_16x16x32_bf16 v[42:45], v[184:187], v[192:195], v[42:45]
	v_mfma_f32_16x16x32_bf16 v[30:33], v[158:161], v[200:203], v[30:33]
	v_mfma_f32_16x16x32_bf16 v[26:29], v[184:187], v[200:203], v[26:29]
	v_mfma_f32_16x16x32_bf16 v[14:17], v[158:161], v[208:211], v[14:17]
	v_mfma_f32_16x16x32_bf16 v[10:13], v[184:187], v[208:211], v[10:13]
	v_mfma_f32_16x16x32_bf16 v[6:9], v[158:161], v[236:239], v[6:9]
	v_mfma_f32_16x16x32_bf16 v[2:5], v[184:187], v[236:239], v[2:5]
	v_mfma_f32_16x16x32_bf16 v[46:49], v[180:183], v[196:199], v[46:49]
	v_mfma_f32_16x16x32_bf16 v[42:45], v[188:191], v[196:199], v[42:45]
	v_mfma_f32_16x16x32_bf16 v[30:33], v[180:183], v[204:207], v[30:33]
	v_mfma_f32_16x16x32_bf16 v[26:29], v[188:191], v[204:207], v[26:29]
	v_mfma_f32_16x16x32_bf16 v[14:17], v[180:183], v[232:235], v[14:17]
	v_mfma_f32_16x16x32_bf16 v[10:13], v[188:191], v[232:235], v[10:13]
	v_mfma_f32_16x16x32_bf16 v[6:9], v[180:183], v[240:243], v[6:9]
	v_mfma_f32_16x16x32_bf16 v[2:5], v[188:191], v[240:243], v[2:5]
	s_setprio 0
	s_barrier
	s_add_u32 s26, s26, 0x100
	s_addc_u32 s27, s27, 0
	s_add_u32 s51, s51, 0x100
	s_addc_u32 s52, s52, 0
	s_cmp_ge_u32 s53, s45
	s_mov_b32 s28, s53
	s_cbranch_scc0 .LBB0_892
	s_and_b64 vcc, exec, s[8:9]
	s_cbranch_vccz .LBB0_895
	s_barrier

; #define PG8_STAGE(bufoff, gbase, voff) do { _Pragma("unroll") for (int _i = 0; _i < 2; ++_i) \
;         __builtin_amdgcn_global_load_lds((const unsigned*)((const char*)(gbase) + (voff)[_i]), (PG8_LAS unsigned*)(lds + (bufoff) + ldsw + _i * 8192), 16, 0, 0); } while (0)
; #define PG8_LDA(dst, b, h) do { _Pragma("unroll") for (int m = 0; m < 4; ++m) _Pragma("unroll") for (int k = 0; k < 2; ++k) dst[m][k] = *(const PG8_LAS bf16x8*)(lds + PG8_SA(b, h) + aoff + m * 2048 + k * 1024); } while (0)
; #define PG8_LDB(dst, b, h) do { _Pragma("unroll") for (int n = 0; n < 2; ++n) _Pragma("unroll") for (int k = 0; k < 2; ++k) dst[n][k] = *(const PG8_LAS bf16x8*)(lds + PG8_SB(b, h) + boff + n * 2048 + k * 1024); } while (0)
; #define PG8_MMA(ai, bj, At, Bt) do { __builtin_amdgcn_s_setprio(1); _Pragma("unroll") for (int m = 0; m < 4; ++m) _Pragma("unroll") for (int n = 0; n < 2; ++n) _Pragma("unroll") for (int k = 0; k < 2; ++k) \
;         acc[ai][bj][m][n] = __builtin_amdgcn_mfma_f32_16x16x32_bf16(Bt[n][k], At[m][k], acc[ai][bj][m][n], 0, 0, 0); __builtin_amdgcn_s_setprio(0); } while (0)
; #define PG8_WAIT_V(n) asm volatile("s_waitcnt vmcnt(" #n ")" ::: "memory")
; #define PG8_WAIT_L(n) asm volatile("s_waitcnt lgkmcnt(" #n ")" ::: "memory")
; #define PG8_BAR __builtin_amdgcn_s_barrier()
; #define PG8_SCHED __builtin_amdgcn_sched_barrier(0)
; template <class Epi, class Sched, bool ALIGN_EPI = false, bool SP2 = false>
; __device__ __forceinline__ void gemm_phase(PG8_LAS unsigned char* lds, const Gemm g, const Sched& S, const Epi& E) {
;     ...
;         for (int t = 0; t < nt; t += 2) {
;             const bool last = (t == nt - 2);
;             const char* a1 = cA + (size_t)(t + 1) * kstep;
;             const char* a2 = last ? nA : cA + (size_t)(t + 2) * kstep; const char* b2 = last ? nB : cB + (size_t)(t + 2) * kstep;
;             const char* a3 = a2 + kstep; const char* b3 = b2 + kstep;
;             if (last && has_next) S.a_ready(nxt);
;             if constexpr (SP2) {
;             PG8_LDB(B0, 0, 0); PG8_LDB(B1, 0, 1); PG8_SCHED; PG8_LDA(At, 0, 0); PG8_STAGE(PG8_SA(1, 1), a1 + hstep, voffA);
;             PG8_WAIT_V(8); PG8_WAIT_L(0); PG8_BAR; PG8_MMA(0, 0, At, B0); PG8_MMA(0, 1, At, B1); PG8_BAR; PG8_SCHED;
;             PG8_LDA(At, 0, 1); PG8_STAGE(PG8_SB(0, 0), b2, voffB); PG8_STAGE(PG8_SB(0, 1), b2 + hstep, voffB); PG8_STAGE(PG8_SA(0, 0), a2, voffA);
.LBB0_1029:
	ds_read_b128 v[144:147], v141
	ds_read_b128 v[148:151], v141 offset:1024
	ds_read_b128 v[152:155], v141 offset:2048
	ds_read_b128 v[156:159], v141 offset:3072
	ds_read_b128 v[180:183], v142
	ds_read_b128 v[184:187], v142 offset:1024
	ds_read_b128 v[188:191], v142 offset:2048
	ds_read_b128 v[192:195], v142 offset:3072
	s_add_i32 s45, s44, 2
	s_add_u32 s22, s6, 0xfff80080
	s_addc_u32 s23, s7, -1
	s_cmp_eq_u32 s41, s44
	s_cselect_b32 s25, s17, s23
	s_cselect_b32 s24, s39, s22
	s_cselect_b32 s23, s15, s43
	s_cselect_b32 s22, s40, s42
	v_lshl_add_u64 v[160:161], s[6:7], 0, v[130:131]
	s_add_i32 m0, s13, 0xc000
	ds_read_b128 v[196:199], v143
	ds_read_b128 v[200:203], v143 offset:1024
	ds_read_b128 v[204:207], v143 offset:2048
	ds_read_b128 v[208:211], v143 offset:3072
	ds_read_b128 v[232:235], v143 offset:4096
	ds_read_b128 v[236:239], v143 offset:5120
	ds_read_b128 v[240:243], v143 offset:6144
	ds_read_b128 v[244:247], v143 offset:7168
	global_load_lds_dwordx4 v[160:161], off
	v_lshl_add_u64 v[160:161], s[6:7], 0, v[132:133]
	s_add_i32 m0, s13, 0xe000
	s_nop 0
	global_load_lds_dwordx4 v[160:161], off
	s_waitcnt vmcnt(8)
	s_waitcnt lgkmcnt(0)
	s_barrier
	s_setprio 1
	s_waitcnt lgkmcnt(0)
	v_mfma_f32_16x16x32_bf16 v[126:129], v[144:147], v[196:199], v[126:129]
	v_mfma_f32_16x16x32_bf16 v[122:125], v[152:155], v[196:199], v[122:125]
	v_mfma_f32_16x16x32_bf16 v[118:121], v[144:147], v[204:207], v[118:121]
	v_mfma_f32_16x16x32_bf16 v[114:117], v[152:155], v[204:207], v[114:117]
	v_mfma_f32_16x16x32_bf16 v[102:105], v[144:147], v[232:235], v[102:105]
	v_mfma_f32_16x16x32_bf16 v[98:101], v[152:155], v[232:235], v[98:101]
	v_mfma_f32_16x16x32_bf16 v[86:89], v[144:147], v[240:243], v[86:89]
	v_mfma_f32_16x16x32_bf16 v[82:85], v[152:155], v[240:243], v[82:85]
	v_mfma_f32_16x16x32_bf16 v[126:129], v[148:151], v[200:203], v[126:129]
	v_mfma_f32_16x16x32_bf16 v[122:125], v[156:159], v[200:203], v[122:125]
	v_mfma_f32_16x16x32_bf16 v[118:121], v[148:151], v[208:211], v[118:121]
	v_mfma_f32_16x16x32_bf16 v[114:117], v[156:159], v[208:211], v[114:117]
	v_mfma_f32_16x16x32_bf16 v[102:105], v[148:151], v[236:239], v[102:105]
	v_mfma_f32_16x16x32_bf16 v[98:101], v[156:159], v[236:239], v[98:101]
	v_mfma_f32_16x16x32_bf16 v[86:89], v[148:151], v[244:247], v[86:89]
	v_mfma_f32_16x16x32_bf16 v[82:85], v[156:159], v[244:247], v[82:85]
	v_mfma_f32_16x16x32_bf16 v[110:113], v[180:183], v[196:199], v[110:113]
	v_mfma_f32_16x16x32_bf16 v[106:109], v[188:191], v[196:199], v[106:109]
	v_mfma_f32_16x16x32_bf16 v[94:97], v[180:183], v[204:207], v[94:97]
	v_mfma_f32_16x16x32_bf16 v[90:93], v[188:191], v[204:207], v[90:93]
	v_mfma_f32_16x16x32_bf16 v[78:81], v[180:183], v[232:235], v[78:81]
	v_mfma_f32_16x16x32_bf16 v[74:77], v[188:191], v[232:235], v[74:77]
	v_mfma_f32_16x16x32_bf16 v[70:73], v[180:183], v[240:243], v[70:73]
	v_mfma_f32_16x16x32_bf16 v[66:69], v[188:191], v[240:243], v[66:69]
	v_mfma_f32_16x16x32_bf16 v[110:113], v[184:187], v[200:203], v[110:113]
	v_mfma_f32_16x16x32_bf16 v[106:109], v[192:195], v[200:203], v[106:109]
	v_mfma_f32_16x16x32_bf16 v[94:97], v[184:187], v[208:211], v[94:97]
	v_mfma_f32_16x16x32_bf16 v[90:93], v[192:195], v[208:211], v[90:93]
	v_mfma_f32_16x16x32_bf16 v[78:81], v[184:187], v[236:239], v[78:81]
	v_mfma_f32_16x16x32_bf16 v[74:77], v[192:195], v[236:239], v[74:77]
	v_mfma_f32_16x16x32_bf16 v[70:73], v[184:187], v[244:247], v[70:73]
	v_mfma_f32_16x16x32_bf16 v[66:69], v[192:195], v[244:247], v[66:69]
	s_setprio 0
	s_barrier
	s_add_i32 s44, s34, s2
	v_lshl_add_u64 v[160:161], s[22:23], 0, v[168:169]
	s_mov_b32 m0, s44
	ds_read_b128 v[196:199], v143 offset:16384
	ds_read_b128 v[200:203], v143 offset:17408
	ds_read_b128 v[204:207], v143 offset:18432
	ds_read_b128 v[208:211], v143 offset:19456
	ds_read_b128 v[232:235], v143 offset:20480
	ds_read_b128 v[236:239], v143 offset:21504
	ds_read_b128 v[240:243], v143 offset:22528
	ds_read_b128 v[244:247], v143 offset:23552
	global_load_lds_dwordx4 v[160:161], off
	s_add_i32 m0, s44, 0x2000
	s_add_u32 s46, s22, 0x80000
	v_lshl_add_u64 v[212:213], s[22:23], 0, v[172:173]
	s_addc_u32 s47, s23, 0
	s_add_i32 s44, s35, s2
	global_load_lds_dwordx4 v[212:213], off
	v_lshl_add_u64 v[222:223], s[46:47], 0, v[168:169]
	s_mov_b32 m0, s44
	v_lshl_add_u64 v[248:249], s[24:25], 0, v[170:171]
	global_load_lds_dwordx4 v[222:223], off
	v_lshl_add_u64 v[222:223], s[46:47], 0, v[172:173]
	s_add_i32 m0, s44, 0x2000
	s_nop 0
	global_load_lds_dwordx4 v[222:223], off
	v_lshl_add_u64 v[222:223], s[24:25], 0, v[166:167]
	s_mov_b32 m0, s13
	s_nop 0
	global_load_lds_dwordx4 v[222:223], off
	s_mov_b32 m0, s26
	s_nop 0
	global_load_lds_dwordx4 v[248:249], off
	s_waitcnt vmcnt(8)
	s_waitcnt lgkmcnt(0)
	s_barrier
; #define PG8_STAGE(bufoff, gbase, voff) do { _Pragma("unroll") for (int _i = 0; _i < 2; ++_i) \
;         __builtin_amdgcn_global_load_lds((const unsigned*)((const char*)(gbase) + (voff)[_i]), (PG8_LAS unsigned*)(lds + (bufoff) + ldsw + _i * 8192), 16, 0, 0); } while (0)
; #define PG8_LDA(dst, b, h) do { _Pragma("unroll") for (int m = 0; m < 4; ++m) _Pragma("unroll") for (int k = 0; k < 2; ++k) dst[m][k] = *(const PG8_LAS bf16x8*)(lds + PG8_SA(b, h) + aoff + m * 2048 + k * 1024); } while (0)
; #define PG8_LDB(dst, b, h) do { _Pragma("unroll") for (int n = 0; n < 2; ++n) _Pragma("unroll") for (int k = 0; k < 2; ++k) dst[n][k] = *(const PG8_LAS bf16x8*)(lds + PG8_SB(b, h) + boff + n * 2048 + k * 1024); } while (0)
; #define PG8_MMA(ai, bj, At, Bt) do { __builtin_amdgcn_s_setprio(1); _Pragma("unroll") for (int m = 0; m < 4; ++m) _Pragma("unroll") for (int n = 0; n < 2; ++n) _Pragma("unroll") for (int k = 0; k < 2; ++k) \
;         acc[ai][bj][m][n] = __builtin_amdgcn_mfma_f32_16x16x32_bf16(Bt[n][k], At[m][k], acc[ai][bj][m][n], 0, 0, 0); __builtin_amdgcn_s_setprio(0); } while (0)
; #define PG8_WAIT_V(n) asm volatile("s_waitcnt vmcnt(" #n ")" ::: "memory")
; #define PG8_WAIT_L(n) asm volatile("s_waitcnt lgkmcnt(" #n ")" ::: "memory")
; #define PG8_BAR __builtin_amdgcn_s_barrier()
; #define PG8_SCHED __builtin_amdgcn_sched_barrier(0)
; template <class Epi, class Sched, bool ALIGN_EPI = false, bool SP2 = false>
; __device__ __forceinline__ void gemm_phase(PG8_LAS unsigned char* lds, const Gemm g, const Sched& S, const Epi& E) {
;     ...
;             PG8_WAIT_V(8); PG8_WAIT_L(0); PG8_BAR; PG8_MMA(1, 0, At, B0); PG8_MMA(1, 1, At, B1); PG8_BAR; PG8_SCHED;
;             PG8_LDB(B0, 1, 0); PG8_LDB(B1, 1, 1); PG8_SCHED; PG8_LDA(At, 1, 0); PG8_STAGE(PG8_SA(0, 1), a2 + hstep, voffA);
;             PG8_WAIT_V(8); PG8_WAIT_L(0); PG8_BAR; PG8_MMA(0, 0, At, B0); PG8_MMA(0, 1, At, B1); PG8_BAR; PG8_SCHED;
	s_setprio 1
	s_waitcnt lgkmcnt(0)
	v_mfma_f32_16x16x32_bf16 v[62:65], v[144:147], v[196:199], v[62:65]
	v_mfma_f32_16x16x32_bf16 v[58:61], v[152:155], v[196:199], v[58:61]
	v_mfma_f32_16x16x32_bf16 v[54:57], v[144:147], v[204:207], v[54:57]
	v_mfma_f32_16x16x32_bf16 v[50:53], v[152:155], v[204:207], v[50:53]
	v_mfma_f32_16x16x32_bf16 v[38:41], v[144:147], v[232:235], v[38:41]
	v_mfma_f32_16x16x32_bf16 v[34:37], v[152:155], v[232:235], v[34:37]
	v_mfma_f32_16x16x32_bf16 v[22:25], v[144:147], v[240:243], v[22:25]
	v_mfma_f32_16x16x32_bf16 v[18:21], v[152:155], v[240:243], v[18:21]
	v_mfma_f32_16x16x32_bf16 v[62:65], v[148:151], v[200:203], v[62:65]
	v_mfma_f32_16x16x32_bf16 v[58:61], v[156:159], v[200:203], v[58:61]
	v_mfma_f32_16x16x32_bf16 v[54:57], v[148:151], v[208:211], v[54:57]
	v_mfma_f32_16x16x32_bf16 v[50:53], v[156:159], v[208:211], v[50:53]
	v_mfma_f32_16x16x32_bf16 v[38:41], v[148:151], v[236:239], v[38:41]
	v_mfma_f32_16x16x32_bf16 v[34:37], v[156:159], v[236:239], v[34:37]
	v_mfma_f32_16x16x32_bf16 v[22:25], v[148:151], v[244:247], v[22:25]
	v_mfma_f32_16x16x32_bf16 v[18:21], v[156:159], v[244:247], v[18:21]
	v_mfma_f32_16x16x32_bf16 v[46:49], v[180:183], v[196:199], v[46:49]
	v_mfma_f32_16x16x32_bf16 v[42:45], v[188:191], v[196:199], v[42:45]
	v_mfma_f32_16x16x32_bf16 v[30:33], v[180:183], v[204:207], v[30:33]
	v_mfma_f32_16x16x32_bf16 v[26:29], v[188:191], v[204:207], v[26:29]
	v_mfma_f32_16x16x32_bf16 v[14:17], v[180:183], v[232:235], v[14:17]
	v_mfma_f32_16x16x32_bf16 v[10:13], v[188:191], v[232:235], v[10:13]
	v_mfma_f32_16x16x32_bf16 v[6:9], v[180:183], v[240:243], v[6:9]
	v_mfma_f32_16x16x32_bf16 v[2:5], v[188:191], v[240:243], v[2:5]
	v_mfma_f32_16x16x32_bf16 v[46:49], v[184:187], v[200:203], v[46:49]
	v_mfma_f32_16x16x32_bf16 v[42:45], v[192:195], v[200:203], v[42:45]
	v_mfma_f32_16x16x32_bf16 v[30:33], v[184:187], v[208:211], v[30:33]
	v_mfma_f32_16x16x32_bf16 v[26:29], v[192:195], v[208:211], v[26:29]
	v_mfma_f32_16x16x32_bf16 v[14:17], v[184:187], v[236:239], v[14:17]
	v_mfma_f32_16x16x32_bf16 v[10:13], v[192:195], v[236:239], v[10:13]
	v_mfma_f32_16x16x32_bf16 v[6:9], v[184:187], v[244:247], v[6:9]
	v_mfma_f32_16x16x32_bf16 v[2:5], v[192:195], v[244:247], v[2:5]
	s_setprio 0
	s_barrier
	s_add_i32 s44, 0, 0x18000
	s_add_i32 s46, 0, 0x1c000
	v_add_u32_e32 v156, s44, v139
	v_add_u32_e32 v192, s46, v139
	ds_read_b128 v[144:147], v156
	ds_read_b128 v[148:151], v156 offset:1024
	ds_read_b128 v[152:155], v156 offset:2048
	ds_read_b128 v[156:159], v156 offset:3072
	ds_read_b128 v[180:183], v192
	ds_read_b128 v[184:187], v192 offset:1024
	ds_read_b128 v[188:191], v192 offset:2048
	ds_read_b128 v[192:195], v192 offset:3072
	s_add_u32 s24, s24, 0x80000
	s_addc_u32 s25, s25, 0
	s_mov_b32 m0, s27
	v_lshl_add_u64 v[250:251], s[24:25], 0, v[166:167]
	ds_read_b128 v[196:199], v143 offset:32768
	ds_read_b128 v[200:203], v143 offset:33792
	ds_read_b128 v[204:207], v143 offset:34816
	ds_read_b128 v[208:211], v143 offset:35840
	ds_read_b128 v[232:235], v143 offset:36864
	ds_read_b128 v[236:239], v143 offset:37888
	ds_read_b128 v[240:243], v143 offset:38912
	ds_read_b128 v[244:247], v143 offset:39936
	global_load_lds_dwordx4 v[250:251], off
	v_lshl_add_u64 v[250:251], s[24:25], 0, v[170:171]
	s_mov_b32 m0, s28
	s_nop 0
	global_load_lds_dwordx4 v[250:251], off
	s_waitcnt vmcnt(8)
	s_waitcnt lgkmcnt(0)
	s_barrier
	s_setprio 1
	s_waitcnt lgkmcnt(0)
	v_mfma_f32_16x16x32_bf16 v[126:129], v[144:147], v[196:199], v[126:129]
	v_mfma_f32_16x16x32_bf16 v[122:125], v[152:155], v[196:199], v[122:125]
	v_mfma_f32_16x16x32_bf16 v[118:121], v[144:147], v[204:207], v[118:121]
	v_mfma_f32_16x16x32_bf16 v[114:117], v[152:155], v[204:207], v[114:117]
	v_mfma_f32_16x16x32_bf16 v[102:105], v[144:147], v[232:235], v[102:105]
	v_mfma_f32_16x16x32_bf16 v[98:101], v[152:155], v[232:235], v[98:101]
	v_mfma_f32_16x16x32_bf16 v[86:89], v[144:147], v[240:243], v[86:89]
	v_mfma_f32_16x16x32_bf16 v[82:85], v[152:155], v[240:243], v[82:85]
	v_mfma_f32_16x16x32_bf16 v[126:129], v[148:151], v[200:203], v[126:129]
	v_mfma_f32_16x16x32_bf16 v[122:125], v[156:159], v[200:203], v[122:125]
	v_mfma_f32_16x16x32_bf16 v[118:121], v[148:151], v[208:211], v[118:121]
	v_mfma_f32_16x16x32_bf16 v[114:117], v[156:159], v[208:211], v[114:117]
	v_mfma_f32_16x16x32_bf16 v[102:105], v[148:151], v[236:239], v[102:105]
	v_mfma_f32_16x16x32_bf16 v[98:101], v[156:159], v[236:239], v[98:101]
	v_mfma_f32_16x16x32_bf16 v[86:89], v[148:151], v[244:247], v[86:89]
	v_mfma_f32_16x16x32_bf16 v[82:85], v[156:159], v[244:247], v[82:85]
	v_mfma_f32_16x16x32_bf16 v[110:113], v[180:183], v[196:199], v[110:113]
	v_mfma_f32_16x16x32_bf16 v[106:109], v[188:191], v[196:199], v[106:109]
	v_mfma_f32_16x16x32_bf16 v[94:97], v[180:183], v[204:207], v[94:97]
	v_mfma_f32_16x16x32_bf16 v[90:93], v[188:191], v[204:207], v[90:93]
	v_mfma_f32_16x16x32_bf16 v[78:81], v[180:183], v[232:235], v[78:81]
	v_mfma_f32_16x16x32_bf16 v[74:77], v[188:191], v[232:235], v[74:77]
	v_mfma_f32_16x16x32_bf16 v[70:73], v[180:183], v[240:243], v[70:73]
	v_mfma_f32_16x16x32_bf16 v[66:69], v[188:191], v[240:243], v[66:69]
	v_mfma_f32_16x16x32_bf16 v[110:113], v[184:187], v[200:203], v[110:113]
	v_mfma_f32_16x16x32_bf16 v[106:109], v[192:195], v[200:203], v[106:109]
	v_mfma_f32_16x16x32_bf16 v[94:97], v[184:187], v[208:211], v[94:97]
	v_mfma_f32_16x16x32_bf16 v[90:93], v[192:195], v[208:211], v[90:93]
	v_mfma_f32_16x16x32_bf16 v[78:81], v[184:187], v[236:239], v[78:81]
	v_mfma_f32_16x16x32_bf16 v[74:77], v[192:195], v[236:239], v[74:77]
	v_mfma_f32_16x16x32_bf16 v[70:73], v[184:187], v[244:247], v[70:73]
	v_mfma_f32_16x16x32_bf16 v[66:69], v[192:195], v[244:247], v[66:69]
	s_setprio 0
	s_barrier
; #define PG8_STAGE(bufoff, gbase, voff) do { _Pragma("unroll") for (int _i = 0; _i < 2; ++_i) \
;         __builtin_amdgcn_global_load_lds((const unsigned*)((const char*)(gbase) + (voff)[_i]), (PG8_LAS unsigned*)(lds + (bufoff) + ldsw + _i * 8192), 16, 0, 0); } while (0)
; #define PG8_LDA(dst, b, h) do { _Pragma("unroll") for (int m = 0; m < 4; ++m) _Pragma("unroll") for (int k = 0; k < 2; ++k) dst[m][k] = *(const PG8_LAS bf16x8*)(lds + PG8_SA(b, h) + aoff + m * 2048 + k * 1024); } while (0)
; #define PG8_MMA(ai, bj, At, Bt) do { __builtin_amdgcn_s_setprio(1); _Pragma("unroll") for (int m = 0; m < 4; ++m) _Pragma("unroll") for (int n = 0; n < 2; ++n) _Pragma("unroll") for (int k = 0; k < 2; ++k) \
;         acc[ai][bj][m][n] = __builtin_amdgcn_mfma_f32_16x16x32_bf16(Bt[n][k], At[m][k], acc[ai][bj][m][n], 0, 0, 0); __builtin_amdgcn_s_setprio(0); } while (0)
; #define PG8_WAIT_V(n) asm volatile("s_waitcnt vmcnt(" #n ")" ::: "memory")
; #define PG8_WAIT_L(n) asm volatile("s_waitcnt lgkmcnt(" #n ")" ::: "memory")
; #define PG8_BAR __builtin_amdgcn_s_barrier()
; #define PG8_SCHED __builtin_amdgcn_sched_barrier(0)
; template <class Epi, class Sched, bool ALIGN_EPI = false, bool SP2 = false>
; __device__ __forceinline__ void gemm_phase(PG8_LAS unsigned char* lds, const Gemm g, const Sched& S, const Epi& E) {
;     ...
;             PG8_LDA(At, 1, 1); PG8_STAGE(PG8_SB(1, 0), b3, voffB); PG8_STAGE(PG8_SB(1, 1), b3 + hstep, voffB); PG8_STAGE(PG8_SA(1, 0), a3, voffA);
;             PG8_WAIT_V(8); PG8_WAIT_L(0); PG8_BAR; PG8_MMA(1, 0, At, B0); PG8_MMA(1, 1, At, B1); PG8_BAR; PG8_SCHED;
;     ...
;         }
;         if constexpr (ALIGN_EPI) { if (wr == 0) PG8_BAR; }
	s_add_i32 s24, s44, s2
	v_lshl_add_u64 v[160:161], v[160:161], 0, s[8:9]
	s_mov_b32 m0, s24
	ds_read_b128 v[196:199], v143 offset:49152
	ds_read_b128 v[200:203], v143 offset:50176
	ds_read_b128 v[204:207], v143 offset:51200
	ds_read_b128 v[208:211], v143 offset:52224
	ds_read_b128 v[232:235], v143 offset:53248
	ds_read_b128 v[236:239], v143 offset:54272
	ds_read_b128 v[240:243], v143 offset:55296
	ds_read_b128 v[244:247], v143 offset:56320
	global_load_lds_dwordx4 v[160:161], off
	s_add_i32 m0, s24, 0x2000
	s_add_u32 s22, s22, 0x80080
	v_lshl_add_u64 v[160:161], v[212:213], 0, s[8:9]
	s_addc_u32 s23, s23, 0
	s_add_i32 s24, s46, s2
	global_load_lds_dwordx4 v[160:161], off
	v_lshl_add_u64 v[160:161], s[22:23], 0, v[168:169]
	s_mov_b32 m0, s24
	s_nop 0
	global_load_lds_dwordx4 v[160:161], off
	v_lshl_add_u64 v[160:161], s[22:23], 0, v[172:173]
	s_add_i32 m0, s24, 0x2000
	s_nop 0
	global_load_lds_dwordx4 v[160:161], off
	v_lshl_add_u64 v[160:161], v[222:223], 0, s[8:9]
	s_mov_b32 m0, s30
	s_nop 0
	global_load_lds_dwordx4 v[160:161], off
	v_lshl_add_u64 v[160:161], v[248:249], 0, s[8:9]
	s_mov_b32 m0, s31
	s_nop 0
	global_load_lds_dwordx4 v[160:161], off
	s_waitcnt vmcnt(8)
	s_waitcnt lgkmcnt(0)
	s_barrier
	s_setprio 1
	s_waitcnt lgkmcnt(0)
	v_mfma_f32_16x16x32_bf16 v[62:65], v[144:147], v[196:199], v[62:65]
	v_mfma_f32_16x16x32_bf16 v[58:61], v[152:155], v[196:199], v[58:61]
	v_mfma_f32_16x16x32_bf16 v[54:57], v[144:147], v[204:207], v[54:57]
	v_mfma_f32_16x16x32_bf16 v[50:53], v[152:155], v[204:207], v[50:53]
	v_mfma_f32_16x16x32_bf16 v[38:41], v[144:147], v[232:235], v[38:41]
	v_mfma_f32_16x16x32_bf16 v[34:37], v[152:155], v[232:235], v[34:37]
	v_mfma_f32_16x16x32_bf16 v[22:25], v[144:147], v[240:243], v[22:25]
	v_mfma_f32_16x16x32_bf16 v[18:21], v[152:155], v[240:243], v[18:21]
	v_mfma_f32_16x16x32_bf16 v[62:65], v[148:151], v[200:203], v[62:65]
	v_mfma_f32_16x16x32_bf16 v[58:61], v[156:159], v[200:203], v[58:61]
	v_mfma_f32_16x16x32_bf16 v[54:57], v[148:151], v[208:211], v[54:57]
	v_mfma_f32_16x16x32_bf16 v[50:53], v[156:159], v[208:211], v[50:53]
	v_mfma_f32_16x16x32_bf16 v[38:41], v[148:151], v[236:239], v[38:41]
	v_mfma_f32_16x16x32_bf16 v[34:37], v[156:159], v[236:239], v[34:37]
	v_mfma_f32_16x16x32_bf16 v[22:25], v[148:151], v[244:247], v[22:25]
	v_mfma_f32_16x16x32_bf16 v[18:21], v[156:159], v[244:247], v[18:21]
	v_mfma_f32_16x16x32_bf16 v[46:49], v[180:183], v[196:199], v[46:49]
	v_mfma_f32_16x16x32_bf16 v[42:45], v[188:191], v[196:199], v[42:45]
	v_mfma_f32_16x16x32_bf16 v[30:33], v[180:183], v[204:207], v[30:33]
	v_mfma_f32_16x16x32_bf16 v[26:29], v[188:191], v[204:207], v[26:29]
	v_mfma_f32_16x16x32_bf16 v[14:17], v[180:183], v[232:235], v[14:17]
	v_mfma_f32_16x16x32_bf16 v[10:13], v[188:191], v[232:235], v[10:13]
	v_mfma_f32_16x16x32_bf16 v[6:9], v[180:183], v[240:243], v[6:9]
	v_mfma_f32_16x16x32_bf16 v[2:5], v[188:191], v[240:243], v[2:5]
	v_mfma_f32_16x16x32_bf16 v[46:49], v[184:187], v[200:203], v[46:49]
	v_mfma_f32_16x16x32_bf16 v[42:45], v[192:195], v[200:203], v[42:45]
	v_mfma_f32_16x16x32_bf16 v[30:33], v[184:187], v[208:211], v[30:33]
	v_mfma_f32_16x16x32_bf16 v[26:29], v[192:195], v[208:211], v[26:29]
	v_mfma_f32_16x16x32_bf16 v[14:17], v[184:187], v[236:239], v[14:17]
	v_mfma_f32_16x16x32_bf16 v[10:13], v[192:195], v[236:239], v[10:13]
	v_mfma_f32_16x16x32_bf16 v[6:9], v[184:187], v[244:247], v[6:9]
	v_mfma_f32_16x16x32_bf16 v[2:5], v[192:195], v[244:247], v[2:5]
	s_setprio 0
	s_barrier
	s_add_u32 s6, s6, 0x100
	s_addc_u32 s7, s7, 0
	s_add_u32 s42, s42, 0x100
	s_addc_u32 s43, s43, 0
	s_cmp_ge_u32 s45, s38
	s_mov_b32 s44, s45
	s_cbranch_scc0 .LBB0_1029
	s_and_b64 vcc, exec, s[10:11]
	s_cbranch_vccz .LBB0_1032
	s_barrier

; #define PG8_STAGE(bufoff, gbase, voff) do { _Pragma("unroll") for (int _i = 0; _i < 2; ++_i) \
;         __builtin_amdgcn_global_load_lds((const unsigned*)((const char*)(gbase) + (voff)[_i]), (PG8_LAS unsigned*)(lds + (bufoff) + ldsw + _i * 8192), 16, 0, 0); } while (0)
; #define PG8_LDA(dst, b, h) do { _Pragma("unroll") for (int m = 0; m < 4; ++m) _Pragma("unroll") for (int k = 0; k < 2; ++k) dst[m][k] = *(const PG8_LAS bf16x8*)(lds + PG8_SA(b, h) + aoff + m * 2048 + k * 1024); } while (0)
; #define PG8_LDB(dst, b, h) do { _Pragma("unroll") for (int n = 0; n < 2; ++n) _Pragma("unroll") for (int k = 0; k < 2; ++k) dst[n][k] = *(const PG8_LAS bf16x8*)(lds + PG8_SB(b, h) + boff + n * 2048 + k * 1024); } while (0)
; #define PG8_MMA(ai, bj, At, Bt) do { __builtin_amdgcn_s_setprio(1); _Pragma("unroll") for (int m = 0; m < 4; ++m) _Pragma("unroll") for (int n = 0; n < 2; ++n) _Pragma("unroll") for (int k = 0; k < 2; ++k) \
;         acc[ai][bj][m][n] = __builtin_amdgcn_mfma_f32_16x16x32_bf16(Bt[n][k], At[m][k], acc[ai][bj][m][n], 0, 0, 0); __builtin_amdgcn_s_setprio(0); } while (0)
; #define PG8_WAIT_V(n) asm volatile("s_waitcnt vmcnt(" #n ")" ::: "memory")
; #define PG8_WAIT_L(n) asm volatile("s_waitcnt lgkmcnt(" #n ")" ::: "memory")
; #define PG8_BAR __builtin_amdgcn_s_barrier()
; #define PG8_SCHED __builtin_amdgcn_sched_barrier(0)
; template <class Epi, class Sched, bool ALIGN_EPI = false, bool SP2 = false>
; __device__ __forceinline__ void gemm_phase(PG8_LAS unsigned char* lds, const Gemm g, const Sched& S, const Epi& E) {
;     ...
;         for (int t = 0; t < nt; t += 2) {
;             const bool last = (t == nt - 2);
;             const char* a1 = cA + (size_t)(t + 1) * kstep;
;             const char* a2 = last ? nA : cA + (size_t)(t + 2) * kstep; const char* b2 = last ? nB : cB + (size_t)(t + 2) * kstep;
;             const char* a3 = a2 + kstep; const char* b3 = b2 + kstep;
;             if (last && has_next) S.a_ready(nxt);
;             if constexpr (SP2) {
;             PG8_LDB(B0, 0, 0); PG8_LDB(B1, 0, 1); PG8_SCHED; PG8_LDA(At, 0, 0); PG8_STAGE(PG8_SA(1, 1), a1 + hstep, voffA);
;             PG8_WAIT_V(8); PG8_WAIT_L(0); PG8_BAR; PG8_MMA(0, 0, At, B0); PG8_MMA(0, 1, At, B1); PG8_BAR; PG8_SCHED;
;             PG8_LDA(At, 0, 1); PG8_STAGE(PG8_SB(0, 0), b2, voffB); PG8_STAGE(PG8_SB(0, 1), b2 + hstep, voffB); PG8_STAGE(PG8_SA(0, 0), a2, voffA);
.LBB0_1053:
	ds_read_b128 v[140:143], v137
	ds_read_b128 v[144:147], v137 offset:1024
	ds_read_b128 v[148:151], v137 offset:2048
	ds_read_b128 v[152:155], v137 offset:3072
	ds_read_b128 v[156:159], v138
	ds_read_b128 v[180:183], v138 offset:1024
	ds_read_b128 v[184:187], v138 offset:2048
	ds_read_b128 v[188:191], v138 offset:3072
	s_add_i32 s54, s26, 2
	s_add_u32 s27, s24, 0xfff80080
	s_addc_u32 s28, s25, -1
	s_cmp_eq_u32 s48, s26
	s_cselect_b32 s26, s47, s49
	s_cselect_b32 s29, s19, s28
	s_cselect_b32 s28, s46, s27
	s_cselect_b32 s27, s17, s53
	v_lshl_add_u64 v[160:161], s[24:25], 0, v[130:131]
	s_add_i32 m0, s34, 0xc000
	ds_read_b128 v[192:195], v139
	ds_read_b128 v[196:199], v139 offset:1024
	ds_read_b128 v[200:203], v139 offset:2048
	ds_read_b128 v[204:207], v139 offset:3072
	ds_read_b128 v[208:211], v139 offset:4096
	ds_read_b128 v[232:235], v139 offset:5120
	ds_read_b128 v[236:239], v139 offset:6144
	ds_read_b128 v[240:243], v139 offset:7168
	global_load_lds_dwordx4 v[160:161], off
	v_lshl_add_u64 v[160:161], s[24:25], 0, v[132:133]
	s_add_i32 m0, s34, 0xe000
	s_nop 0
	global_load_lds_dwordx4 v[160:161], off
	s_waitcnt vmcnt(8)
	s_waitcnt lgkmcnt(0)
	s_barrier
	s_setprio 1
	s_waitcnt lgkmcnt(0)
	v_mfma_f32_16x16x32_bf16 v[126:129], v[140:143], v[192:195], v[126:129]
	v_mfma_f32_16x16x32_bf16 v[122:125], v[148:151], v[192:195], v[122:125]
	v_mfma_f32_16x16x32_bf16 v[118:121], v[140:143], v[200:203], v[118:121]
	v_mfma_f32_16x16x32_bf16 v[110:113], v[148:151], v[200:203], v[110:113]
	v_mfma_f32_16x16x32_bf16 v[102:105], v[140:143], v[208:211], v[102:105]
	v_mfma_f32_16x16x32_bf16 v[94:97], v[148:151], v[208:211], v[94:97]
	v_mfma_f32_16x16x32_bf16 v[86:89], v[140:143], v[236:239], v[86:89]
	v_mfma_f32_16x16x32_bf16 v[78:81], v[148:151], v[236:239], v[78:81]
	v_mfma_f32_16x16x32_bf16 v[126:129], v[144:147], v[196:199], v[126:129]
	v_mfma_f32_16x16x32_bf16 v[122:125], v[152:155], v[196:199], v[122:125]
	v_mfma_f32_16x16x32_bf16 v[118:121], v[144:147], v[204:207], v[118:121]
	v_mfma_f32_16x16x32_bf16 v[110:113], v[152:155], v[204:207], v[110:113]
	v_mfma_f32_16x16x32_bf16 v[102:105], v[144:147], v[232:235], v[102:105]
	v_mfma_f32_16x16x32_bf16 v[94:97], v[152:155], v[232:235], v[94:97]
	v_mfma_f32_16x16x32_bf16 v[86:89], v[144:147], v[240:243], v[86:89]
	v_mfma_f32_16x16x32_bf16 v[78:81], v[152:155], v[240:243], v[78:81]
	v_mfma_f32_16x16x32_bf16 v[114:117], v[156:159], v[192:195], v[114:117]
	v_mfma_f32_16x16x32_bf16 v[106:109], v[184:187], v[192:195], v[106:109]
	v_mfma_f32_16x16x32_bf16 v[98:101], v[156:159], v[200:203], v[98:101]
	v_mfma_f32_16x16x32_bf16 v[90:93], v[184:187], v[200:203], v[90:93]
	v_mfma_f32_16x16x32_bf16 v[82:85], v[156:159], v[208:211], v[82:85]
	v_mfma_f32_16x16x32_bf16 v[74:77], v[184:187], v[208:211], v[74:77]
	v_mfma_f32_16x16x32_bf16 v[70:73], v[156:159], v[236:239], v[70:73]
	v_mfma_f32_16x16x32_bf16 v[66:69], v[184:187], v[236:239], v[66:69]
	v_mfma_f32_16x16x32_bf16 v[114:117], v[180:183], v[196:199], v[114:117]
	v_mfma_f32_16x16x32_bf16 v[106:109], v[188:191], v[196:199], v[106:109]
	v_mfma_f32_16x16x32_bf16 v[98:101], v[180:183], v[204:207], v[98:101]
	v_mfma_f32_16x16x32_bf16 v[90:93], v[188:191], v[204:207], v[90:93]
	v_mfma_f32_16x16x32_bf16 v[82:85], v[180:183], v[232:235], v[82:85]
	v_mfma_f32_16x16x32_bf16 v[74:77], v[188:191], v[232:235], v[74:77]
	v_mfma_f32_16x16x32_bf16 v[70:73], v[180:183], v[240:243], v[70:73]
	v_mfma_f32_16x16x32_bf16 v[66:69], v[188:191], v[240:243], v[66:69]
	s_setprio 0
	s_barrier
	s_add_i32 s55, s42, s30
	v_lshl_add_u64 v[160:161], s[26:27], 0, v[166:167]
	s_mov_b32 m0, s55
	ds_read_b128 v[192:195], v139 offset:16384
	ds_read_b128 v[196:199], v139 offset:17408
	ds_read_b128 v[200:203], v139 offset:18432
	ds_read_b128 v[204:207], v139 offset:19456
	ds_read_b128 v[208:211], v139 offset:20480
	ds_read_b128 v[232:235], v139 offset:21504
	ds_read_b128 v[236:239], v139 offset:22528
	ds_read_b128 v[240:243], v139 offset:23552
	global_load_lds_dwordx4 v[160:161], off
	s_add_i32 m0, s55, 0x2000
	s_add_u32 s56, s26, 0x80000
	v_lshl_add_u64 v[212:213], s[26:27], 0, v[170:171]
	s_addc_u32 s57, s27, 0
	s_add_i32 s55, s43, s30
	global_load_lds_dwordx4 v[212:213], off
	v_lshl_add_u64 v[222:223], s[56:57], 0, v[166:167]
	s_mov_b32 m0, s55
	v_lshl_add_u64 v[244:245], s[28:29], 0, v[170:171]
	global_load_lds_dwordx4 v[222:223], off
	v_lshl_add_u64 v[222:223], s[56:57], 0, v[170:171]
	s_add_i32 m0, s55, 0x2000
	s_nop 0
	global_load_lds_dwordx4 v[222:223], off
	v_lshl_add_u64 v[222:223], s[28:29], 0, v[166:167]
	s_mov_b32 m0, s34
	s_nop 0
	global_load_lds_dwordx4 v[222:223], off
	s_mov_b32 m0, s35
	s_nop 0
	global_load_lds_dwordx4 v[244:245], off
	s_waitcnt vmcnt(8)
	s_waitcnt lgkmcnt(0)
	s_barrier
; #define PG8_STAGE(bufoff, gbase, voff) do { _Pragma("unroll") for (int _i = 0; _i < 2; ++_i) \
;         __builtin_amdgcn_global_load_lds((const unsigned*)((const char*)(gbase) + (voff)[_i]), (PG8_LAS unsigned*)(lds + (bufoff) + ldsw + _i * 8192), 16, 0, 0); } while (0)
; #define PG8_LDA(dst, b, h) do { _Pragma("unroll") for (int m = 0; m < 4; ++m) _Pragma("unroll") for (int k = 0; k < 2; ++k) dst[m][k] = *(const PG8_LAS bf16x8*)(lds + PG8_SA(b, h) + aoff + m * 2048 + k * 1024); } while (0)
; #define PG8_LDB(dst, b, h) do { _Pragma("unroll") for (int n = 0; n < 2; ++n) _Pragma("unroll") for (int k = 0; k < 2; ++k) dst[n][k] = *(const PG8_LAS bf16x8*)(lds + PG8_SB(b, h) + boff + n * 2048 + k * 1024); } while (0)
; #define PG8_MMA(ai, bj, At, Bt) do { __builtin_amdgcn_s_setprio(1); _Pragma("unroll") for (int m = 0; m < 4; ++m) _Pragma("unroll") for (int n = 0; n < 2; ++n) _Pragma("unroll") for (int k = 0; k < 2; ++k) \
;         acc[ai][bj][m][n] = __builtin_amdgcn_mfma_f32_16x16x32_bf16(Bt[n][k], At[m][k], acc[ai][bj][m][n], 0, 0, 0); __builtin_amdgcn_s_setprio(0); } while (0)
; #define PG8_WAIT_V(n) asm volatile("s_waitcnt vmcnt(" #n ")" ::: "memory")
; #define PG8_WAIT_L(n) asm volatile("s_waitcnt lgkmcnt(" #n ")" ::: "memory")
; #define PG8_BAR __builtin_amdgcn_s_barrier()
; #define PG8_SCHED __builtin_amdgcn_sched_barrier(0)
; template <class Epi, class Sched, bool ALIGN_EPI = false, bool SP2 = false>
; __device__ __forceinline__ void gemm_phase(PG8_LAS unsigned char* lds, const Gemm g, const Sched& S, const Epi& E) {
;     ...
;             PG8_WAIT_V(8); PG8_WAIT_L(0); PG8_BAR; PG8_MMA(1, 0, At, B0); PG8_MMA(1, 1, At, B1); PG8_BAR; PG8_SCHED;
;             PG8_LDB(B0, 1, 0); PG8_LDB(B1, 1, 1); PG8_SCHED; PG8_LDA(At, 1, 0); PG8_STAGE(PG8_SA(0, 1), a2 + hstep, voffA);
;             PG8_WAIT_V(8); PG8_WAIT_L(0); PG8_BAR; PG8_MMA(0, 0, At, B0); PG8_MMA(0, 1, At, B1); PG8_BAR; PG8_SCHED;
	s_setprio 1
	s_waitcnt lgkmcnt(0)
	v_mfma_f32_16x16x32_bf16 v[62:65], v[140:143], v[192:195], v[62:65]
	v_mfma_f32_16x16x32_bf16 v[58:61], v[148:151], v[192:195], v[58:61]
	v_mfma_f32_16x16x32_bf16 v[54:57], v[140:143], v[200:203], v[54:57]
	v_mfma_f32_16x16x32_bf16 v[46:49], v[148:151], v[200:203], v[46:49]
	v_mfma_f32_16x16x32_bf16 v[38:41], v[140:143], v[208:211], v[38:41]
	v_mfma_f32_16x16x32_bf16 v[30:33], v[148:151], v[208:211], v[30:33]
	v_mfma_f32_16x16x32_bf16 v[22:25], v[140:143], v[236:239], v[22:25]
	v_mfma_f32_16x16x32_bf16 v[14:17], v[148:151], v[236:239], v[14:17]
	v_mfma_f32_16x16x32_bf16 v[62:65], v[144:147], v[196:199], v[62:65]
	v_mfma_f32_16x16x32_bf16 v[58:61], v[152:155], v[196:199], v[58:61]
	v_mfma_f32_16x16x32_bf16 v[54:57], v[144:147], v[204:207], v[54:57]
	v_mfma_f32_16x16x32_bf16 v[46:49], v[152:155], v[204:207], v[46:49]
	v_mfma_f32_16x16x32_bf16 v[38:41], v[144:147], v[232:235], v[38:41]
	v_mfma_f32_16x16x32_bf16 v[30:33], v[152:155], v[232:235], v[30:33]
	v_mfma_f32_16x16x32_bf16 v[22:25], v[144:147], v[240:243], v[22:25]
	v_mfma_f32_16x16x32_bf16 v[14:17], v[152:155], v[240:243], v[14:17]
	v_mfma_f32_16x16x32_bf16 v[50:53], v[156:159], v[192:195], v[50:53]
	v_mfma_f32_16x16x32_bf16 v[42:45], v[184:187], v[192:195], v[42:45]
	v_mfma_f32_16x16x32_bf16 v[34:37], v[156:159], v[200:203], v[34:37]
	v_mfma_f32_16x16x32_bf16 v[26:29], v[184:187], v[200:203], v[26:29]
	v_mfma_f32_16x16x32_bf16 v[18:21], v[156:159], v[208:211], v[18:21]
	v_mfma_f32_16x16x32_bf16 v[10:13], v[184:187], v[208:211], v[10:13]
	v_mfma_f32_16x16x32_bf16 v[6:9], v[156:159], v[236:239], v[6:9]
	v_mfma_f32_16x16x32_bf16 v[2:5], v[184:187], v[236:239], v[2:5]
	v_mfma_f32_16x16x32_bf16 v[50:53], v[180:183], v[196:199], v[50:53]
	v_mfma_f32_16x16x32_bf16 v[42:45], v[188:191], v[196:199], v[42:45]
	v_mfma_f32_16x16x32_bf16 v[34:37], v[180:183], v[204:207], v[34:37]
	v_mfma_f32_16x16x32_bf16 v[26:29], v[188:191], v[204:207], v[26:29]
	v_mfma_f32_16x16x32_bf16 v[18:21], v[180:183], v[232:235], v[18:21]
	v_mfma_f32_16x16x32_bf16 v[10:13], v[188:191], v[232:235], v[10:13]
	v_mfma_f32_16x16x32_bf16 v[6:9], v[180:183], v[240:243], v[6:9]
	v_mfma_f32_16x16x32_bf16 v[2:5], v[188:191], v[240:243], v[2:5]
	s_setprio 0
	s_barrier
	s_add_i32 s55, 0, 0x18000
	s_add_i32 s56, 0, 0x1c000
	v_add_u32_e32 v152, s55, v135
	v_add_u32_e32 v169, s56, v135
	ds_read_b128 v[140:143], v152
	ds_read_b128 v[144:147], v152 offset:1024
	ds_read_b128 v[148:151], v152 offset:2048
	ds_read_b128 v[152:155], v152 offset:3072
	ds_read_b128 v[156:159], v169
	ds_read_b128 v[180:183], v169 offset:1024
	ds_read_b128 v[184:187], v169 offset:2048
	ds_read_b128 v[188:191], v169 offset:3072
	s_add_u32 s28, s28, 0x80000
	s_addc_u32 s29, s29, 0
	s_mov_b32 m0, s36
	v_lshl_add_u64 v[246:247], s[28:29], 0, v[166:167]
	ds_read_b128 v[192:195], v139 offset:32768
	ds_read_b128 v[196:199], v139 offset:33792
	ds_read_b128 v[200:203], v139 offset:34816
	ds_read_b128 v[204:207], v139 offset:35840
	ds_read_b128 v[208:211], v139 offset:36864
	ds_read_b128 v[232:235], v139 offset:37888
	ds_read_b128 v[236:239], v139 offset:38912
	ds_read_b128 v[240:243], v139 offset:39936
	global_load_lds_dwordx4 v[246:247], off
	v_lshl_add_u64 v[246:247], s[28:29], 0, v[170:171]
	s_mov_b32 m0, s37
	s_nop 0
	global_load_lds_dwordx4 v[246:247], off
	s_waitcnt vmcnt(8)
	s_waitcnt lgkmcnt(0)
	s_barrier
	s_setprio 1
	s_waitcnt lgkmcnt(0)
	v_mfma_f32_16x16x32_bf16 v[126:129], v[140:143], v[192:195], v[126:129]
	v_mfma_f32_16x16x32_bf16 v[122:125], v[148:151], v[192:195], v[122:125]
	v_mfma_f32_16x16x32_bf16 v[118:121], v[140:143], v[200:203], v[118:121]
	v_mfma_f32_16x16x32_bf16 v[110:113], v[148:151], v[200:203], v[110:113]
	v_mfma_f32_16x16x32_bf16 v[102:105], v[140:143], v[208:211], v[102:105]
	v_mfma_f32_16x16x32_bf16 v[94:97], v[148:151], v[208:211], v[94:97]
	v_mfma_f32_16x16x32_bf16 v[86:89], v[140:143], v[236:239], v[86:89]
	v_mfma_f32_16x16x32_bf16 v[78:81], v[148:151], v[236:239], v[78:81]
	v_mfma_f32_16x16x32_bf16 v[126:129], v[144:147], v[196:199], v[126:129]
	v_mfma_f32_16x16x32_bf16 v[122:125], v[152:155], v[196:199], v[122:125]
	v_mfma_f32_16x16x32_bf16 v[118:121], v[144:147], v[204:207], v[118:121]
	v_mfma_f32_16x16x32_bf16 v[110:113], v[152:155], v[204:207], v[110:113]
	v_mfma_f32_16x16x32_bf16 v[102:105], v[144:147], v[232:235], v[102:105]
	v_mfma_f32_16x16x32_bf16 v[94:97], v[152:155], v[232:235], v[94:97]
	v_mfma_f32_16x16x32_bf16 v[86:89], v[144:147], v[240:243], v[86:89]
	v_mfma_f32_16x16x32_bf16 v[78:81], v[152:155], v[240:243], v[78:81]
	v_mfma_f32_16x16x32_bf16 v[114:117], v[156:159], v[192:195], v[114:117]
	v_mfma_f32_16x16x32_bf16 v[106:109], v[184:187], v[192:195], v[106:109]
	v_mfma_f32_16x16x32_bf16 v[98:101], v[156:159], v[200:203], v[98:101]
	v_mfma_f32_16x16x32_bf16 v[90:93], v[184:187], v[200:203], v[90:93]
	v_mfma_f32_16x16x32_bf16 v[82:85], v[156:159], v[208:211], v[82:85]
	v_mfma_f32_16x16x32_bf16 v[74:77], v[184:187], v[208:211], v[74:77]
	v_mfma_f32_16x16x32_bf16 v[70:73], v[156:159], v[236:239], v[70:73]
	v_mfma_f32_16x16x32_bf16 v[66:69], v[184:187], v[236:239], v[66:69]
	v_mfma_f32_16x16x32_bf16 v[114:117], v[180:183], v[196:199], v[114:117]
	v_mfma_f32_16x16x32_bf16 v[106:109], v[188:191], v[196:199], v[106:109]
	v_mfma_f32_16x16x32_bf16 v[98:101], v[180:183], v[204:207], v[98:101]
	v_mfma_f32_16x16x32_bf16 v[90:93], v[188:191], v[204:207], v[90:93]
	v_mfma_f32_16x16x32_bf16 v[82:85], v[180:183], v[232:235], v[82:85]
	v_mfma_f32_16x16x32_bf16 v[74:77], v[188:191], v[232:235], v[74:77]
	v_mfma_f32_16x16x32_bf16 v[70:73], v[180:183], v[240:243], v[70:73]
	v_mfma_f32_16x16x32_bf16 v[66:69], v[188:191], v[240:243], v[66:69]
	s_setprio 0
	s_barrier
; #define PG8_STAGE(bufoff, gbase, voff) do { _Pragma("unroll") for (int _i = 0; _i < 2; ++_i) \
;         __builtin_amdgcn_global_load_lds((const unsigned*)((const char*)(gbase) + (voff)[_i]), (PG8_LAS unsigned*)(lds + (bufoff) + ldsw + _i * 8192), 16, 0, 0); } while (0)
; #define PG8_LDA(dst, b, h) do { _Pragma("unroll") for (int m = 0; m < 4; ++m) _Pragma("unroll") for (int k = 0; k < 2; ++k) dst[m][k] = *(const PG8_LAS bf16x8*)(lds + PG8_SA(b, h) + aoff + m * 2048 + k * 1024); } while (0)
; #define PG8_MMA(ai, bj, At, Bt) do { __builtin_amdgcn_s_setprio(1); _Pragma("unroll") for (int m = 0; m < 4; ++m) _Pragma("unroll") for (int n = 0; n < 2; ++n) _Pragma("unroll") for (int k = 0; k < 2; ++k) \
;         acc[ai][bj][m][n] = __builtin_amdgcn_mfma_f32_16x16x32_bf16(Bt[n][k], At[m][k], acc[ai][bj][m][n], 0, 0, 0); __builtin_amdgcn_s_setprio(0); } while (0)
; #define PG8_WAIT_V(n) asm volatile("s_waitcnt vmcnt(" #n ")" ::: "memory")
; #define PG8_WAIT_L(n) asm volatile("s_waitcnt lgkmcnt(" #n ")" ::: "memory")
; #define PG8_BAR __builtin_amdgcn_s_barrier()
; #define PG8_SCHED __builtin_amdgcn_sched_barrier(0)
; template <class Epi, class Sched, bool ALIGN_EPI = false, bool SP2 = false>
; __device__ __forceinline__ void gemm_phase(PG8_LAS unsigned char* lds, const Gemm g, const Sched& S, const Epi& E) {
;     ...
;             PG8_LDA(At, 1, 1); PG8_STAGE(PG8_SB(1, 0), b3, voffB); PG8_STAGE(PG8_SB(1, 1), b3 + hstep, voffB); PG8_STAGE(PG8_SA(1, 0), a3, voffA);
;             PG8_WAIT_V(8); PG8_WAIT_L(0); PG8_BAR; PG8_MMA(1, 0, At, B0); PG8_MMA(1, 1, At, B1); PG8_BAR; PG8_SCHED;
;     ...
;         }
;         if constexpr (ALIGN_EPI) { if (wr == 0) PG8_BAR; }
	s_add_i32 s28, s55, s30
	v_lshl_add_u64 v[160:161], v[160:161], 0, s[4:5]
	s_mov_b32 m0, s28
	ds_read_b128 v[192:195], v139 offset:49152
	ds_read_b128 v[196:199], v139 offset:50176
	ds_read_b128 v[200:203], v139 offset:51200
	ds_read_b128 v[204:207], v139 offset:52224
	ds_read_b128 v[208:211], v139 offset:53248
	ds_read_b128 v[232:235], v139 offset:54272
	ds_read_b128 v[236:239], v139 offset:55296
	ds_read_b128 v[240:243], v139 offset:56320
	global_load_lds_dwordx4 v[160:161], off
	s_add_i32 m0, s28, 0x2000
	s_add_u32 s26, s26, 0x80080
	v_lshl_add_u64 v[160:161], v[212:213], 0, s[4:5]
	s_addc_u32 s27, s27, 0
	s_add_i32 s28, s56, s30
	global_load_lds_dwordx4 v[160:161], off
	v_lshl_add_u64 v[160:161], s[26:27], 0, v[166:167]
	s_mov_b32 m0, s28
	s_nop 0
	global_load_lds_dwordx4 v[160:161], off
	v_lshl_add_u64 v[160:161], s[26:27], 0, v[170:171]
	s_add_i32 m0, s28, 0x2000
	s_nop 0
	global_load_lds_dwordx4 v[160:161], off
	v_lshl_add_u64 v[160:161], v[222:223], 0, s[4:5]
	s_mov_b32 m0, s39
	s_nop 0
	global_load_lds_dwordx4 v[160:161], off
	v_lshl_add_u64 v[160:161], v[244:245], 0, s[4:5]
	s_mov_b32 m0, s40
	s_nop 0
	global_load_lds_dwordx4 v[160:161], off
	s_waitcnt vmcnt(8)
	s_waitcnt lgkmcnt(0)
	s_barrier
	s_setprio 1
	s_waitcnt lgkmcnt(0)
	v_mfma_f32_16x16x32_bf16 v[62:65], v[140:143], v[192:195], v[62:65]
	v_mfma_f32_16x16x32_bf16 v[58:61], v[148:151], v[192:195], v[58:61]
	v_mfma_f32_16x16x32_bf16 v[54:57], v[140:143], v[200:203], v[54:57]
	v_mfma_f32_16x16x32_bf16 v[46:49], v[148:151], v[200:203], v[46:49]
	v_mfma_f32_16x16x32_bf16 v[38:41], v[140:143], v[208:211], v[38:41]
	v_mfma_f32_16x16x32_bf16 v[30:33], v[148:151], v[208:211], v[30:33]
	v_mfma_f32_16x16x32_bf16 v[22:25], v[140:143], v[236:239], v[22:25]
	v_mfma_f32_16x16x32_bf16 v[14:17], v[148:151], v[236:239], v[14:17]
	v_mfma_f32_16x16x32_bf16 v[62:65], v[144:147], v[196:199], v[62:65]
	v_mfma_f32_16x16x32_bf16 v[58:61], v[152:155], v[196:199], v[58:61]
	v_mfma_f32_16x16x32_bf16 v[54:57], v[144:147], v[204:207], v[54:57]
	v_mfma_f32_16x16x32_bf16 v[46:49], v[152:155], v[204:207], v[46:49]
	v_mfma_f32_16x16x32_bf16 v[38:41], v[144:147], v[232:235], v[38:41]
	v_mfma_f32_16x16x32_bf16 v[30:33], v[152:155], v[232:235], v[30:33]
	v_mfma_f32_16x16x32_bf16 v[22:25], v[144:147], v[240:243], v[22:25]
	v_mfma_f32_16x16x32_bf16 v[14:17], v[152:155], v[240:243], v[14:17]
	v_mfma_f32_16x16x32_bf16 v[50:53], v[156:159], v[192:195], v[50:53]
	v_mfma_f32_16x16x32_bf16 v[42:45], v[184:187], v[192:195], v[42:45]
	v_mfma_f32_16x16x32_bf16 v[34:37], v[156:159], v[200:203], v[34:37]
	v_mfma_f32_16x16x32_bf16 v[26:29], v[184:187], v[200:203], v[26:29]
	v_mfma_f32_16x16x32_bf16 v[18:21], v[156:159], v[208:211], v[18:21]
	v_mfma_f32_16x16x32_bf16 v[10:13], v[184:187], v[208:211], v[10:13]
	v_mfma_f32_16x16x32_bf16 v[6:9], v[156:159], v[236:239], v[6:9]
	v_mfma_f32_16x16x32_bf16 v[2:5], v[184:187], v[236:239], v[2:5]
	v_mfma_f32_16x16x32_bf16 v[50:53], v[180:183], v[196:199], v[50:53]
	v_mfma_f32_16x16x32_bf16 v[42:45], v[188:191], v[196:199], v[42:45]
	v_mfma_f32_16x16x32_bf16 v[34:37], v[180:183], v[204:207], v[34:37]
	v_mfma_f32_16x16x32_bf16 v[26:29], v[188:191], v[204:207], v[26:29]
	v_mfma_f32_16x16x32_bf16 v[18:21], v[180:183], v[232:235], v[18:21]
	v_mfma_f32_16x16x32_bf16 v[10:13], v[188:191], v[232:235], v[10:13]
	v_mfma_f32_16x16x32_bf16 v[6:9], v[180:183], v[240:243], v[6:9]
	v_mfma_f32_16x16x32_bf16 v[2:5], v[188:191], v[240:243], v[2:5]
	s_setprio 0
	s_barrier
	s_add_u32 s24, s24, 0x100
	s_addc_u32 s25, s25, 0
	s_add_u32 s49, s49, 0x100
	s_addc_u32 s53, s53, 0
	s_cmp_ge_u32 s54, s45
	s_mov_b32 s26, s54
	s_cbranch_scc0 .LBB0_1053
	s_and_b64 vcc, exec, s[6:7]
	s_cbranch_vccz .LBB0_1056
	s_barrier

; #define PG8_STAGE(bufoff, gbase, voff) do { _Pragma("unroll") for (int _i = 0; _i < 2; ++_i) \
;         __builtin_amdgcn_global_load_lds((const unsigned*)((const char*)(gbase) + (voff)[_i]), (PG8_LAS unsigned*)(lds + (bufoff) + ldsw + _i * 8192), 16, 0, 0); } while (0)
; #define PG8_LDA(dst, b, h) do { _Pragma("unroll") for (int m = 0; m < 4; ++m) _Pragma("unroll") for (int k = 0; k < 2; ++k) dst[m][k] = *(const PG8_LAS bf16x8*)(lds + PG8_SA(b, h) + aoff + m * 2048 + k * 1024); } while (0)
; #define PG8_LDB(dst, b, h) do { _Pragma("unroll") for (int n = 0; n < 2; ++n) _Pragma("unroll") for (int k = 0; k < 2; ++k) dst[n][k] = *(const PG8_LAS bf16x8*)(lds + PG8_SB(b, h) + boff + n * 2048 + k * 1024); } while (0)
; #define PG8_MMA(ai, bj, At, Bt) do { __builtin_amdgcn_s_setprio(1); _Pragma("unroll") for (int m = 0; m < 4; ++m) _Pragma("unroll") for (int n = 0; n < 2; ++n) _Pragma("unroll") for (int k = 0; k < 2; ++k) \
;         acc[ai][bj][m][n] = __builtin_amdgcn_mfma_f32_16x16x32_bf16(Bt[n][k], At[m][k], acc[ai][bj][m][n], 0, 0, 0); __builtin_amdgcn_s_setprio(0); } while (0)
; #define PG8_WAIT_V(n) asm volatile("s_waitcnt vmcnt(" #n ")" ::: "memory")
; #define PG8_WAIT_L(n) asm volatile("s_waitcnt lgkmcnt(" #n ")" ::: "memory")
; #define PG8_BAR __builtin_amdgcn_s_barrier()
; #define PG8_SCHED __builtin_amdgcn_sched_barrier(0)
; template <class Epi, class Sched, bool ALIGN_EPI = false, bool SP2 = false>
; __device__ __forceinline__ void gemm_phase(PG8_LAS unsigned char* lds, const Gemm g, const Sched& S, const Epi& E) {
;     ...
;         for (int t = 0; t < nt; t += 2) {
;             const bool last = (t == nt - 2);
;             const char* a1 = cA + (size_t)(t + 1) * kstep;
;             const char* a2 = last ? nA : cA + (size_t)(t + 2) * kstep; const char* b2 = last ? nB : cB + (size_t)(t + 2) * kstep;
;             const char* a3 = a2 + kstep; const char* b3 = b2 + kstep;
;             if (last && has_next) S.a_ready(nxt);
;             if constexpr (SP2) {
;             PG8_LDB(B0, 0, 0); PG8_LDB(B1, 0, 1); PG8_SCHED; PG8_LDA(At, 0, 0); PG8_STAGE(PG8_SA(1, 1), a1 + hstep, voffA);
;             PG8_WAIT_V(8); PG8_WAIT_L(0); PG8_BAR; PG8_MMA(0, 0, At, B0); PG8_MMA(0, 1, At, B1); PG8_BAR; PG8_SCHED;
;             PG8_LDA(At, 0, 1); PG8_STAGE(PG8_SB(0, 0), b2, voffB); PG8_STAGE(PG8_SB(0, 1), b2 + hstep, voffB); PG8_STAGE(PG8_SA(0, 0), a2, voffA);
.LBB0_1228:
	ds_read_b128 v[148:151], v145
	ds_read_b128 v[152:155], v145 offset:1024
	ds_read_b128 v[156:159], v145 offset:2048
	ds_read_b128 v[180:183], v145 offset:3072
	ds_read_b128 v[184:187], v146
	ds_read_b128 v[188:191], v146 offset:1024
	ds_read_b128 v[192:195], v146 offset:2048
	ds_read_b128 v[196:199], v146 offset:3072
	s_add_i32 s48, s47, 2
	s_add_u32 s24, s6, 0xfffe0080
	s_addc_u32 s25, s7, -1
	s_cmp_eq_u32 s44, s47
	s_cselect_b32 s27, s19, s25
	s_cselect_b32 s26, s42, s24
	s_cselect_b32 s25, s17, s46
	s_cselect_b32 s24, s43, s45
	v_lshl_add_u64 v[160:161], s[6:7], 0, v[134:135]
	s_add_i32 m0, s15, 0xc000
	ds_read_b128 v[200:203], v147
	ds_read_b128 v[204:207], v147 offset:1024
	ds_read_b128 v[208:211], v147 offset:2048
	ds_read_b128 v[228:231], v147 offset:3072
	ds_read_b128 v[232:235], v147 offset:4096
	ds_read_b128 v[236:239], v147 offset:5120
	ds_read_b128 v[240:243], v147 offset:6144
	ds_read_b128 v[244:247], v147 offset:7168
	global_load_lds_dwordx4 v[160:161], off
	v_lshl_add_u64 v[160:161], s[6:7], 0, v[136:137]
	s_add_i32 m0, s15, 0xe000
	s_nop 0
	global_load_lds_dwordx4 v[160:161], off
	s_waitcnt vmcnt(8)
	s_waitcnt lgkmcnt(0)
	s_barrier
	s_setprio 1
	s_waitcnt lgkmcnt(0)
	v_mfma_f32_16x16x32_bf16 v[126:129], v[148:151], v[200:203], v[126:129]
	v_mfma_f32_16x16x32_bf16 v[122:125], v[156:159], v[200:203], v[122:125]
	v_mfma_f32_16x16x32_bf16 v[118:121], v[148:151], v[208:211], v[118:121]
	v_mfma_f32_16x16x32_bf16 v[110:113], v[156:159], v[208:211], v[110:113]
	v_mfma_f32_16x16x32_bf16 v[102:105], v[148:151], v[232:235], v[102:105]
	v_mfma_f32_16x16x32_bf16 v[94:97], v[156:159], v[232:235], v[94:97]
	v_mfma_f32_16x16x32_bf16 v[86:89], v[148:151], v[240:243], v[86:89]
	v_mfma_f32_16x16x32_bf16 v[78:81], v[156:159], v[240:243], v[78:81]
	v_mfma_f32_16x16x32_bf16 v[126:129], v[152:155], v[204:207], v[126:129]
	v_mfma_f32_16x16x32_bf16 v[122:125], v[180:183], v[204:207], v[122:125]
	v_mfma_f32_16x16x32_bf16 v[118:121], v[152:155], v[228:231], v[118:121]
	v_mfma_f32_16x16x32_bf16 v[110:113], v[180:183], v[228:231], v[110:113]
	v_mfma_f32_16x16x32_bf16 v[102:105], v[152:155], v[236:239], v[102:105]
	v_mfma_f32_16x16x32_bf16 v[94:97], v[180:183], v[236:239], v[94:97]
	v_mfma_f32_16x16x32_bf16 v[86:89], v[152:155], v[244:247], v[86:89]
	v_mfma_f32_16x16x32_bf16 v[78:81], v[180:183], v[244:247], v[78:81]
	v_mfma_f32_16x16x32_bf16 v[114:117], v[184:187], v[200:203], v[114:117]
	v_mfma_f32_16x16x32_bf16 v[106:109], v[192:195], v[200:203], v[106:109]
	v_mfma_f32_16x16x32_bf16 v[98:101], v[184:187], v[208:211], v[98:101]
	v_mfma_f32_16x16x32_bf16 v[90:93], v[192:195], v[208:211], v[90:93]
	v_mfma_f32_16x16x32_bf16 v[82:85], v[184:187], v[232:235], v[82:85]
	v_mfma_f32_16x16x32_bf16 v[74:77], v[192:195], v[232:235], v[74:77]
	v_mfma_f32_16x16x32_bf16 v[70:73], v[184:187], v[240:243], v[70:73]
	v_mfma_f32_16x16x32_bf16 v[66:69], v[192:195], v[240:243], v[66:69]
	v_mfma_f32_16x16x32_bf16 v[114:117], v[188:191], v[204:207], v[114:117]
	v_mfma_f32_16x16x32_bf16 v[106:109], v[196:199], v[204:207], v[106:109]
	v_mfma_f32_16x16x32_bf16 v[98:101], v[188:191], v[228:231], v[98:101]
	v_mfma_f32_16x16x32_bf16 v[90:93], v[196:199], v[228:231], v[90:93]
	v_mfma_f32_16x16x32_bf16 v[82:85], v[188:191], v[236:239], v[82:85]
	v_mfma_f32_16x16x32_bf16 v[74:77], v[196:199], v[236:239], v[74:77]
	v_mfma_f32_16x16x32_bf16 v[70:73], v[188:191], v[244:247], v[70:73]
	v_mfma_f32_16x16x32_bf16 v[66:69], v[196:199], v[244:247], v[66:69]
	s_setprio 0
	s_barrier
	s_add_i32 s47, s37, s2
	v_lshl_add_u64 v[160:161], s[24:25], 0, v[132:133]
	s_mov_b32 m0, s47
	ds_read_b128 v[200:203], v147 offset:16384
	ds_read_b128 v[204:207], v147 offset:17408
	ds_read_b128 v[208:211], v147 offset:18432
	ds_read_b128 v[228:231], v147 offset:19456
	ds_read_b128 v[232:235], v147 offset:20480
	ds_read_b128 v[236:239], v147 offset:21504
	ds_read_b128 v[240:243], v147 offset:22528
	ds_read_b128 v[244:247], v147 offset:23552
	global_load_lds_dwordx4 v[160:161], off
	s_add_i32 m0, s47, 0x2000
	s_add_u32 s54, s24, 0x20000
	v_lshl_add_u64 v[212:213], s[24:25], 0, v[130:131]
	s_addc_u32 s55, s25, 0
	s_add_i32 s47, s38, s2
	global_load_lds_dwordx4 v[212:213], off
	v_lshl_add_u64 v[222:223], s[54:55], 0, v[132:133]
	s_mov_b32 m0, s47
	v_lshl_add_u64 v[248:249], s[26:27], 0, v[130:131]
	global_load_lds_dwordx4 v[222:223], off
	v_lshl_add_u64 v[222:223], s[54:55], 0, v[130:131]
	s_add_i32 m0, s47, 0x2000
	s_nop 0
	global_load_lds_dwordx4 v[222:223], off
	v_lshl_add_u64 v[222:223], s[26:27], 0, v[132:133]
	s_mov_b32 m0, s15
	s_nop 0
	global_load_lds_dwordx4 v[222:223], off
	s_mov_b32 m0, s29
	s_nop 0
	global_load_lds_dwordx4 v[248:249], off
	s_waitcnt vmcnt(8)
	s_waitcnt lgkmcnt(0)
	s_barrier
; #define PG8_STAGE(bufoff, gbase, voff) do { _Pragma("unroll") for (int _i = 0; _i < 2; ++_i) \
;         __builtin_amdgcn_global_load_lds((const unsigned*)((const char*)(gbase) + (voff)[_i]), (PG8_LAS unsigned*)(lds + (bufoff) + ldsw + _i * 8192), 16, 0, 0); } while (0)
; #define PG8_LDA(dst, b, h) do { _Pragma("unroll") for (int m = 0; m < 4; ++m) _Pragma("unroll") for (int k = 0; k < 2; ++k) dst[m][k] = *(const PG8_LAS bf16x8*)(lds + PG8_SA(b, h) + aoff + m * 2048 + k * 1024); } while (0)
; #define PG8_LDB(dst, b, h) do { _Pragma("unroll") for (int n = 0; n < 2; ++n) _Pragma("unroll") for (int k = 0; k < 2; ++k) dst[n][k] = *(const PG8_LAS bf16x8*)(lds + PG8_SB(b, h) + boff + n * 2048 + k * 1024); } while (0)
; #define PG8_MMA(ai, bj, At, Bt) do { __builtin_amdgcn_s_setprio(1); _Pragma("unroll") for (int m = 0; m < 4; ++m) _Pragma("unroll") for (int n = 0; n < 2; ++n) _Pragma("unroll") for (int k = 0; k < 2; ++k) \
;         acc[ai][bj][m][n] = __builtin_amdgcn_mfma_f32_16x16x32_bf16(Bt[n][k], At[m][k], acc[ai][bj][m][n], 0, 0, 0); __builtin_amdgcn_s_setprio(0); } while (0)
; #define PG8_WAIT_V(n) asm volatile("s_waitcnt vmcnt(" #n ")" ::: "memory")
; #define PG8_WAIT_L(n) asm volatile("s_waitcnt lgkmcnt(" #n ")" ::: "memory")
; #define PG8_BAR __builtin_amdgcn_s_barrier()
; #define PG8_SCHED __builtin_amdgcn_sched_barrier(0)
; template <class Epi, class Sched, bool ALIGN_EPI = false, bool SP2 = false>
; __device__ __forceinline__ void gemm_phase(PG8_LAS unsigned char* lds, const Gemm g, const Sched& S, const Epi& E) {
;     ...
;             PG8_WAIT_V(8); PG8_WAIT_L(0); PG8_BAR; PG8_MMA(1, 0, At, B0); PG8_MMA(1, 1, At, B1); PG8_BAR; PG8_SCHED;
;             PG8_LDB(B0, 1, 0); PG8_LDB(B1, 1, 1); PG8_SCHED; PG8_LDA(At, 1, 0); PG8_STAGE(PG8_SA(0, 1), a2 + hstep, voffA);
;             PG8_WAIT_V(8); PG8_WAIT_L(0); PG8_BAR; PG8_MMA(0, 0, At, B0); PG8_MMA(0, 1, At, B1); PG8_BAR; PG8_SCHED;
	s_setprio 1
	s_waitcnt lgkmcnt(0)
	v_mfma_f32_16x16x32_bf16 v[62:65], v[148:151], v[200:203], v[62:65]
	v_mfma_f32_16x16x32_bf16 v[58:61], v[156:159], v[200:203], v[58:61]
	v_mfma_f32_16x16x32_bf16 v[54:57], v[148:151], v[208:211], v[54:57]
	v_mfma_f32_16x16x32_bf16 v[46:49], v[156:159], v[208:211], v[46:49]
	v_mfma_f32_16x16x32_bf16 v[38:41], v[148:151], v[232:235], v[38:41]
	v_mfma_f32_16x16x32_bf16 v[30:33], v[156:159], v[232:235], v[30:33]
	v_mfma_f32_16x16x32_bf16 v[22:25], v[148:151], v[240:243], v[22:25]
	v_mfma_f32_16x16x32_bf16 v[14:17], v[156:159], v[240:243], v[14:17]
	v_mfma_f32_16x16x32_bf16 v[62:65], v[152:155], v[204:207], v[62:65]
	v_mfma_f32_16x16x32_bf16 v[58:61], v[180:183], v[204:207], v[58:61]
	v_mfma_f32_16x16x32_bf16 v[54:57], v[152:155], v[228:231], v[54:57]
	v_mfma_f32_16x16x32_bf16 v[46:49], v[180:183], v[228:231], v[46:49]
	v_mfma_f32_16x16x32_bf16 v[38:41], v[152:155], v[236:239], v[38:41]
	v_mfma_f32_16x16x32_bf16 v[30:33], v[180:183], v[236:239], v[30:33]
	v_mfma_f32_16x16x32_bf16 v[22:25], v[152:155], v[244:247], v[22:25]
	v_mfma_f32_16x16x32_bf16 v[14:17], v[180:183], v[244:247], v[14:17]
	v_mfma_f32_16x16x32_bf16 v[50:53], v[184:187], v[200:203], v[50:53]
	v_mfma_f32_16x16x32_bf16 v[42:45], v[192:195], v[200:203], v[42:45]
	v_mfma_f32_16x16x32_bf16 v[34:37], v[184:187], v[208:211], v[34:37]
	v_mfma_f32_16x16x32_bf16 v[26:29], v[192:195], v[208:211], v[26:29]
	v_mfma_f32_16x16x32_bf16 v[18:21], v[184:187], v[232:235], v[18:21]
	v_mfma_f32_16x16x32_bf16 v[10:13], v[192:195], v[232:235], v[10:13]
	v_mfma_f32_16x16x32_bf16 v[6:9], v[184:187], v[240:243], v[6:9]
	v_mfma_f32_16x16x32_bf16 v[2:5], v[192:195], v[240:243], v[2:5]
	v_mfma_f32_16x16x32_bf16 v[50:53], v[188:191], v[204:207], v[50:53]
	v_mfma_f32_16x16x32_bf16 v[42:45], v[196:199], v[204:207], v[42:45]
	v_mfma_f32_16x16x32_bf16 v[34:37], v[188:191], v[228:231], v[34:37]
	v_mfma_f32_16x16x32_bf16 v[26:29], v[196:199], v[228:231], v[26:29]
	v_mfma_f32_16x16x32_bf16 v[18:21], v[188:191], v[236:239], v[18:21]
	v_mfma_f32_16x16x32_bf16 v[10:13], v[196:199], v[236:239], v[10:13]
	v_mfma_f32_16x16x32_bf16 v[6:9], v[188:191], v[244:247], v[6:9]
	v_mfma_f32_16x16x32_bf16 v[2:5], v[196:199], v[244:247], v[2:5]
	s_setprio 0
	s_barrier
	s_add_i32 s47, 0, 0x18000
	v_add_u32_e32 v167, s47, v143
	s_add_i32 s49, 0, 0x1c000
	ds_read_b128 v[148:151], v167
	ds_read_b128 v[152:155], v167 offset:1024
	ds_read_b128 v[156:159], v167 offset:2048
	ds_read_b128 v[180:183], v167 offset:3072
	v_add_u32_e32 v167, s49, v143
	ds_read_b128 v[184:187], v167
	ds_read_b128 v[188:191], v167 offset:1024
	ds_read_b128 v[192:195], v167 offset:2048
	ds_read_b128 v[196:199], v167 offset:3072
	s_add_u32 s26, s26, 0x20000
	s_addc_u32 s27, s27, 0
	s_mov_b32 m0, s30
	v_lshl_add_u64 v[250:251], s[26:27], 0, v[132:133]
	ds_read_b128 v[200:203], v147 offset:32768
	ds_read_b128 v[204:207], v147 offset:33792
	ds_read_b128 v[208:211], v147 offset:34816
	ds_read_b128 v[228:231], v147 offset:35840
	ds_read_b128 v[232:235], v147 offset:36864
	ds_read_b128 v[236:239], v147 offset:37888
	ds_read_b128 v[240:243], v147 offset:38912
	ds_read_b128 v[244:247], v147 offset:39936
	global_load_lds_dwordx4 v[250:251], off
	v_lshl_add_u64 v[250:251], s[26:27], 0, v[130:131]
	s_mov_b32 m0, s31
	s_nop 0
	global_load_lds_dwordx4 v[250:251], off
	s_waitcnt vmcnt(8)
	s_waitcnt lgkmcnt(0)
	s_barrier
	s_setprio 1
	s_waitcnt lgkmcnt(0)
	v_mfma_f32_16x16x32_bf16 v[126:129], v[148:151], v[200:203], v[126:129]
	v_mfma_f32_16x16x32_bf16 v[122:125], v[156:159], v[200:203], v[122:125]
	v_mfma_f32_16x16x32_bf16 v[118:121], v[148:151], v[208:211], v[118:121]
	v_mfma_f32_16x16x32_bf16 v[110:113], v[156:159], v[208:211], v[110:113]
	v_mfma_f32_16x16x32_bf16 v[102:105], v[148:151], v[232:235], v[102:105]
	v_mfma_f32_16x16x32_bf16 v[94:97], v[156:159], v[232:235], v[94:97]
	v_mfma_f32_16x16x32_bf16 v[86:89], v[148:151], v[240:243], v[86:89]
	v_mfma_f32_16x16x32_bf16 v[78:81], v[156:159], v[240:243], v[78:81]
	v_mfma_f32_16x16x32_bf16 v[126:129], v[152:155], v[204:207], v[126:129]
	v_mfma_f32_16x16x32_bf16 v[122:125], v[180:183], v[204:207], v[122:125]
	v_mfma_f32_16x16x32_bf16 v[118:121], v[152:155], v[228:231], v[118:121]
	v_mfma_f32_16x16x32_bf16 v[110:113], v[180:183], v[228:231], v[110:113]
	v_mfma_f32_16x16x32_bf16 v[102:105], v[152:155], v[236:239], v[102:105]
	v_mfma_f32_16x16x32_bf16 v[94:97], v[180:183], v[236:239], v[94:97]
	v_mfma_f32_16x16x32_bf16 v[86:89], v[152:155], v[244:247], v[86:89]
	v_mfma_f32_16x16x32_bf16 v[78:81], v[180:183], v[244:247], v[78:81]
	v_mfma_f32_16x16x32_bf16 v[114:117], v[184:187], v[200:203], v[114:117]
	v_mfma_f32_16x16x32_bf16 v[106:109], v[192:195], v[200:203], v[106:109]
	v_mfma_f32_16x16x32_bf16 v[98:101], v[184:187], v[208:211], v[98:101]
	v_mfma_f32_16x16x32_bf16 v[90:93], v[192:195], v[208:211], v[90:93]
	v_mfma_f32_16x16x32_bf16 v[82:85], v[184:187], v[232:235], v[82:85]
	v_mfma_f32_16x16x32_bf16 v[74:77], v[192:195], v[232:235], v[74:77]
	v_mfma_f32_16x16x32_bf16 v[70:73], v[184:187], v[240:243], v[70:73]
	v_mfma_f32_16x16x32_bf16 v[66:69], v[192:195], v[240:243], v[66:69]
	v_mfma_f32_16x16x32_bf16 v[114:117], v[188:191], v[204:207], v[114:117]
	v_mfma_f32_16x16x32_bf16 v[106:109], v[196:199], v[204:207], v[106:109]
	v_mfma_f32_16x16x32_bf16 v[98:101], v[188:191], v[228:231], v[98:101]
	v_mfma_f32_16x16x32_bf16 v[90:93], v[196:199], v[228:231], v[90:93]
	v_mfma_f32_16x16x32_bf16 v[82:85], v[188:191], v[236:239], v[82:85]
	v_mfma_f32_16x16x32_bf16 v[74:77], v[196:199], v[236:239], v[74:77]
	v_mfma_f32_16x16x32_bf16 v[70:73], v[188:191], v[244:247], v[70:73]
	v_mfma_f32_16x16x32_bf16 v[66:69], v[196:199], v[244:247], v[66:69]
	s_setprio 0
	s_barrier
; #define PG8_STAGE(bufoff, gbase, voff) do { _Pragma("unroll") for (int _i = 0; _i < 2; ++_i) \
;         __builtin_amdgcn_global_load_lds((const unsigned*)((const char*)(gbase) + (voff)[_i]), (PG8_LAS unsigned*)(lds + (bufoff) + ldsw + _i * 8192), 16, 0, 0); } while (0)
; #define PG8_LDA(dst, b, h) do { _Pragma("unroll") for (int m = 0; m < 4; ++m) _Pragma("unroll") for (int k = 0; k < 2; ++k) dst[m][k] = *(const PG8_LAS bf16x8*)(lds + PG8_SA(b, h) + aoff + m * 2048 + k * 1024); } while (0)
; #define PG8_MMA(ai, bj, At, Bt) do { __builtin_amdgcn_s_setprio(1); _Pragma("unroll") for (int m = 0; m < 4; ++m) _Pragma("unroll") for (int n = 0; n < 2; ++n) _Pragma("unroll") for (int k = 0; k < 2; ++k) \
;         acc[ai][bj][m][n] = __builtin_amdgcn_mfma_f32_16x16x32_bf16(Bt[n][k], At[m][k], acc[ai][bj][m][n], 0, 0, 0); __builtin_amdgcn_s_setprio(0); } while (0)
; #define PG8_WAIT_V(n) asm volatile("s_waitcnt vmcnt(" #n ")" ::: "memory")
; #define PG8_WAIT_L(n) asm volatile("s_waitcnt lgkmcnt(" #n ")" ::: "memory")
; #define PG8_BAR __builtin_amdgcn_s_barrier()
; #define PG8_SCHED __builtin_amdgcn_sched_barrier(0)
; template <class Epi, class Sched, bool ALIGN_EPI = false, bool SP2 = false>
; __device__ __forceinline__ void gemm_phase(PG8_LAS unsigned char* lds, const Gemm g, const Sched& S, const Epi& E) {
;     ...
;             PG8_LDA(At, 1, 1); PG8_STAGE(PG8_SB(1, 0), b3, voffB); PG8_STAGE(PG8_SB(1, 1), b3 + hstep, voffB); PG8_STAGE(PG8_SA(1, 0), a3, voffA);
;             PG8_WAIT_V(8); PG8_WAIT_L(0); PG8_BAR; PG8_MMA(1, 0, At, B0); PG8_MMA(1, 1, At, B1); PG8_BAR; PG8_SCHED;
;     ...
;         }
;         if constexpr (ALIGN_EPI) { if (wr == 0) PG8_BAR; }
	s_add_i32 s26, s47, s2
	v_lshl_add_u64 v[160:161], v[160:161], 0, s[8:9]
	s_mov_b32 m0, s26
	ds_read_b128 v[200:203], v147 offset:49152
	ds_read_b128 v[204:207], v147 offset:50176
	ds_read_b128 v[208:211], v147 offset:51200
	ds_read_b128 v[228:231], v147 offset:52224
	ds_read_b128 v[232:235], v147 offset:53248
	ds_read_b128 v[236:239], v147 offset:54272
	ds_read_b128 v[240:243], v147 offset:55296
	ds_read_b128 v[244:247], v147 offset:56320
	global_load_lds_dwordx4 v[160:161], off
	s_add_i32 m0, s26, 0x2000
	s_add_u32 s24, s24, 0x20080
	v_lshl_add_u64 v[160:161], v[212:213], 0, s[8:9]
	s_addc_u32 s25, s25, 0
	s_add_i32 s26, s49, s2
	global_load_lds_dwordx4 v[160:161], off
	v_lshl_add_u64 v[160:161], s[24:25], 0, v[132:133]
	s_mov_b32 m0, s26
	s_nop 0
	global_load_lds_dwordx4 v[160:161], off
	v_lshl_add_u64 v[160:161], s[24:25], 0, v[130:131]
	s_add_i32 m0, s26, 0x2000
	s_nop 0
	global_load_lds_dwordx4 v[160:161], off
	v_lshl_add_u64 v[160:161], v[222:223], 0, s[8:9]
	s_mov_b32 m0, s34
	s_nop 0
	global_load_lds_dwordx4 v[160:161], off
	v_lshl_add_u64 v[160:161], v[248:249], 0, s[8:9]
	s_mov_b32 m0, s35
	s_nop 0
	global_load_lds_dwordx4 v[160:161], off
	s_waitcnt vmcnt(8)
	s_waitcnt lgkmcnt(0)
	s_barrier
	s_setprio 1
	s_waitcnt lgkmcnt(0)
	v_mfma_f32_16x16x32_bf16 v[62:65], v[148:151], v[200:203], v[62:65]
	v_mfma_f32_16x16x32_bf16 v[58:61], v[156:159], v[200:203], v[58:61]
	v_mfma_f32_16x16x32_bf16 v[54:57], v[148:151], v[208:211], v[54:57]
	v_mfma_f32_16x16x32_bf16 v[46:49], v[156:159], v[208:211], v[46:49]
	v_mfma_f32_16x16x32_bf16 v[38:41], v[148:151], v[232:235], v[38:41]
	v_mfma_f32_16x16x32_bf16 v[30:33], v[156:159], v[232:235], v[30:33]
	v_mfma_f32_16x16x32_bf16 v[22:25], v[148:151], v[240:243], v[22:25]
	v_mfma_f32_16x16x32_bf16 v[14:17], v[156:159], v[240:243], v[14:17]
	v_mfma_f32_16x16x32_bf16 v[62:65], v[152:155], v[204:207], v[62:65]
	v_mfma_f32_16x16x32_bf16 v[58:61], v[180:183], v[204:207], v[58:61]
	v_mfma_f32_16x16x32_bf16 v[54:57], v[152:155], v[228:231], v[54:57]
	v_mfma_f32_16x16x32_bf16 v[46:49], v[180:183], v[228:231], v[46:49]
	v_mfma_f32_16x16x32_bf16 v[38:41], v[152:155], v[236:239], v[38:41]
	v_mfma_f32_16x16x32_bf16 v[30:33], v[180:183], v[236:239], v[30:33]
	v_mfma_f32_16x16x32_bf16 v[22:25], v[152:155], v[244:247], v[22:25]
	v_mfma_f32_16x16x32_bf16 v[14:17], v[180:183], v[244:247], v[14:17]
	v_mfma_f32_16x16x32_bf16 v[50:53], v[184:187], v[200:203], v[50:53]
	v_mfma_f32_16x16x32_bf16 v[42:45], v[192:195], v[200:203], v[42:45]
	v_mfma_f32_16x16x32_bf16 v[34:37], v[184:187], v[208:211], v[34:37]
	v_mfma_f32_16x16x32_bf16 v[26:29], v[192:195], v[208:211], v[26:29]
	v_mfma_f32_16x16x32_bf16 v[18:21], v[184:187], v[232:235], v[18:21]
	v_mfma_f32_16x16x32_bf16 v[10:13], v[192:195], v[232:235], v[10:13]
	v_mfma_f32_16x16x32_bf16 v[6:9], v[184:187], v[240:243], v[6:9]
	v_mfma_f32_16x16x32_bf16 v[2:5], v[192:195], v[240:243], v[2:5]
	v_mfma_f32_16x16x32_bf16 v[50:53], v[188:191], v[204:207], v[50:53]
	v_mfma_f32_16x16x32_bf16 v[42:45], v[196:199], v[204:207], v[42:45]
	v_mfma_f32_16x16x32_bf16 v[34:37], v[188:191], v[228:231], v[34:37]
	v_mfma_f32_16x16x32_bf16 v[26:29], v[196:199], v[228:231], v[26:29]
	v_mfma_f32_16x16x32_bf16 v[18:21], v[188:191], v[236:239], v[18:21]
	v_mfma_f32_16x16x32_bf16 v[10:13], v[196:199], v[236:239], v[10:13]
	v_mfma_f32_16x16x32_bf16 v[6:9], v[188:191], v[244:247], v[6:9]
	v_mfma_f32_16x16x32_bf16 v[2:5], v[196:199], v[244:247], v[2:5]
	s_setprio 0
	s_barrier
	s_add_u32 s6, s6, 0x100
	s_addc_u32 s7, s7, 0
	s_add_u32 s45, s45, 0x100
	s_addc_u32 s46, s46, 0
	s_cmp_ge_u32 s48, s40
	s_mov_b32 s47, s48
	s_cbranch_scc0 .LBB0_1228
	s_and_b64 vcc, exec, s[10:11]
	s_cbranch_vccz .LBB0_1231
	s_barrier

; #define PG8_STAGE(bufoff, gbase, voff) do { _Pragma("unroll") for (int _i = 0; _i < 2; ++_i) \
;         __builtin_amdgcn_global_load_lds((const unsigned*)((const char*)(gbase) + (voff)[_i]), (PG8_LAS unsigned*)(lds + (bufoff) + ldsw + _i * 8192), 16, 0, 0); } while (0)
; #define PG8_LDA(dst, b, h) do { _Pragma("unroll") for (int m = 0; m < 4; ++m) _Pragma("unroll") for (int k = 0; k < 2; ++k) dst[m][k] = *(const PG8_LAS bf16x8*)(lds + PG8_SA(b, h) + aoff + m * 2048 + k * 1024); } while (0)
; #define PG8_LDB(dst, b, h) do { _Pragma("unroll") for (int n = 0; n < 2; ++n) _Pragma("unroll") for (int k = 0; k < 2; ++k) dst[n][k] = *(const PG8_LAS bf16x8*)(lds + PG8_SB(b, h) + boff + n * 2048 + k * 1024); } while (0)
; #define PG8_MMA(ai, bj, At, Bt) do { __builtin_amdgcn_s_setprio(1); _Pragma("unroll") for (int m = 0; m < 4; ++m) _Pragma("unroll") for (int n = 0; n < 2; ++n) _Pragma("unroll") for (int k = 0; k < 2; ++k) \
;         acc[ai][bj][m][n] = __builtin_amdgcn_mfma_f32_16x16x32_bf16(Bt[n][k], At[m][k], acc[ai][bj][m][n], 0, 0, 0); __builtin_amdgcn_s_setprio(0); } while (0)
; #define PG8_WAIT_V(n) asm volatile("s_waitcnt vmcnt(" #n ")" ::: "memory")
; #define PG8_WAIT_L(n) asm volatile("s_waitcnt lgkmcnt(" #n ")" ::: "memory")
; #define PG8_BAR __builtin_amdgcn_s_barrier()
; #define PG8_SCHED __builtin_amdgcn_sched_barrier(0)
; template <class Epi, class Sched, bool ALIGN_EPI = false, bool SP2 = false>
; __device__ __forceinline__ void gemm_phase(PG8_LAS unsigned char* lds, const Gemm g, const Sched& S, const Epi& E) {
;     ...
;         for (int t = 0; t < nt; t += 2) {
;             const bool last = (t == nt - 2);
;             const char* a1 = cA + (size_t)(t + 1) * kstep;
;             const char* a2 = last ? nA : cA + (size_t)(t + 2) * kstep; const char* b2 = last ? nB : cB + (size_t)(t + 2) * kstep;
;             const char* a3 = a2 + kstep; const char* b3 = b2 + kstep;
;             if (last && has_next) S.a_ready(nxt);
;             if constexpr (SP2) {
;             PG8_LDB(B0, 0, 0); PG8_LDB(B1, 0, 1); PG8_SCHED; PG8_LDA(At, 0, 0); PG8_STAGE(PG8_SA(1, 1), a1 + hstep, voffA);
;             PG8_WAIT_V(8); PG8_WAIT_L(0); PG8_BAR; PG8_MMA(0, 0, At, B0); PG8_MMA(0, 1, At, B1); PG8_BAR; PG8_SCHED;
;             PG8_LDA(At, 0, 1); PG8_STAGE(PG8_SB(0, 0), b2, voffB); PG8_STAGE(PG8_SB(0, 1), b2 + hstep, voffB); PG8_STAGE(PG8_SA(0, 0), a2, voffA);
.LBB0_1373:
	ds_read_b128 v[146:149], v143
	ds_read_b128 v[150:153], v143 offset:1024
	ds_read_b128 v[154:157], v143 offset:2048
	ds_read_b128 v[158:161], v143 offset:3072
	ds_read_b128 v[178:181], v144
	ds_read_b128 v[182:185], v144 offset:1024
	ds_read_b128 v[186:189], v144 offset:2048
	ds_read_b128 v[190:193], v144 offset:3072
	s_add_i32 s47, s46, 2
	s_add_u32 s22, s0, 0xfff80080
	s_addc_u32 s23, s1, -1
	s_cmp_eq_u32 s43, s46
	s_cselect_b32 s25, s15, s23
	s_cselect_b32 s24, s41, s22
	s_cselect_b32 s23, s13, s45
	s_cselect_b32 s22, s42, s44
	v_lshl_add_u64 v[138:139], s[0:1], 0, v[130:131]
	s_add_i32 m0, s21, 0xc000
	ds_read_b128 v[194:197], v145
	ds_read_b128 v[198:201], v145 offset:1024
	ds_read_b128 v[202:205], v145 offset:2048
	ds_read_b128 v[206:209], v145 offset:3072
	ds_read_b128 v[210:213], v145 offset:4096
	ds_read_b128 v[218:221], v145 offset:5120
	ds_read_b128 v[228:231], v145 offset:6144
	ds_read_b128 v[232:235], v145 offset:7168
	global_load_lds_dwordx4 v[138:139], off
	v_lshl_add_u64 v[138:139], s[0:1], 0, v[132:133]
	s_add_i32 m0, s21, 0xe000
	s_nop 0
	global_load_lds_dwordx4 v[138:139], off
	s_waitcnt vmcnt(8)
	s_waitcnt lgkmcnt(0)
	s_barrier
	s_setprio 1
	s_waitcnt lgkmcnt(0)
	v_mfma_f32_16x16x32_bf16 v[126:129], v[146:149], v[194:197], v[126:129]
	v_mfma_f32_16x16x32_bf16 v[122:125], v[154:157], v[194:197], v[122:125]
	v_mfma_f32_16x16x32_bf16 v[110:113], v[146:149], v[202:205], v[110:113]
	v_mfma_f32_16x16x32_bf16 v[106:109], v[154:157], v[202:205], v[106:109]
	v_mfma_f32_16x16x32_bf16 v[94:97], v[146:149], v[210:213], v[94:97]
	v_mfma_f32_16x16x32_bf16 v[90:93], v[154:157], v[210:213], v[90:93]
	v_mfma_f32_16x16x32_bf16 v[78:81], v[146:149], v[228:231], v[78:81]
	v_mfma_f32_16x16x32_bf16 v[74:77], v[154:157], v[228:231], v[74:77]
	v_mfma_f32_16x16x32_bf16 v[126:129], v[150:153], v[198:201], v[126:129]
	v_mfma_f32_16x16x32_bf16 v[122:125], v[158:161], v[198:201], v[122:125]
	v_mfma_f32_16x16x32_bf16 v[110:113], v[150:153], v[206:209], v[110:113]
	v_mfma_f32_16x16x32_bf16 v[106:109], v[158:161], v[206:209], v[106:109]
	v_mfma_f32_16x16x32_bf16 v[94:97], v[150:153], v[218:221], v[94:97]
	v_mfma_f32_16x16x32_bf16 v[90:93], v[158:161], v[218:221], v[90:93]
	v_mfma_f32_16x16x32_bf16 v[78:81], v[150:153], v[232:235], v[78:81]
	v_mfma_f32_16x16x32_bf16 v[74:77], v[158:161], v[232:235], v[74:77]
	v_mfma_f32_16x16x32_bf16 v[118:121], v[178:181], v[194:197], v[118:121]
	v_mfma_f32_16x16x32_bf16 v[114:117], v[186:189], v[194:197], v[114:117]
	v_mfma_f32_16x16x32_bf16 v[102:105], v[178:181], v[202:205], v[102:105]
	v_mfma_f32_16x16x32_bf16 v[98:101], v[186:189], v[202:205], v[98:101]
	v_mfma_f32_16x16x32_bf16 v[86:89], v[178:181], v[210:213], v[86:89]
	v_mfma_f32_16x16x32_bf16 v[82:85], v[186:189], v[210:213], v[82:85]
	v_mfma_f32_16x16x32_bf16 v[70:73], v[178:181], v[228:231], v[70:73]
	v_mfma_f32_16x16x32_bf16 v[66:69], v[186:189], v[228:231], v[66:69]
	v_mfma_f32_16x16x32_bf16 v[118:121], v[182:185], v[198:201], v[118:121]
	v_mfma_f32_16x16x32_bf16 v[114:117], v[190:193], v[198:201], v[114:117]
	v_mfma_f32_16x16x32_bf16 v[102:105], v[182:185], v[206:209], v[102:105]
	v_mfma_f32_16x16x32_bf16 v[98:101], v[190:193], v[206:209], v[98:101]
	v_mfma_f32_16x16x32_bf16 v[86:89], v[182:185], v[218:221], v[86:89]
	v_mfma_f32_16x16x32_bf16 v[82:85], v[190:193], v[218:221], v[82:85]
	v_mfma_f32_16x16x32_bf16 v[70:73], v[182:185], v[232:235], v[70:73]
	v_mfma_f32_16x16x32_bf16 v[66:69], v[190:193], v[232:235], v[66:69]
	s_setprio 0
	s_barrier
	s_add_i32 s46, s35, s2
	v_lshl_add_u64 v[138:139], s[22:23], 0, v[168:169]
	s_mov_b32 m0, s46
	ds_read_b128 v[194:197], v145 offset:16384
	ds_read_b128 v[198:201], v145 offset:17408
	ds_read_b128 v[202:205], v145 offset:18432
	ds_read_b128 v[206:209], v145 offset:19456
	ds_read_b128 v[210:213], v145 offset:20480
	ds_read_b128 v[218:221], v145 offset:21504
	ds_read_b128 v[228:231], v145 offset:22528
	ds_read_b128 v[232:235], v145 offset:23552
	global_load_lds_dwordx4 v[138:139], off
	s_add_i32 m0, s46, 0x2000
	s_add_u32 s48, s22, 0x80000
	v_lshl_add_u64 v[222:223], s[22:23], 0, v[172:173]
	s_addc_u32 s49, s23, 0
	s_add_i32 s46, s36, s2
	global_load_lds_dwordx4 v[222:223], off
	v_lshl_add_u64 v[236:237], s[48:49], 0, v[168:169]
	s_mov_b32 m0, s46
	v_lshl_add_u64 v[238:239], s[24:25], 0, v[170:171]
	global_load_lds_dwordx4 v[236:237], off
	v_lshl_add_u64 v[236:237], s[48:49], 0, v[172:173]
	s_add_i32 m0, s46, 0x2000
	s_nop 0
	global_load_lds_dwordx4 v[236:237], off
	v_lshl_add_u64 v[236:237], s[24:25], 0, v[166:167]
	s_mov_b32 m0, s21
	s_nop 0
	global_load_lds_dwordx4 v[236:237], off
	s_mov_b32 m0, s27
	s_nop 0
	global_load_lds_dwordx4 v[238:239], off
	s_waitcnt vmcnt(8)
	s_waitcnt lgkmcnt(0)
	s_barrier
; #define PG8_STAGE(bufoff, gbase, voff) do { _Pragma("unroll") for (int _i = 0; _i < 2; ++_i) \
;         __builtin_amdgcn_global_load_lds((const unsigned*)((const char*)(gbase) + (voff)[_i]), (PG8_LAS unsigned*)(lds + (bufoff) + ldsw + _i * 8192), 16, 0, 0); } while (0)
; #define PG8_LDA(dst, b, h) do { _Pragma("unroll") for (int m = 0; m < 4; ++m) _Pragma("unroll") for (int k = 0; k < 2; ++k) dst[m][k] = *(const PG8_LAS bf16x8*)(lds + PG8_SA(b, h) + aoff + m * 2048 + k * 1024); } while (0)
; #define PG8_LDB(dst, b, h) do { _Pragma("unroll") for (int n = 0; n < 2; ++n) _Pragma("unroll") for (int k = 0; k < 2; ++k) dst[n][k] = *(const PG8_LAS bf16x8*)(lds + PG8_SB(b, h) + boff + n * 2048 + k * 1024); } while (0)
; #define PG8_MMA(ai, bj, At, Bt) do { __builtin_amdgcn_s_setprio(1); _Pragma("unroll") for (int m = 0; m < 4; ++m) _Pragma("unroll") for (int n = 0; n < 2; ++n) _Pragma("unroll") for (int k = 0; k < 2; ++k) \
;         acc[ai][bj][m][n] = __builtin_amdgcn_mfma_f32_16x16x32_bf16(Bt[n][k], At[m][k], acc[ai][bj][m][n], 0, 0, 0); __builtin_amdgcn_s_setprio(0); } while (0)
; #define PG8_WAIT_V(n) asm volatile("s_waitcnt vmcnt(" #n ")" ::: "memory")
; #define PG8_WAIT_L(n) asm volatile("s_waitcnt lgkmcnt(" #n ")" ::: "memory")
; #define PG8_BAR __builtin_amdgcn_s_barrier()
; #define PG8_SCHED __builtin_amdgcn_sched_barrier(0)
; template <class Epi, class Sched, bool ALIGN_EPI = false, bool SP2 = false>
; __device__ __forceinline__ void gemm_phase(PG8_LAS unsigned char* lds, const Gemm g, const Sched& S, const Epi& E) {
;     ...
;             PG8_WAIT_V(8); PG8_WAIT_L(0); PG8_BAR; PG8_MMA(1, 0, At, B0); PG8_MMA(1, 1, At, B1); PG8_BAR; PG8_SCHED;
;             PG8_LDB(B0, 1, 0); PG8_LDB(B1, 1, 1); PG8_SCHED; PG8_LDA(At, 1, 0); PG8_STAGE(PG8_SA(0, 1), a2 + hstep, voffA);
;             PG8_WAIT_V(8); PG8_WAIT_L(0); PG8_BAR; PG8_MMA(0, 0, At, B0); PG8_MMA(0, 1, At, B1); PG8_BAR; PG8_SCHED;
	s_setprio 1
	s_waitcnt lgkmcnt(0)
	v_mfma_f32_16x16x32_bf16 v[62:65], v[146:149], v[194:197], v[62:65]
	v_mfma_f32_16x16x32_bf16 v[58:61], v[154:157], v[194:197], v[58:61]
	v_mfma_f32_16x16x32_bf16 v[46:49], v[146:149], v[202:205], v[46:49]
	v_mfma_f32_16x16x32_bf16 v[42:45], v[154:157], v[202:205], v[42:45]
	v_mfma_f32_16x16x32_bf16 v[30:33], v[146:149], v[210:213], v[30:33]
	v_mfma_f32_16x16x32_bf16 v[26:29], v[154:157], v[210:213], v[26:29]
	v_mfma_f32_16x16x32_bf16 v[14:17], v[146:149], v[228:231], v[14:17]
	v_mfma_f32_16x16x32_bf16 v[10:13], v[154:157], v[228:231], v[10:13]
	v_mfma_f32_16x16x32_bf16 v[62:65], v[150:153], v[198:201], v[62:65]
	v_mfma_f32_16x16x32_bf16 v[58:61], v[158:161], v[198:201], v[58:61]
	v_mfma_f32_16x16x32_bf16 v[46:49], v[150:153], v[206:209], v[46:49]
	v_mfma_f32_16x16x32_bf16 v[42:45], v[158:161], v[206:209], v[42:45]
	v_mfma_f32_16x16x32_bf16 v[30:33], v[150:153], v[218:221], v[30:33]
	v_mfma_f32_16x16x32_bf16 v[26:29], v[158:161], v[218:221], v[26:29]
	v_mfma_f32_16x16x32_bf16 v[14:17], v[150:153], v[232:235], v[14:17]
	v_mfma_f32_16x16x32_bf16 v[10:13], v[158:161], v[232:235], v[10:13]
	v_mfma_f32_16x16x32_bf16 v[54:57], v[178:181], v[194:197], v[54:57]
	v_mfma_f32_16x16x32_bf16 v[50:53], v[186:189], v[194:197], v[50:53]
	v_mfma_f32_16x16x32_bf16 v[38:41], v[178:181], v[202:205], v[38:41]
	v_mfma_f32_16x16x32_bf16 v[34:37], v[186:189], v[202:205], v[34:37]
	v_mfma_f32_16x16x32_bf16 v[22:25], v[178:181], v[210:213], v[22:25]
	v_mfma_f32_16x16x32_bf16 v[18:21], v[186:189], v[210:213], v[18:21]
	v_mfma_f32_16x16x32_bf16 v[6:9], v[178:181], v[228:231], v[6:9]
	v_mfma_f32_16x16x32_bf16 v[2:5], v[186:189], v[228:231], v[2:5]
	v_mfma_f32_16x16x32_bf16 v[54:57], v[182:185], v[198:201], v[54:57]
	v_mfma_f32_16x16x32_bf16 v[50:53], v[190:193], v[198:201], v[50:53]
	v_mfma_f32_16x16x32_bf16 v[38:41], v[182:185], v[206:209], v[38:41]
	v_mfma_f32_16x16x32_bf16 v[34:37], v[190:193], v[206:209], v[34:37]
	v_mfma_f32_16x16x32_bf16 v[22:25], v[182:185], v[218:221], v[22:25]
	v_mfma_f32_16x16x32_bf16 v[18:21], v[190:193], v[218:221], v[18:21]
	v_mfma_f32_16x16x32_bf16 v[6:9], v[182:185], v[232:235], v[6:9]
	v_mfma_f32_16x16x32_bf16 v[2:5], v[190:193], v[232:235], v[2:5]
	s_setprio 0
	s_barrier
	s_add_i32 s46, 0, 0x18000
	s_add_i32 s48, 0, 0x1c000
	v_add_u32_e32 v158, s46, v141
	v_add_u32_e32 v175, s48, v141
	ds_read_b128 v[146:149], v158
	ds_read_b128 v[150:153], v158 offset:1024
	ds_read_b128 v[154:157], v158 offset:2048
	ds_read_b128 v[158:161], v158 offset:3072
	ds_read_b128 v[178:181], v175
	ds_read_b128 v[182:185], v175 offset:1024
	ds_read_b128 v[186:189], v175 offset:2048
	ds_read_b128 v[190:193], v175 offset:3072
	s_add_u32 s24, s24, 0x80000
	s_addc_u32 s25, s25, 0
	s_mov_b32 m0, s28
	v_lshl_add_u64 v[240:241], s[24:25], 0, v[166:167]
	ds_read_b128 v[194:197], v145 offset:32768
	ds_read_b128 v[198:201], v145 offset:33792
	ds_read_b128 v[202:205], v145 offset:34816
	ds_read_b128 v[206:209], v145 offset:35840
	ds_read_b128 v[210:213], v145 offset:36864
	ds_read_b128 v[218:221], v145 offset:37888
	ds_read_b128 v[228:231], v145 offset:38912
	ds_read_b128 v[232:235], v145 offset:39936
	global_load_lds_dwordx4 v[240:241], off
	v_lshl_add_u64 v[240:241], s[24:25], 0, v[170:171]
	s_mov_b32 m0, s29
	s_nop 0
	global_load_lds_dwordx4 v[240:241], off
	s_waitcnt vmcnt(8)
	s_waitcnt lgkmcnt(0)
	s_barrier
	s_setprio 1
	s_waitcnt lgkmcnt(0)
	v_mfma_f32_16x16x32_bf16 v[126:129], v[146:149], v[194:197], v[126:129]
	v_mfma_f32_16x16x32_bf16 v[122:125], v[154:157], v[194:197], v[122:125]
	v_mfma_f32_16x16x32_bf16 v[110:113], v[146:149], v[202:205], v[110:113]
	v_mfma_f32_16x16x32_bf16 v[106:109], v[154:157], v[202:205], v[106:109]
	v_mfma_f32_16x16x32_bf16 v[94:97], v[146:149], v[210:213], v[94:97]
	v_mfma_f32_16x16x32_bf16 v[90:93], v[154:157], v[210:213], v[90:93]
	v_mfma_f32_16x16x32_bf16 v[78:81], v[146:149], v[228:231], v[78:81]
	v_mfma_f32_16x16x32_bf16 v[74:77], v[154:157], v[228:231], v[74:77]
	v_mfma_f32_16x16x32_bf16 v[126:129], v[150:153], v[198:201], v[126:129]
	v_mfma_f32_16x16x32_bf16 v[122:125], v[158:161], v[198:201], v[122:125]
	v_mfma_f32_16x16x32_bf16 v[110:113], v[150:153], v[206:209], v[110:113]
	v_mfma_f32_16x16x32_bf16 v[106:109], v[158:161], v[206:209], v[106:109]
	v_mfma_f32_16x16x32_bf16 v[94:97], v[150:153], v[218:221], v[94:97]
	v_mfma_f32_16x16x32_bf16 v[90:93], v[158:161], v[218:221], v[90:93]
	v_mfma_f32_16x16x32_bf16 v[78:81], v[150:153], v[232:235], v[78:81]
	v_mfma_f32_16x16x32_bf16 v[74:77], v[158:161], v[232:235], v[74:77]
	v_mfma_f32_16x16x32_bf16 v[118:121], v[178:181], v[194:197], v[118:121]
	v_mfma_f32_16x16x32_bf16 v[114:117], v[186:189], v[194:197], v[114:117]
	v_mfma_f32_16x16x32_bf16 v[102:105], v[178:181], v[202:205], v[102:105]
	v_mfma_f32_16x16x32_bf16 v[98:101], v[186:189], v[202:205], v[98:101]
	v_mfma_f32_16x16x32_bf16 v[86:89], v[178:181], v[210:213], v[86:89]
	v_mfma_f32_16x16x32_bf16 v[82:85], v[186:189], v[210:213], v[82:85]
	v_mfma_f32_16x16x32_bf16 v[70:73], v[178:181], v[228:231], v[70:73]
	v_mfma_f32_16x16x32_bf16 v[66:69], v[186:189], v[228:231], v[66:69]
	v_mfma_f32_16x16x32_bf16 v[118:121], v[182:185], v[198:201], v[118:121]
	v_mfma_f32_16x16x32_bf16 v[114:117], v[190:193], v[198:201], v[114:117]
	v_mfma_f32_16x16x32_bf16 v[102:105], v[182:185], v[206:209], v[102:105]
	v_mfma_f32_16x16x32_bf16 v[98:101], v[190:193], v[206:209], v[98:101]
	v_mfma_f32_16x16x32_bf16 v[86:89], v[182:185], v[218:221], v[86:89]
	v_mfma_f32_16x16x32_bf16 v[82:85], v[190:193], v[218:221], v[82:85]
	v_mfma_f32_16x16x32_bf16 v[70:73], v[182:185], v[232:235], v[70:73]
	v_mfma_f32_16x16x32_bf16 v[66:69], v[190:193], v[232:235], v[66:69]
	s_setprio 0
	s_barrier
; #define PG8_STAGE(bufoff, gbase, voff) do { _Pragma("unroll") for (int _i = 0; _i < 2; ++_i) \
;         __builtin_amdgcn_global_load_lds((const unsigned*)((const char*)(gbase) + (voff)[_i]), (PG8_LAS unsigned*)(lds + (bufoff) + ldsw + _i * 8192), 16, 0, 0); } while (0)
; #define PG8_LDA(dst, b, h) do { _Pragma("unroll") for (int m = 0; m < 4; ++m) _Pragma("unroll") for (int k = 0; k < 2; ++k) dst[m][k] = *(const PG8_LAS bf16x8*)(lds + PG8_SA(b, h) + aoff + m * 2048 + k * 1024); } while (0)
; #define PG8_MMA(ai, bj, At, Bt) do { __builtin_amdgcn_s_setprio(1); _Pragma("unroll") for (int m = 0; m < 4; ++m) _Pragma("unroll") for (int n = 0; n < 2; ++n) _Pragma("unroll") for (int k = 0; k < 2; ++k) \
;         acc[ai][bj][m][n] = __builtin_amdgcn_mfma_f32_16x16x32_bf16(Bt[n][k], At[m][k], acc[ai][bj][m][n], 0, 0, 0); __builtin_amdgcn_s_setprio(0); } while (0)
; #define PG8_WAIT_V(n) asm volatile("s_waitcnt vmcnt(" #n ")" ::: "memory")
; #define PG8_WAIT_L(n) asm volatile("s_waitcnt lgkmcnt(" #n ")" ::: "memory")
; #define PG8_BAR __builtin_amdgcn_s_barrier()
; #define PG8_SCHED __builtin_amdgcn_sched_barrier(0)
; template <class Epi, class Sched, bool ALIGN_EPI = false, bool SP2 = false>
; __device__ __forceinline__ void gemm_phase(PG8_LAS unsigned char* lds, const Gemm g, const Sched& S, const Epi& E) {
;     ...
;             PG8_LDA(At, 1, 1); PG8_STAGE(PG8_SB(1, 0), b3, voffB); PG8_STAGE(PG8_SB(1, 1), b3 + hstep, voffB); PG8_STAGE(PG8_SA(1, 0), a3, voffA);
;             PG8_WAIT_V(8); PG8_WAIT_L(0); PG8_BAR; PG8_MMA(1, 0, At, B0); PG8_MMA(1, 1, At, B1); PG8_BAR; PG8_SCHED;
;     ...
;         }
;         if constexpr (ALIGN_EPI) { if (wr == 0) PG8_BAR; }
	s_add_i32 s24, s46, s2
	v_lshl_add_u64 v[138:139], v[138:139], 0, s[8:9]
	s_mov_b32 m0, s24
	ds_read_b128 v[194:197], v145 offset:49152
	ds_read_b128 v[198:201], v145 offset:50176
	ds_read_b128 v[202:205], v145 offset:51200
	ds_read_b128 v[206:209], v145 offset:52224
	ds_read_b128 v[210:213], v145 offset:53248
	ds_read_b128 v[218:221], v145 offset:54272
	ds_read_b128 v[228:231], v145 offset:55296
	ds_read_b128 v[232:235], v145 offset:56320
	global_load_lds_dwordx4 v[138:139], off
	s_add_i32 m0, s24, 0x2000
	s_add_u32 s22, s22, 0x80080
	v_lshl_add_u64 v[138:139], v[222:223], 0, s[8:9]
	s_addc_u32 s23, s23, 0
	s_add_i32 s24, s48, s2
	global_load_lds_dwordx4 v[138:139], off
	v_lshl_add_u64 v[138:139], s[22:23], 0, v[168:169]
	s_mov_b32 m0, s24
	s_nop 0
	global_load_lds_dwordx4 v[138:139], off
	v_lshl_add_u64 v[138:139], s[22:23], 0, v[172:173]
	s_add_i32 m0, s24, 0x2000
	s_nop 0
	global_load_lds_dwordx4 v[138:139], off
	v_lshl_add_u64 v[138:139], v[236:237], 0, s[8:9]
	s_mov_b32 m0, s31
	s_nop 0
	global_load_lds_dwordx4 v[138:139], off
	v_lshl_add_u64 v[138:139], v[238:239], 0, s[8:9]
	s_mov_b32 m0, s33
	s_nop 0
	global_load_lds_dwordx4 v[138:139], off
	s_waitcnt vmcnt(8)
	s_waitcnt lgkmcnt(0)
	s_barrier
	s_setprio 1
	s_waitcnt lgkmcnt(0)
	v_mfma_f32_16x16x32_bf16 v[62:65], v[146:149], v[194:197], v[62:65]
	v_mfma_f32_16x16x32_bf16 v[58:61], v[154:157], v[194:197], v[58:61]
	v_mfma_f32_16x16x32_bf16 v[46:49], v[146:149], v[202:205], v[46:49]
	v_mfma_f32_16x16x32_bf16 v[42:45], v[154:157], v[202:205], v[42:45]
	v_mfma_f32_16x16x32_bf16 v[30:33], v[146:149], v[210:213], v[30:33]
	v_mfma_f32_16x16x32_bf16 v[26:29], v[154:157], v[210:213], v[26:29]
	v_mfma_f32_16x16x32_bf16 v[14:17], v[146:149], v[228:231], v[14:17]
	v_mfma_f32_16x16x32_bf16 v[10:13], v[154:157], v[228:231], v[10:13]
	v_mfma_f32_16x16x32_bf16 v[62:65], v[150:153], v[198:201], v[62:65]
	v_mfma_f32_16x16x32_bf16 v[58:61], v[158:161], v[198:201], v[58:61]
	v_mfma_f32_16x16x32_bf16 v[46:49], v[150:153], v[206:209], v[46:49]
	v_mfma_f32_16x16x32_bf16 v[42:45], v[158:161], v[206:209], v[42:45]
	v_mfma_f32_16x16x32_bf16 v[30:33], v[150:153], v[218:221], v[30:33]
	v_mfma_f32_16x16x32_bf16 v[26:29], v[158:161], v[218:221], v[26:29]
	v_mfma_f32_16x16x32_bf16 v[14:17], v[150:153], v[232:235], v[14:17]
	v_mfma_f32_16x16x32_bf16 v[10:13], v[158:161], v[232:235], v[10:13]
	v_mfma_f32_16x16x32_bf16 v[54:57], v[178:181], v[194:197], v[54:57]
	v_mfma_f32_16x16x32_bf16 v[50:53], v[186:189], v[194:197], v[50:53]
	v_mfma_f32_16x16x32_bf16 v[38:41], v[178:181], v[202:205], v[38:41]
	v_mfma_f32_16x16x32_bf16 v[34:37], v[186:189], v[202:205], v[34:37]
	v_mfma_f32_16x16x32_bf16 v[22:25], v[178:181], v[210:213], v[22:25]
	v_mfma_f32_16x16x32_bf16 v[18:21], v[186:189], v[210:213], v[18:21]
	v_mfma_f32_16x16x32_bf16 v[6:9], v[178:181], v[228:231], v[6:9]
	v_mfma_f32_16x16x32_bf16 v[2:5], v[186:189], v[228:231], v[2:5]
	v_mfma_f32_16x16x32_bf16 v[54:57], v[182:185], v[198:201], v[54:57]
	v_mfma_f32_16x16x32_bf16 v[50:53], v[190:193], v[198:201], v[50:53]
	v_mfma_f32_16x16x32_bf16 v[38:41], v[182:185], v[206:209], v[38:41]
	v_mfma_f32_16x16x32_bf16 v[34:37], v[190:193], v[206:209], v[34:37]
	v_mfma_f32_16x16x32_bf16 v[22:25], v[182:185], v[218:221], v[22:25]
	v_mfma_f32_16x16x32_bf16 v[18:21], v[190:193], v[218:221], v[18:21]
	v_mfma_f32_16x16x32_bf16 v[6:9], v[182:185], v[232:235], v[6:9]
	v_mfma_f32_16x16x32_bf16 v[2:5], v[190:193], v[232:235], v[2:5]
	s_setprio 0
	s_barrier
	s_add_u32 s0, s0, 0x100
	s_addc_u32 s1, s1, 0
	s_add_u32 s44, s44, 0x100
	s_addc_u32 s45, s45, 0
	s_cmp_ge_u32 s47, s40
	s_mov_b32 s46, s47
	s_cbranch_scc0 .LBB0_1373
	s_and_b64 vcc, exec, s[10:11]
	s_cbranch_vccz .LBB0_1376
	s_barrier

; #define PG8_STAGE(bufoff, gbase, voff) do { _Pragma("unroll") for (int _i = 0; _i < 2; ++_i) \
;         __builtin_amdgcn_global_load_lds((const unsigned*)((const char*)(gbase) + (voff)[_i]), (PG8_LAS unsigned*)(lds + (bufoff) + ldsw + _i * 8192), 16, 0, 0); } while (0)
; #define PG8_LDA(dst, b, h) do { _Pragma("unroll") for (int m = 0; m < 4; ++m) _Pragma("unroll") for (int k = 0; k < 2; ++k) dst[m][k] = *(const PG8_LAS bf16x8*)(lds + PG8_SA(b, h) + aoff + m * 2048 + k * 1024); } while (0)
; #define PG8_LDB(dst, b, h) do { _Pragma("unroll") for (int n = 0; n < 2; ++n) _Pragma("unroll") for (int k = 0; k < 2; ++k) dst[n][k] = *(const PG8_LAS bf16x8*)(lds + PG8_SB(b, h) + boff + n * 2048 + k * 1024); } while (0)
; #define PG8_MMA(ai, bj, At, Bt) do { __builtin_amdgcn_s_setprio(1); _Pragma("unroll") for (int m = 0; m < 4; ++m) _Pragma("unroll") for (int n = 0; n < 2; ++n) _Pragma("unroll") for (int k = 0; k < 2; ++k) \
;         acc[ai][bj][m][n] = __builtin_amdgcn_mfma_f32_16x16x32_bf16(Bt[n][k], At[m][k], acc[ai][bj][m][n], 0, 0, 0); __builtin_amdgcn_s_setprio(0); } while (0)
; #define PG8_WAIT_V(n) asm volatile("s_waitcnt vmcnt(" #n ")" ::: "memory")
; #define PG8_WAIT_L(n) asm volatile("s_waitcnt lgkmcnt(" #n ")" ::: "memory")
; #define PG8_BAR __builtin_amdgcn_s_barrier()
; #define PG8_SCHED __builtin_amdgcn_sched_barrier(0)
; template <class Epi, class Sched, bool ALIGN_EPI = false, bool SP2 = false>
; __device__ __forceinline__ void gemm_phase(PG8_LAS unsigned char* lds, const Gemm g, const Sched& S, const Epi& E) {
;     ...
;         for (int t = 0; t < nt; t += 2) {
;             const bool last = (t == nt - 2);
;             const char* a1 = cA + (size_t)(t + 1) * kstep;
;             const char* a2 = last ? nA : cA + (size_t)(t + 2) * kstep; const char* b2 = last ? nB : cB + (size_t)(t + 2) * kstep;
;             const char* a3 = a2 + kstep; const char* b3 = b2 + kstep;
;             if (last && has_next) S.a_ready(nxt);
;             if constexpr (SP2) {
;             PG8_LDB(B0, 0, 0); PG8_LDB(B1, 0, 1); PG8_SCHED; PG8_LDA(At, 0, 0); PG8_STAGE(PG8_SA(1, 1), a1 + hstep, voffA);
;             PG8_WAIT_V(8); PG8_WAIT_L(0); PG8_BAR; PG8_MMA(0, 0, At, B0); PG8_MMA(0, 1, At, B1); PG8_BAR; PG8_SCHED;
;             PG8_LDA(At, 0, 1); PG8_STAGE(PG8_SB(0, 0), b2, voffB); PG8_STAGE(PG8_SB(0, 1), b2 + hstep, voffB); PG8_STAGE(PG8_SA(0, 0), a2, voffA);
.LBB0_1532:
	ds_read_b128 v[136:139], v143
	ds_read_b128 v[146:149], v143 offset:1024
	ds_read_b128 v[150:153], v143 offset:2048
	ds_read_b128 v[154:157], v143 offset:3072
	ds_read_b128 v[158:161], v144
	ds_read_b128 v[166:169], v144 offset:1024
	ds_read_b128 v[170:173], v144 offset:2048
	ds_read_b128 v[178:181], v144 offset:3072
	s_add_i32 s67, s34, 2
	s_add_u32 s35, s30, 0xffea0080
	s_addc_u32 s36, s31, -1
	s_cmp_eq_u32 s64, s34
	s_cselect_b32 s34, s28, s65
	s_cselect_b32 s37, s27, s36
	s_cselect_b32 s36, s26, s35
	s_cselect_b32 s35, s29, s66
	v_lshl_add_u64 v[216:217], s[30:31], 0, v[130:131]
	s_add_i32 m0, s3, 0xc000
	ds_read_b128 v[182:185], v145
	ds_read_b128 v[186:189], v145 offset:1024
	ds_read_b128 v[190:193], v145 offset:2048
	ds_read_b128 v[194:197], v145 offset:3072
	ds_read_b128 v[198:201], v145 offset:4096
	ds_read_b128 v[202:205], v145 offset:5120
	ds_read_b128 v[206:209], v145 offset:6144
	ds_read_b128 v[210:213], v145 offset:7168
	global_load_lds_dwordx4 v[216:217], off
	v_lshl_add_u64 v[216:217], s[30:31], 0, v[132:133]
	s_add_i32 m0, s3, 0xe000
	s_nop 0
	global_load_lds_dwordx4 v[216:217], off
	s_waitcnt vmcnt(8)
	s_waitcnt lgkmcnt(0)
	s_barrier
	s_setprio 1
	s_waitcnt lgkmcnt(0)
	v_mfma_f32_16x16x32_bf16 v[126:129], v[136:139], v[182:185], v[126:129]
	v_mfma_f32_16x16x32_bf16 v[122:125], v[150:153], v[182:185], v[122:125]
	v_mfma_f32_16x16x32_bf16 v[118:121], v[136:139], v[190:193], v[118:121]
	v_mfma_f32_16x16x32_bf16 v[114:117], v[150:153], v[190:193], v[114:117]
	v_mfma_f32_16x16x32_bf16 v[102:105], v[136:139], v[198:201], v[102:105]
	v_mfma_f32_16x16x32_bf16 v[98:101], v[150:153], v[198:201], v[98:101]
	v_mfma_f32_16x16x32_bf16 v[90:93], v[136:139], v[206:209], v[90:93]
	v_mfma_f32_16x16x32_bf16 v[82:85], v[150:153], v[206:209], v[82:85]
	v_mfma_f32_16x16x32_bf16 v[126:129], v[146:149], v[186:189], v[126:129]
	v_mfma_f32_16x16x32_bf16 v[122:125], v[154:157], v[186:189], v[122:125]
	v_mfma_f32_16x16x32_bf16 v[118:121], v[146:149], v[194:197], v[118:121]
	v_mfma_f32_16x16x32_bf16 v[114:117], v[154:157], v[194:197], v[114:117]
	v_mfma_f32_16x16x32_bf16 v[102:105], v[146:149], v[202:205], v[102:105]
	v_mfma_f32_16x16x32_bf16 v[98:101], v[154:157], v[202:205], v[98:101]
	v_mfma_f32_16x16x32_bf16 v[90:93], v[146:149], v[210:213], v[90:93]
	v_mfma_f32_16x16x32_bf16 v[82:85], v[154:157], v[210:213], v[82:85]
	v_mfma_f32_16x16x32_bf16 v[110:113], v[158:161], v[182:185], v[110:113]
	v_mfma_f32_16x16x32_bf16 v[106:109], v[170:173], v[182:185], v[106:109]
	v_mfma_f32_16x16x32_bf16 v[94:97], v[158:161], v[190:193], v[94:97]
	v_mfma_f32_16x16x32_bf16 v[86:89], v[170:173], v[190:193], v[86:89]
	v_mfma_f32_16x16x32_bf16 v[78:81], v[158:161], v[198:201], v[78:81]
	v_mfma_f32_16x16x32_bf16 v[74:77], v[170:173], v[198:201], v[74:77]
	v_mfma_f32_16x16x32_bf16 v[70:73], v[158:161], v[206:209], v[70:73]
	v_mfma_f32_16x16x32_bf16 v[66:69], v[170:173], v[206:209], v[66:69]
	v_mfma_f32_16x16x32_bf16 v[110:113], v[166:169], v[186:189], v[110:113]
	v_mfma_f32_16x16x32_bf16 v[106:109], v[178:181], v[186:189], v[106:109]
	v_mfma_f32_16x16x32_bf16 v[94:97], v[166:169], v[194:197], v[94:97]
	v_mfma_f32_16x16x32_bf16 v[86:89], v[178:181], v[194:197], v[86:89]
	v_mfma_f32_16x16x32_bf16 v[78:81], v[166:169], v[202:205], v[78:81]
	v_mfma_f32_16x16x32_bf16 v[74:77], v[178:181], v[202:205], v[74:77]
	v_mfma_f32_16x16x32_bf16 v[70:73], v[166:169], v[210:213], v[70:73]
	v_mfma_f32_16x16x32_bf16 v[66:69], v[178:181], v[210:213], v[66:69]
	s_setprio 0
	s_barrier
	s_add_i32 s68, s48, s2
	v_lshl_add_u64 v[216:217], s[34:35], 0, v[174:175]
	s_mov_b32 m0, s68
	ds_read_b128 v[182:185], v145 offset:16384
	ds_read_b128 v[186:189], v145 offset:17408
	ds_read_b128 v[190:193], v145 offset:18432
	ds_read_b128 v[194:197], v145 offset:19456
	ds_read_b128 v[198:201], v145 offset:20480
	ds_read_b128 v[202:205], v145 offset:21504
	ds_read_b128 v[206:209], v145 offset:22528
	ds_read_b128 v[210:213], v145 offset:23552
	global_load_lds_dwordx4 v[216:217], off
	s_add_i32 m0, s68, 0x2000
	s_add_u32 s68, s34, 0x160000
	v_lshl_add_u64 v[218:219], s[34:35], 0, v[176:177]
	s_addc_u32 s69, s35, 0
	s_add_i32 s70, s49, s2
	global_load_lds_dwordx4 v[218:219], off
	v_lshl_add_u64 v[220:221], s[68:69], 0, v[174:175]
	s_mov_b32 m0, s70
	v_lshl_add_u64 v[222:223], s[36:37], 0, v[176:177]
	global_load_lds_dwordx4 v[220:221], off
	v_lshl_add_u64 v[220:221], s[68:69], 0, v[176:177]
	s_add_i32 m0, s70, 0x2000
	s_nop 0
	global_load_lds_dwordx4 v[220:221], off
	v_lshl_add_u64 v[220:221], s[36:37], 0, v[174:175]
	s_mov_b32 m0, s3
	s_nop 0
	global_load_lds_dwordx4 v[220:221], off
	s_mov_b32 m0, s33
	s_nop 0
	global_load_lds_dwordx4 v[222:223], off
	s_waitcnt vmcnt(8)
	s_waitcnt lgkmcnt(0)
	s_barrier
; #define PG8_STAGE(bufoff, gbase, voff) do { _Pragma("unroll") for (int _i = 0; _i < 2; ++_i) \
;         __builtin_amdgcn_global_load_lds((const unsigned*)((const char*)(gbase) + (voff)[_i]), (PG8_LAS unsigned*)(lds + (bufoff) + ldsw + _i * 8192), 16, 0, 0); } while (0)
; #define PG8_LDA(dst, b, h) do { _Pragma("unroll") for (int m = 0; m < 4; ++m) _Pragma("unroll") for (int k = 0; k < 2; ++k) dst[m][k] = *(const PG8_LAS bf16x8*)(lds + PG8_SA(b, h) + aoff + m * 2048 + k * 1024); } while (0)
; #define PG8_LDB(dst, b, h) do { _Pragma("unroll") for (int n = 0; n < 2; ++n) _Pragma("unroll") for (int k = 0; k < 2; ++k) dst[n][k] = *(const PG8_LAS bf16x8*)(lds + PG8_SB(b, h) + boff + n * 2048 + k * 1024); } while (0)
; #define PG8_MMA(ai, bj, At, Bt) do { __builtin_amdgcn_s_setprio(1); _Pragma("unroll") for (int m = 0; m < 4; ++m) _Pragma("unroll") for (int n = 0; n < 2; ++n) _Pragma("unroll") for (int k = 0; k < 2; ++k) \
;         acc[ai][bj][m][n] = __builtin_amdgcn_mfma_f32_16x16x32_bf16(Bt[n][k], At[m][k], acc[ai][bj][m][n], 0, 0, 0); __builtin_amdgcn_s_setprio(0); } while (0)
; #define PG8_WAIT_V(n) asm volatile("s_waitcnt vmcnt(" #n ")" ::: "memory")
; #define PG8_WAIT_L(n) asm volatile("s_waitcnt lgkmcnt(" #n ")" ::: "memory")
; #define PG8_BAR __builtin_amdgcn_s_barrier()
; #define PG8_SCHED __builtin_amdgcn_sched_barrier(0)
; template <class Epi, class Sched, bool ALIGN_EPI = false, bool SP2 = false>
; __device__ __forceinline__ void gemm_phase(PG8_LAS unsigned char* lds, const Gemm g, const Sched& S, const Epi& E) {
;     ...
;             PG8_WAIT_V(8); PG8_WAIT_L(0); PG8_BAR; PG8_MMA(1, 0, At, B0); PG8_MMA(1, 1, At, B1); PG8_BAR; PG8_SCHED;
;             PG8_LDB(B0, 1, 0); PG8_LDB(B1, 1, 1); PG8_SCHED; PG8_LDA(At, 1, 0); PG8_STAGE(PG8_SA(0, 1), a2 + hstep, voffA);
;             PG8_WAIT_V(8); PG8_WAIT_L(0); PG8_BAR; PG8_MMA(0, 0, At, B0); PG8_MMA(0, 1, At, B1); PG8_BAR; PG8_SCHED;
	s_setprio 1
	s_waitcnt lgkmcnt(0)
	v_mfma_f32_16x16x32_bf16 v[62:65], v[136:139], v[182:185], v[62:65]
	v_mfma_f32_16x16x32_bf16 v[58:61], v[150:153], v[182:185], v[58:61]
	v_mfma_f32_16x16x32_bf16 v[54:57], v[136:139], v[190:193], v[54:57]
	v_mfma_f32_16x16x32_bf16 v[50:53], v[150:153], v[190:193], v[50:53]
	v_mfma_f32_16x16x32_bf16 v[42:45], v[136:139], v[198:201], v[42:45]
	v_mfma_f32_16x16x32_bf16 v[34:37], v[150:153], v[198:201], v[34:37]
	v_mfma_f32_16x16x32_bf16 v[26:29], v[136:139], v[206:209], v[26:29]
	v_mfma_f32_16x16x32_bf16 v[18:21], v[150:153], v[206:209], v[18:21]
	v_mfma_f32_16x16x32_bf16 v[62:65], v[146:149], v[186:189], v[62:65]
	v_mfma_f32_16x16x32_bf16 v[58:61], v[154:157], v[186:189], v[58:61]
	v_mfma_f32_16x16x32_bf16 v[54:57], v[146:149], v[194:197], v[54:57]
	v_mfma_f32_16x16x32_bf16 v[50:53], v[154:157], v[194:197], v[50:53]
	v_mfma_f32_16x16x32_bf16 v[42:45], v[146:149], v[202:205], v[42:45]
	v_mfma_f32_16x16x32_bf16 v[34:37], v[154:157], v[202:205], v[34:37]
	v_mfma_f32_16x16x32_bf16 v[26:29], v[146:149], v[210:213], v[26:29]
	v_mfma_f32_16x16x32_bf16 v[18:21], v[154:157], v[210:213], v[18:21]
	v_mfma_f32_16x16x32_bf16 v[46:49], v[158:161], v[182:185], v[46:49]
	v_mfma_f32_16x16x32_bf16 v[38:41], v[170:173], v[182:185], v[38:41]
	v_mfma_f32_16x16x32_bf16 v[30:33], v[158:161], v[190:193], v[30:33]
	v_mfma_f32_16x16x32_bf16 v[22:25], v[170:173], v[190:193], v[22:25]
	v_mfma_f32_16x16x32_bf16 v[14:17], v[158:161], v[198:201], v[14:17]
	v_mfma_f32_16x16x32_bf16 v[10:13], v[170:173], v[198:201], v[10:13]
	v_mfma_f32_16x16x32_bf16 v[6:9], v[158:161], v[206:209], v[6:9]
	v_mfma_f32_16x16x32_bf16 v[2:5], v[170:173], v[206:209], v[2:5]
	v_mfma_f32_16x16x32_bf16 v[46:49], v[166:169], v[186:189], v[46:49]
	v_mfma_f32_16x16x32_bf16 v[38:41], v[178:181], v[186:189], v[38:41]
	v_mfma_f32_16x16x32_bf16 v[30:33], v[166:169], v[194:197], v[30:33]
	v_mfma_f32_16x16x32_bf16 v[22:25], v[178:181], v[194:197], v[22:25]
	v_mfma_f32_16x16x32_bf16 v[14:17], v[166:169], v[202:205], v[14:17]
	v_mfma_f32_16x16x32_bf16 v[10:13], v[178:181], v[202:205], v[10:13]
	v_mfma_f32_16x16x32_bf16 v[6:9], v[166:169], v[210:213], v[6:9]
	v_mfma_f32_16x16x32_bf16 v[2:5], v[178:181], v[210:213], v[2:5]
	s_setprio 0
	s_barrier
	s_add_i32 s68, 0, 0x18000
	s_add_i32 s69, 0, 0x1c000
	v_add_u32_e32 v154, s68, v141
	v_add_u32_e32 v178, s69, v141
	ds_read_b128 v[136:139], v154
	ds_read_b128 v[146:149], v154 offset:1024
	ds_read_b128 v[150:153], v154 offset:2048
	ds_read_b128 v[154:157], v154 offset:3072
	ds_read_b128 v[158:161], v178
	ds_read_b128 v[166:169], v178 offset:1024
	ds_read_b128 v[170:173], v178 offset:2048
	ds_read_b128 v[178:181], v178 offset:3072
	s_add_u32 s36, s36, 0x160000
	s_addc_u32 s37, s37, 0
	s_mov_b32 m0, s38
	v_lshl_add_u64 v[224:225], s[36:37], 0, v[174:175]
	ds_read_b128 v[182:185], v145 offset:32768
	ds_read_b128 v[186:189], v145 offset:33792
	ds_read_b128 v[190:193], v145 offset:34816
	ds_read_b128 v[194:197], v145 offset:35840
	ds_read_b128 v[198:201], v145 offset:36864
	ds_read_b128 v[202:205], v145 offset:37888
	ds_read_b128 v[206:209], v145 offset:38912
	ds_read_b128 v[210:213], v145 offset:39936
	global_load_lds_dwordx4 v[224:225], off
	v_lshl_add_u64 v[224:225], s[36:37], 0, v[176:177]
	s_mov_b32 m0, s39
	s_nop 0
	global_load_lds_dwordx4 v[224:225], off
	s_waitcnt vmcnt(8)
	s_waitcnt lgkmcnt(0)
	s_barrier
	s_setprio 1
	s_waitcnt lgkmcnt(0)
	v_mfma_f32_16x16x32_bf16 v[126:129], v[136:139], v[182:185], v[126:129]
	v_mfma_f32_16x16x32_bf16 v[122:125], v[150:153], v[182:185], v[122:125]
	v_mfma_f32_16x16x32_bf16 v[118:121], v[136:139], v[190:193], v[118:121]
	v_mfma_f32_16x16x32_bf16 v[114:117], v[150:153], v[190:193], v[114:117]
	v_mfma_f32_16x16x32_bf16 v[102:105], v[136:139], v[198:201], v[102:105]
	v_mfma_f32_16x16x32_bf16 v[98:101], v[150:153], v[198:201], v[98:101]
	v_mfma_f32_16x16x32_bf16 v[90:93], v[136:139], v[206:209], v[90:93]
	v_mfma_f32_16x16x32_bf16 v[82:85], v[150:153], v[206:209], v[82:85]
	v_mfma_f32_16x16x32_bf16 v[126:129], v[146:149], v[186:189], v[126:129]
	v_mfma_f32_16x16x32_bf16 v[122:125], v[154:157], v[186:189], v[122:125]
	v_mfma_f32_16x16x32_bf16 v[118:121], v[146:149], v[194:197], v[118:121]
	v_mfma_f32_16x16x32_bf16 v[114:117], v[154:157], v[194:197], v[114:117]
	v_mfma_f32_16x16x32_bf16 v[102:105], v[146:149], v[202:205], v[102:105]
	v_mfma_f32_16x16x32_bf16 v[98:101], v[154:157], v[202:205], v[98:101]
	v_mfma_f32_16x16x32_bf16 v[90:93], v[146:149], v[210:213], v[90:93]
	v_mfma_f32_16x16x32_bf16 v[82:85], v[154:157], v[210:213], v[82:85]
	v_mfma_f32_16x16x32_bf16 v[110:113], v[158:161], v[182:185], v[110:113]
	v_mfma_f32_16x16x32_bf16 v[106:109], v[170:173], v[182:185], v[106:109]
	v_mfma_f32_16x16x32_bf16 v[94:97], v[158:161], v[190:193], v[94:97]
	v_mfma_f32_16x16x32_bf16 v[86:89], v[170:173], v[190:193], v[86:89]
	v_mfma_f32_16x16x32_bf16 v[78:81], v[158:161], v[198:201], v[78:81]
	v_mfma_f32_16x16x32_bf16 v[74:77], v[170:173], v[198:201], v[74:77]
	v_mfma_f32_16x16x32_bf16 v[70:73], v[158:161], v[206:209], v[70:73]
	v_mfma_f32_16x16x32_bf16 v[66:69], v[170:173], v[206:209], v[66:69]
	v_mfma_f32_16x16x32_bf16 v[110:113], v[166:169], v[186:189], v[110:113]
	v_mfma_f32_16x16x32_bf16 v[106:109], v[178:181], v[186:189], v[106:109]
	v_mfma_f32_16x16x32_bf16 v[94:97], v[166:169], v[194:197], v[94:97]
	v_mfma_f32_16x16x32_bf16 v[86:89], v[178:181], v[194:197], v[86:89]
	v_mfma_f32_16x16x32_bf16 v[78:81], v[166:169], v[202:205], v[78:81]
	v_mfma_f32_16x16x32_bf16 v[74:77], v[178:181], v[202:205], v[74:77]
	v_mfma_f32_16x16x32_bf16 v[70:73], v[166:169], v[210:213], v[70:73]
	v_mfma_f32_16x16x32_bf16 v[66:69], v[178:181], v[210:213], v[66:69]
	s_setprio 0
	s_barrier
; #define PG8_STAGE(bufoff, gbase, voff) do { _Pragma("unroll") for (int _i = 0; _i < 2; ++_i) \
;         __builtin_amdgcn_global_load_lds((const unsigned*)((const char*)(gbase) + (voff)[_i]), (PG8_LAS unsigned*)(lds + (bufoff) + ldsw + _i * 8192), 16, 0, 0); } while (0)
; #define PG8_LDA(dst, b, h) do { _Pragma("unroll") for (int m = 0; m < 4; ++m) _Pragma("unroll") for (int k = 0; k < 2; ++k) dst[m][k] = *(const PG8_LAS bf16x8*)(lds + PG8_SA(b, h) + aoff + m * 2048 + k * 1024); } while (0)
; #define PG8_MMA(ai, bj, At, Bt) do { __builtin_amdgcn_s_setprio(1); _Pragma("unroll") for (int m = 0; m < 4; ++m) _Pragma("unroll") for (int n = 0; n < 2; ++n) _Pragma("unroll") for (int k = 0; k < 2; ++k) \
;         acc[ai][bj][m][n] = __builtin_amdgcn_mfma_f32_16x16x32_bf16(Bt[n][k], At[m][k], acc[ai][bj][m][n], 0, 0, 0); __builtin_amdgcn_s_setprio(0); } while (0)
; #define PG8_WAIT_V(n) asm volatile("s_waitcnt vmcnt(" #n ")" ::: "memory")
; #define PG8_WAIT_L(n) asm volatile("s_waitcnt lgkmcnt(" #n ")" ::: "memory")
; #define PG8_BAR __builtin_amdgcn_s_barrier()
; #define PG8_SCHED __builtin_amdgcn_sched_barrier(0)
; template <class Epi, class Sched, bool ALIGN_EPI = false, bool SP2 = false>
; __device__ __forceinline__ void gemm_phase(PG8_LAS unsigned char* lds, const Gemm g, const Sched& S, const Epi& E) {
;     ...
;             PG8_LDA(At, 1, 1); PG8_STAGE(PG8_SB(1, 0), b3, voffB); PG8_STAGE(PG8_SB(1, 1), b3 + hstep, voffB); PG8_STAGE(PG8_SA(1, 0), a3, voffA);
;             PG8_WAIT_V(8); PG8_WAIT_L(0); PG8_BAR; PG8_MMA(1, 0, At, B0); PG8_MMA(1, 1, At, B1); PG8_BAR; PG8_SCHED;
;     ...
;         }
;         if constexpr (ALIGN_EPI) { if (wr == 0) PG8_BAR; }
	s_add_i32 s36, s68, s2
	v_lshl_add_u64 v[216:217], v[216:217], 0, s[8:9]
	s_mov_b32 m0, s36
	ds_read_b128 v[182:185], v145 offset:49152
	ds_read_b128 v[186:189], v145 offset:50176
	ds_read_b128 v[190:193], v145 offset:51200
	ds_read_b128 v[194:197], v145 offset:52224
	ds_read_b128 v[198:201], v145 offset:53248
	ds_read_b128 v[202:205], v145 offset:54272
	ds_read_b128 v[206:209], v145 offset:55296
	ds_read_b128 v[210:213], v145 offset:56320
	global_load_lds_dwordx4 v[216:217], off
	s_add_i32 m0, s36, 0x2000
	s_add_u32 s34, s34, 0x160080
	v_lshl_add_u64 v[216:217], v[218:219], 0, s[8:9]
	s_addc_u32 s35, s35, 0
	s_add_i32 s36, s69, s2
	global_load_lds_dwordx4 v[216:217], off
	v_lshl_add_u64 v[216:217], s[34:35], 0, v[174:175]
	s_mov_b32 m0, s36
	s_nop 0
	global_load_lds_dwordx4 v[216:217], off
	v_lshl_add_u64 v[216:217], s[34:35], 0, v[176:177]
	s_add_i32 m0, s36, 0x2000
	s_nop 0
	global_load_lds_dwordx4 v[216:217], off
	v_lshl_add_u64 v[216:217], v[220:221], 0, s[8:9]
	s_mov_b32 m0, s40
	s_nop 0
	global_load_lds_dwordx4 v[216:217], off
	v_lshl_add_u64 v[216:217], v[222:223], 0, s[8:9]
	s_mov_b32 m0, s41
	s_nop 0
	global_load_lds_dwordx4 v[216:217], off
	s_waitcnt vmcnt(8)
	s_waitcnt lgkmcnt(0)
	s_barrier
	s_setprio 1
	s_waitcnt lgkmcnt(0)
	v_mfma_f32_16x16x32_bf16 v[62:65], v[136:139], v[182:185], v[62:65]
	v_mfma_f32_16x16x32_bf16 v[58:61], v[150:153], v[182:185], v[58:61]
	v_mfma_f32_16x16x32_bf16 v[54:57], v[136:139], v[190:193], v[54:57]
	v_mfma_f32_16x16x32_bf16 v[50:53], v[150:153], v[190:193], v[50:53]
	v_mfma_f32_16x16x32_bf16 v[42:45], v[136:139], v[198:201], v[42:45]
	v_mfma_f32_16x16x32_bf16 v[34:37], v[150:153], v[198:201], v[34:37]
	v_mfma_f32_16x16x32_bf16 v[26:29], v[136:139], v[206:209], v[26:29]
	v_mfma_f32_16x16x32_bf16 v[18:21], v[150:153], v[206:209], v[18:21]
	v_mfma_f32_16x16x32_bf16 v[62:65], v[146:149], v[186:189], v[62:65]
	v_mfma_f32_16x16x32_bf16 v[58:61], v[154:157], v[186:189], v[58:61]
	v_mfma_f32_16x16x32_bf16 v[54:57], v[146:149], v[194:197], v[54:57]
	v_mfma_f32_16x16x32_bf16 v[50:53], v[154:157], v[194:197], v[50:53]
	v_mfma_f32_16x16x32_bf16 v[42:45], v[146:149], v[202:205], v[42:45]
	v_mfma_f32_16x16x32_bf16 v[34:37], v[154:157], v[202:205], v[34:37]
	v_mfma_f32_16x16x32_bf16 v[26:29], v[146:149], v[210:213], v[26:29]
	v_mfma_f32_16x16x32_bf16 v[18:21], v[154:157], v[210:213], v[18:21]
	v_mfma_f32_16x16x32_bf16 v[46:49], v[158:161], v[182:185], v[46:49]
	v_mfma_f32_16x16x32_bf16 v[38:41], v[170:173], v[182:185], v[38:41]
	v_mfma_f32_16x16x32_bf16 v[30:33], v[158:161], v[190:193], v[30:33]
	v_mfma_f32_16x16x32_bf16 v[22:25], v[170:173], v[190:193], v[22:25]
	v_mfma_f32_16x16x32_bf16 v[14:17], v[158:161], v[198:201], v[14:17]
	v_mfma_f32_16x16x32_bf16 v[10:13], v[170:173], v[198:201], v[10:13]
	v_mfma_f32_16x16x32_bf16 v[6:9], v[158:161], v[206:209], v[6:9]
	v_mfma_f32_16x16x32_bf16 v[2:5], v[170:173], v[206:209], v[2:5]
	v_mfma_f32_16x16x32_bf16 v[46:49], v[166:169], v[186:189], v[46:49]
	v_mfma_f32_16x16x32_bf16 v[38:41], v[178:181], v[186:189], v[38:41]
	v_mfma_f32_16x16x32_bf16 v[30:33], v[166:169], v[194:197], v[30:33]
	v_mfma_f32_16x16x32_bf16 v[22:25], v[178:181], v[194:197], v[22:25]
	v_mfma_f32_16x16x32_bf16 v[14:17], v[166:169], v[202:205], v[14:17]
	v_mfma_f32_16x16x32_bf16 v[10:13], v[178:181], v[202:205], v[10:13]
	v_mfma_f32_16x16x32_bf16 v[6:9], v[166:169], v[210:213], v[6:9]
	v_mfma_f32_16x16x32_bf16 v[2:5], v[178:181], v[210:213], v[2:5]
	s_setprio 0
	s_barrier
	s_add_u32 s30, s30, 0x100
	s_addc_u32 s31, s31, 0
	s_add_u32 s65, s65, 0x100
	s_addc_u32 s66, s66, 0
	s_cmp_ge_u32 s67, s59
	s_mov_b32 s34, s67
	s_cbranch_scc0 .LBB0_1532
	s_and_b64 vcc, exec, s[10:11]
	s_cbranch_vccz .LBB0_1535
	s_barrier
